# plus removed mid-burst s_setprio 0/1 toggles in all K-loops
# baseline (speedup 1.0000x reference)
; #define PG8_STAGE(bufoff, gbase, voff) do { _Pragma("unroll") for (int _i = 0; _i < 2; ++_i) \
;         __builtin_amdgcn_global_load_lds((const unsigned*)((const char*)(gbase) + (voff)[_i]), (LAS unsigned*)(lds + (bufoff) + ldsw + _i * 8192), 16, 0, 0); } while (0)
; #define PG8_LDA(dst, b, h) do { _Pragma("unroll") for (int m = 0; m < 4; ++m) _Pragma("unroll") for (int k = 0; k < 2; ++k) dst[m][k] = *(const LAS bf16x8*)(lds + PG8_SA(b, h) + aoff + m * 2048 + k * 1024); } while (0)
; #define PG8_LDB(dst, b, h) do { _Pragma("unroll") for (int n = 0; n < 2; ++n) _Pragma("unroll") for (int k = 0; k < 2; ++k) dst[n][k] = *(const LAS bf16x8*)(lds + PG8_SB(b, h) + boff + n * 2048 + k * 1024); } while (0)
; #define PG8_MMA(ai, bj, At, Bt) do { __builtin_amdgcn_s_setprio(1); _Pragma("unroll") for (int m = 0; m < 4; ++m) _Pragma("unroll") for (int n = 0; n < 2; ++n) _Pragma("unroll") for (int k = 0; k < 2; ++k) \
;         acc[ai][bj][m][n] = __builtin_amdgcn_mfma_f32_16x16x32_bf16(Bt[n][k], At[m][k], acc[ai][bj][m][n], 0, 0, 0); __builtin_amdgcn_s_setprio(0); } while (0)
; #define PG8_WAIT_V(n) asm volatile("s_waitcnt vmcnt(" #n ")" ::: "memory")
; #define PG8_WAIT_L(n) asm volatile("s_waitcnt lgkmcnt(" #n ")" ::: "memory")
; #define PG8_BAR __builtin_amdgcn_s_barrier()
; #define PG8_SCHED __builtin_amdgcn_sched_barrier(0)
; template <class Epi>
; __device__ __forceinline__ void gemm_phase(ldsp lds, const Gemm g, const StaticOrder& S, const Epi& E, int wave0) {
;     ...
;             const bool last = (t == nt - 2);
;             const char* a1 = cA + (size_t)(t + 1) * kstep;
;             const char* a2 = last ? nA : cA + (size_t)(t + 2) * kstep; const char* b2 = last ? nB : cB + (size_t)(t + 2) * kstep;
;             const char* a3 = a2 + kstep; const char* b3 = b2 + kstep;
;             PG8_LDB(B0, 0, 0); PG8_LDB(B1, 0, 1); PG8_SCHED; PG8_LDA(At, 0, 0); PG8_STAGE(PG8_SA(1, 1), a1 + hstep, voffA);
;             PG8_WAIT_V(8); PG8_WAIT_L(0); PG8_BAR; PG8_MMA(0, 0, At, B0); PG8_MMA(0, 1, At, B1); PG8_BAR; PG8_SCHED;
;             PG8_LDA(At, 0, 1); PG8_STAGE(PG8_SB(0, 0), b2, voffB); PG8_STAGE(PG8_SB(0, 1), b2 + hstep, voffB); PG8_STAGE(PG8_SA(0, 0), a2, voffA);
;             PG8_WAIT_V(8); PG8_WAIT_L(0); PG8_BAR; PG8_MMA(1, 0, At, B0); PG8_MMA(1, 1, At, B1); PG8_BAR; PG8_SCHED;
.LBB0_150:
	ds_read_b128 v[152:155], v149
	ds_read_b128 v[156:159], v149 offset:1024
	ds_read_b128 v[160:163], v149 offset:2048
	ds_read_b128 v[164:167], v149 offset:3072
	ds_read_b128 v[168:171], v150
	ds_read_b128 v[172:175], v150 offset:1024
	ds_read_b128 v[176:179], v150 offset:2048
	ds_read_b128 v[180:183], v150 offset:3072
	s_add_u32 s22, s20, 0xfff80080
	s_addc_u32 s23, s21, -1
	s_cmp_eq_u32 s54, 28
	s_cselect_b32 s25, s13, s23
	s_cselect_b32 s24, s50, s22
	s_cselect_b32 s23, s11, s53
	s_cselect_b32 s22, s51, s52
	s_add_i32 m0, s19, 0xc000
	ds_read_b128 v[184:187], v151
	ds_read_b128 v[188:191], v151 offset:1024
	ds_read_b128 v[192:195], v151 offset:2048
	ds_read_b128 v[196:199], v151 offset:3072
	ds_read_b128 v[200:203], v151 offset:4096
	ds_read_b128 v[204:207], v151 offset:5120
	ds_read_b128 v[208:211], v151 offset:6144
	ds_read_b128 v[212:215], v151 offset:7168
	global_load_lds_dwordx4 v138, s[20:21]
	s_add_i32 m0, s19, 0xe000
	s_nop 0
	global_load_lds_dwordx4 v136, s[20:21]
	s_waitcnt vmcnt(8)
	s_waitcnt lgkmcnt(0)
	s_barrier
	s_setprio 1
	s_waitcnt lgkmcnt(0)
	v_mfma_f32_16x16x32_bf16 v[124:127], v[152:155], v[184:187], v[124:127]
	v_mfma_f32_16x16x32_bf16 v[120:123], v[160:163], v[184:187], v[120:123]
	v_mfma_f32_16x16x32_bf16 v[108:111], v[152:155], v[192:195], v[108:111]
	v_mfma_f32_16x16x32_bf16 v[104:107], v[160:163], v[192:195], v[104:107]
	v_mfma_f32_16x16x32_bf16 v[92:95], v[152:155], v[200:203], v[92:95]
	v_mfma_f32_16x16x32_bf16 v[88:91], v[160:163], v[200:203], v[88:91]
	v_mfma_f32_16x16x32_bf16 v[76:79], v[152:155], v[208:211], v[76:79]
	v_mfma_f32_16x16x32_bf16 v[72:75], v[160:163], v[208:211], v[72:75]
	v_mfma_f32_16x16x32_bf16 v[124:127], v[156:159], v[188:191], v[124:127]
	v_mfma_f32_16x16x32_bf16 v[120:123], v[164:167], v[188:191], v[120:123]
	v_mfma_f32_16x16x32_bf16 v[108:111], v[156:159], v[196:199], v[108:111]
	v_mfma_f32_16x16x32_bf16 v[104:107], v[164:167], v[196:199], v[104:107]
	v_mfma_f32_16x16x32_bf16 v[92:95], v[156:159], v[204:207], v[92:95]
	v_mfma_f32_16x16x32_bf16 v[88:91], v[164:167], v[204:207], v[88:91]
	v_mfma_f32_16x16x32_bf16 v[76:79], v[156:159], v[212:215], v[76:79]
	v_mfma_f32_16x16x32_bf16 v[72:75], v[164:167], v[212:215], v[72:75]
	v_mfma_f32_16x16x32_bf16 v[116:119], v[168:171], v[184:187], v[116:119]
	v_mfma_f32_16x16x32_bf16 v[112:115], v[176:179], v[184:187], v[112:115]
	v_mfma_f32_16x16x32_bf16 v[100:103], v[168:171], v[192:195], v[100:103]
	v_mfma_f32_16x16x32_bf16 v[96:99], v[176:179], v[192:195], v[96:99]
	v_mfma_f32_16x16x32_bf16 v[84:87], v[168:171], v[200:203], v[84:87]
	v_mfma_f32_16x16x32_bf16 v[80:83], v[176:179], v[200:203], v[80:83]
	v_mfma_f32_16x16x32_bf16 v[68:71], v[168:171], v[208:211], v[68:71]
	v_mfma_f32_16x16x32_bf16 v[64:67], v[176:179], v[208:211], v[64:67]
	v_mfma_f32_16x16x32_bf16 v[116:119], v[172:175], v[188:191], v[116:119]
	v_mfma_f32_16x16x32_bf16 v[112:115], v[180:183], v[188:191], v[112:115]
	v_mfma_f32_16x16x32_bf16 v[100:103], v[172:175], v[196:199], v[100:103]
	v_mfma_f32_16x16x32_bf16 v[96:99], v[180:183], v[196:199], v[96:99]
	v_mfma_f32_16x16x32_bf16 v[84:87], v[172:175], v[204:207], v[84:87]
	v_mfma_f32_16x16x32_bf16 v[80:83], v[180:183], v[204:207], v[80:83]
	v_mfma_f32_16x16x32_bf16 v[68:71], v[172:175], v[212:215], v[68:71]
	v_mfma_f32_16x16x32_bf16 v[64:67], v[180:183], v[212:215], v[64:67]
	s_setprio 0
	s_barrier
	s_add_i32 s55, s46, s34
	s_add_u32 s100, s24, 0x80
	s_addc_u32 s101, s25, 0
	s_mov_b32 m0, s55
	ds_read_b128 v[184:187], v151 offset:16384
	ds_read_b128 v[188:191], v151 offset:17408
	ds_read_b128 v[192:195], v151 offset:18432
	ds_read_b128 v[196:199], v151 offset:19456
	ds_read_b128 v[200:203], v151 offset:20480
	ds_read_b128 v[204:207], v151 offset:21504
	ds_read_b128 v[208:211], v151 offset:22528
	ds_read_b128 v[212:215], v151 offset:23552
	global_load_lds_dwordx4 v132, s[22:23]
	s_add_i32 m0, s55, 0x2000
	s_add_u32 s56, s22, 0x80000
	s_addc_u32 s57, s23, 0
	s_add_i32 s55, s47, s34
	global_load_lds_dwordx4 v128, s[22:23]
	s_mov_b32 m0, s55
	s_nop 0
	global_load_lds_dwordx4 v132, s[56:57]
	s_add_i32 m0, s55, 0x2000
	s_nop 0
	global_load_lds_dwordx4 v128, s[56:57]
	s_mov_b32 m0, s19
	s_nop 0
	global_load_lds_dwordx4 v134, s[24:25]
	s_mov_b32 m0, s37
	s_nop 0
	global_load_lds_dwordx4 v130, s[24:25]
	s_waitcnt vmcnt(8)
	s_waitcnt lgkmcnt(0)
	s_barrier
	s_setprio 1
	s_waitcnt lgkmcnt(0)
	v_mfma_f32_16x16x32_bf16 v[60:63], v[152:155], v[184:187], v[60:63]
	v_mfma_f32_16x16x32_bf16 v[56:59], v[160:163], v[184:187], v[56:59]
	v_mfma_f32_16x16x32_bf16 v[44:47], v[152:155], v[192:195], v[44:47]
	v_mfma_f32_16x16x32_bf16 v[40:43], v[160:163], v[192:195], v[40:43]
	v_mfma_f32_16x16x32_bf16 v[28:31], v[152:155], v[200:203], v[28:31]
	v_mfma_f32_16x16x32_bf16 v[24:27], v[160:163], v[200:203], v[24:27]
	v_mfma_f32_16x16x32_bf16 v[12:15], v[152:155], v[208:211], v[12:15]
	v_mfma_f32_16x16x32_bf16 v[8:11], v[160:163], v[208:211], v[8:11]
	v_mfma_f32_16x16x32_bf16 v[60:63], v[156:159], v[188:191], v[60:63]
	v_mfma_f32_16x16x32_bf16 v[56:59], v[164:167], v[188:191], v[56:59]
	v_mfma_f32_16x16x32_bf16 v[44:47], v[156:159], v[196:199], v[44:47]
	v_mfma_f32_16x16x32_bf16 v[40:43], v[164:167], v[196:199], v[40:43]
	v_mfma_f32_16x16x32_bf16 v[28:31], v[156:159], v[204:207], v[28:31]
	v_mfma_f32_16x16x32_bf16 v[24:27], v[164:167], v[204:207], v[24:27]
	v_mfma_f32_16x16x32_bf16 v[12:15], v[156:159], v[212:215], v[12:15]
	v_mfma_f32_16x16x32_bf16 v[8:11], v[164:167], v[212:215], v[8:11]
	v_mfma_f32_16x16x32_bf16 v[52:55], v[168:171], v[184:187], v[52:55]
	v_mfma_f32_16x16x32_bf16 v[48:51], v[176:179], v[184:187], v[48:51]
	v_mfma_f32_16x16x32_bf16 v[36:39], v[168:171], v[192:195], v[36:39]
	v_mfma_f32_16x16x32_bf16 v[32:35], v[176:179], v[192:195], v[32:35]
	v_mfma_f32_16x16x32_bf16 v[20:23], v[168:171], v[200:203], v[20:23]
	v_mfma_f32_16x16x32_bf16 v[16:19], v[176:179], v[200:203], v[16:19]
	v_mfma_f32_16x16x32_bf16 v[4:7], v[168:171], v[208:211], v[4:7]
	v_mfma_f32_16x16x32_bf16 v[0:3], v[176:179], v[208:211], v[0:3]
	v_mfma_f32_16x16x32_bf16 v[52:55], v[172:175], v[188:191], v[52:55]
	v_mfma_f32_16x16x32_bf16 v[48:51], v[180:183], v[188:191], v[48:51]
	v_mfma_f32_16x16x32_bf16 v[36:39], v[172:175], v[196:199], v[36:39]
	v_mfma_f32_16x16x32_bf16 v[32:35], v[180:183], v[196:199], v[32:35]
	v_mfma_f32_16x16x32_bf16 v[20:23], v[172:175], v[204:207], v[20:23]
	v_mfma_f32_16x16x32_bf16 v[16:19], v[180:183], v[204:207], v[16:19]
	v_mfma_f32_16x16x32_bf16 v[4:7], v[172:175], v[212:215], v[4:7]
	v_mfma_f32_16x16x32_bf16 v[0:3], v[180:183], v[212:215], v[0:3]
	s_setprio 0
	s_barrier
; #define PG8_STAGE(bufoff, gbase, voff) do { _Pragma("unroll") for (int _i = 0; _i < 2; ++_i) \
;         __builtin_amdgcn_global_load_lds((const unsigned*)((const char*)(gbase) + (voff)[_i]), (LAS unsigned*)(lds + (bufoff) + ldsw + _i * 8192), 16, 0, 0); } while (0)
; #define PG8_LDA(dst, b, h) do { _Pragma("unroll") for (int m = 0; m < 4; ++m) _Pragma("unroll") for (int k = 0; k < 2; ++k) dst[m][k] = *(const LAS bf16x8*)(lds + PG8_SA(b, h) + aoff + m * 2048 + k * 1024); } while (0)
; #define PG8_LDB(dst, b, h) do { _Pragma("unroll") for (int n = 0; n < 2; ++n) _Pragma("unroll") for (int k = 0; k < 2; ++k) dst[n][k] = *(const LAS bf16x8*)(lds + PG8_SB(b, h) + boff + n * 2048 + k * 1024); } while (0)
; #define PG8_MMA(ai, bj, At, Bt) do { __builtin_amdgcn_s_setprio(1); _Pragma("unroll") for (int m = 0; m < 4; ++m) _Pragma("unroll") for (int n = 0; n < 2; ++n) _Pragma("unroll") for (int k = 0; k < 2; ++k) \
;         acc[ai][bj][m][n] = __builtin_amdgcn_mfma_f32_16x16x32_bf16(Bt[n][k], At[m][k], acc[ai][bj][m][n], 0, 0, 0); __builtin_amdgcn_s_setprio(0); } while (0)
; #define PG8_WAIT_V(n) asm volatile("s_waitcnt vmcnt(" #n ")" ::: "memory")
; #define PG8_WAIT_L(n) asm volatile("s_waitcnt lgkmcnt(" #n ")" ::: "memory")
; #define PG8_BAR __builtin_amdgcn_s_barrier()
; #define PG8_SCHED __builtin_amdgcn_sched_barrier(0)
; template <class Epi>
; __device__ __forceinline__ void gemm_phase(ldsp lds, const Gemm g, const StaticOrder& S, const Epi& E, int wave0) {
;     ...
;             PG8_LDB(B0, 1, 0); PG8_LDB(B1, 1, 1); PG8_SCHED; PG8_LDA(At, 1, 0); PG8_STAGE(PG8_SA(0, 1), a2 + hstep, voffA);
;             PG8_WAIT_V(8); PG8_WAIT_L(0); PG8_BAR; PG8_MMA(0, 0, At, B0); PG8_MMA(0, 1, At, B1); PG8_BAR; PG8_SCHED;
;             PG8_LDA(At, 1, 1); PG8_STAGE(PG8_SB(1, 0), b3, voffB); PG8_STAGE(PG8_SB(1, 1), b3 + hstep, voffB); PG8_STAGE(PG8_SA(1, 0), a3, voffA);
;             PG8_WAIT_V(8); PG8_WAIT_L(0); PG8_BAR; PG8_MMA(1, 0, At, B0); PG8_MMA(1, 1, At, B1); PG8_BAR; PG8_SCHED;
;         }
	s_add_i32 s55, 0, 0x18000
	s_add_i32 s56, 0, 0x1c000
	v_add_u32_e32 v164, s55, v148
	v_add_u32_e32 v180, s56, v148
	ds_read_b128 v[152:155], v164
	ds_read_b128 v[156:159], v164 offset:1024
	ds_read_b128 v[160:163], v164 offset:2048
	ds_read_b128 v[164:167], v164 offset:3072
	ds_read_b128 v[168:171], v180
	ds_read_b128 v[172:175], v180 offset:1024
	ds_read_b128 v[176:179], v180 offset:2048
	ds_read_b128 v[180:183], v180 offset:3072
	s_add_u32 s24, s24, 0x80000
	s_addc_u32 s25, s25, 0
	s_mov_b32 m0, s38
	ds_read_b128 v[184:187], v151 offset:32768
	ds_read_b128 v[188:191], v151 offset:33792
	ds_read_b128 v[192:195], v151 offset:34816
	ds_read_b128 v[196:199], v151 offset:35840
	ds_read_b128 v[200:203], v151 offset:36864
	ds_read_b128 v[204:207], v151 offset:37888
	ds_read_b128 v[208:211], v151 offset:38912
	ds_read_b128 v[212:215], v151 offset:39936
	global_load_lds_dwordx4 v134, s[24:25]
	s_mov_b32 m0, s39
	s_nop 0
	global_load_lds_dwordx4 v130, s[24:25]
	s_waitcnt vmcnt(8)
	s_waitcnt lgkmcnt(0)
	s_barrier
	s_setprio 1
	s_waitcnt lgkmcnt(0)
	v_mfma_f32_16x16x32_bf16 v[124:127], v[152:155], v[184:187], v[124:127]
	v_mfma_f32_16x16x32_bf16 v[120:123], v[160:163], v[184:187], v[120:123]
	v_mfma_f32_16x16x32_bf16 v[108:111], v[152:155], v[192:195], v[108:111]
	v_mfma_f32_16x16x32_bf16 v[104:107], v[160:163], v[192:195], v[104:107]
	v_mfma_f32_16x16x32_bf16 v[92:95], v[152:155], v[200:203], v[92:95]
	v_mfma_f32_16x16x32_bf16 v[88:91], v[160:163], v[200:203], v[88:91]
	v_mfma_f32_16x16x32_bf16 v[76:79], v[152:155], v[208:211], v[76:79]
	v_mfma_f32_16x16x32_bf16 v[72:75], v[160:163], v[208:211], v[72:75]
	v_mfma_f32_16x16x32_bf16 v[124:127], v[156:159], v[188:191], v[124:127]
	v_mfma_f32_16x16x32_bf16 v[120:123], v[164:167], v[188:191], v[120:123]
	v_mfma_f32_16x16x32_bf16 v[108:111], v[156:159], v[196:199], v[108:111]
	v_mfma_f32_16x16x32_bf16 v[104:107], v[164:167], v[196:199], v[104:107]
	v_mfma_f32_16x16x32_bf16 v[92:95], v[156:159], v[204:207], v[92:95]
	v_mfma_f32_16x16x32_bf16 v[88:91], v[164:167], v[204:207], v[88:91]
	v_mfma_f32_16x16x32_bf16 v[76:79], v[156:159], v[212:215], v[76:79]
	v_mfma_f32_16x16x32_bf16 v[72:75], v[164:167], v[212:215], v[72:75]
	v_mfma_f32_16x16x32_bf16 v[116:119], v[168:171], v[184:187], v[116:119]
	v_mfma_f32_16x16x32_bf16 v[112:115], v[176:179], v[184:187], v[112:115]
	v_mfma_f32_16x16x32_bf16 v[100:103], v[168:171], v[192:195], v[100:103]
	v_mfma_f32_16x16x32_bf16 v[96:99], v[176:179], v[192:195], v[96:99]
	v_mfma_f32_16x16x32_bf16 v[84:87], v[168:171], v[200:203], v[84:87]
	v_mfma_f32_16x16x32_bf16 v[80:83], v[176:179], v[200:203], v[80:83]
	v_mfma_f32_16x16x32_bf16 v[68:71], v[168:171], v[208:211], v[68:71]
	v_mfma_f32_16x16x32_bf16 v[64:67], v[176:179], v[208:211], v[64:67]
	v_mfma_f32_16x16x32_bf16 v[116:119], v[172:175], v[188:191], v[116:119]
	v_mfma_f32_16x16x32_bf16 v[112:115], v[180:183], v[188:191], v[112:115]
	v_mfma_f32_16x16x32_bf16 v[100:103], v[172:175], v[196:199], v[100:103]
	v_mfma_f32_16x16x32_bf16 v[96:99], v[180:183], v[196:199], v[96:99]
	v_mfma_f32_16x16x32_bf16 v[84:87], v[172:175], v[204:207], v[84:87]
	v_mfma_f32_16x16x32_bf16 v[80:83], v[180:183], v[204:207], v[80:83]
	v_mfma_f32_16x16x32_bf16 v[68:71], v[172:175], v[212:215], v[68:71]
	v_mfma_f32_16x16x32_bf16 v[64:67], v[180:183], v[212:215], v[64:67]
	s_setprio 0
	s_barrier
	s_add_i32 s24, s55, s34
	s_add_u32 s22, s22, 0x80
	s_addc_u32 s23, s23, 0
	s_mov_b32 m0, s24
	ds_read_b128 v[184:187], v151 offset:49152
	ds_read_b128 v[188:191], v151 offset:50176
	ds_read_b128 v[192:195], v151 offset:51200
	ds_read_b128 v[196:199], v151 offset:52224
	ds_read_b128 v[200:203], v151 offset:53248
	ds_read_b128 v[204:207], v151 offset:54272
	ds_read_b128 v[208:211], v151 offset:55296
	ds_read_b128 v[212:215], v151 offset:56320
	global_load_lds_dwordx4 v132, s[22:23]
	s_add_i32 m0, s24, 0x2000
	s_add_i32 s24, s56, s34
	global_load_lds_dwordx4 v128, s[22:23]
	s_add_u32 s22, s22, 0x80000
	s_addc_u32 s23, s23, 0
	s_mov_b32 m0, s24
	s_nop 0
	global_load_lds_dwordx4 v132, s[22:23]
	s_add_i32 m0, s24, 0x2000
	s_nop 0
	global_load_lds_dwordx4 v128, s[22:23]
	s_mov_b32 m0, s42
	s_nop 0
	global_load_lds_dwordx4 v134, s[100:101]
	s_mov_b32 m0, s43
	s_nop 0
	global_load_lds_dwordx4 v130, s[100:101]
	s_waitcnt vmcnt(8)
	s_waitcnt lgkmcnt(0)
	s_barrier
	s_setprio 1
	s_waitcnt lgkmcnt(0)
	v_mfma_f32_16x16x32_bf16 v[60:63], v[152:155], v[184:187], v[60:63]
	v_mfma_f32_16x16x32_bf16 v[56:59], v[160:163], v[184:187], v[56:59]
	v_mfma_f32_16x16x32_bf16 v[44:47], v[152:155], v[192:195], v[44:47]
	v_mfma_f32_16x16x32_bf16 v[40:43], v[160:163], v[192:195], v[40:43]
	v_mfma_f32_16x16x32_bf16 v[28:31], v[152:155], v[200:203], v[28:31]
	v_mfma_f32_16x16x32_bf16 v[24:27], v[160:163], v[200:203], v[24:27]
	v_mfma_f32_16x16x32_bf16 v[12:15], v[152:155], v[208:211], v[12:15]
	v_mfma_f32_16x16x32_bf16 v[8:11], v[160:163], v[208:211], v[8:11]
	v_mfma_f32_16x16x32_bf16 v[60:63], v[156:159], v[188:191], v[60:63]
	v_mfma_f32_16x16x32_bf16 v[56:59], v[164:167], v[188:191], v[56:59]
	v_mfma_f32_16x16x32_bf16 v[44:47], v[156:159], v[196:199], v[44:47]
	v_mfma_f32_16x16x32_bf16 v[40:43], v[164:167], v[196:199], v[40:43]
	v_mfma_f32_16x16x32_bf16 v[28:31], v[156:159], v[204:207], v[28:31]
	v_mfma_f32_16x16x32_bf16 v[24:27], v[164:167], v[204:207], v[24:27]
	v_mfma_f32_16x16x32_bf16 v[12:15], v[156:159], v[212:215], v[12:15]
	v_mfma_f32_16x16x32_bf16 v[8:11], v[164:167], v[212:215], v[8:11]
	v_mfma_f32_16x16x32_bf16 v[52:55], v[168:171], v[184:187], v[52:55]
	v_mfma_f32_16x16x32_bf16 v[48:51], v[176:179], v[184:187], v[48:51]
	v_mfma_f32_16x16x32_bf16 v[36:39], v[168:171], v[192:195], v[36:39]
	v_mfma_f32_16x16x32_bf16 v[32:35], v[176:179], v[192:195], v[32:35]
	v_mfma_f32_16x16x32_bf16 v[20:23], v[168:171], v[200:203], v[20:23]
	v_mfma_f32_16x16x32_bf16 v[16:19], v[176:179], v[200:203], v[16:19]
	v_mfma_f32_16x16x32_bf16 v[4:7], v[168:171], v[208:211], v[4:7]
	v_mfma_f32_16x16x32_bf16 v[0:3], v[176:179], v[208:211], v[0:3]
	v_mfma_f32_16x16x32_bf16 v[52:55], v[172:175], v[188:191], v[52:55]
	v_mfma_f32_16x16x32_bf16 v[48:51], v[180:183], v[188:191], v[48:51]
	v_mfma_f32_16x16x32_bf16 v[36:39], v[172:175], v[196:199], v[36:39]
	v_mfma_f32_16x16x32_bf16 v[32:35], v[180:183], v[196:199], v[32:35]
	v_mfma_f32_16x16x32_bf16 v[20:23], v[172:175], v[204:207], v[20:23]
	v_mfma_f32_16x16x32_bf16 v[16:19], v[180:183], v[204:207], v[16:19]
	v_mfma_f32_16x16x32_bf16 v[4:7], v[172:175], v[212:215], v[4:7]
	v_mfma_f32_16x16x32_bf16 v[0:3], v[180:183], v[212:215], v[0:3]
	s_setprio 0
	s_barrier
	s_add_i32 s54, s54, 2
	s_add_u32 s52, s52, 0x100
	s_addc_u32 s53, s53, 0
	s_add_u32 s20, s20, 0x100
	s_addc_u32 s21, s21, 0
	s_cmp_gt_u32 s54, 29
	s_cbranch_scc0 .LBB0_150
	s_and_b64 vcc, exec, s[8:9]
	s_cbranch_vccz .LBB0_153
	s_barrier

; #define PG8_STAGE(bufoff, gbase, voff) do { _Pragma("unroll") for (int _i = 0; _i < 2; ++_i) \
;         __builtin_amdgcn_global_load_lds((const unsigned*)((const char*)(gbase) + (voff)[_i]), (LAS unsigned*)(lds + (bufoff) + ldsw + _i * 8192), 16, 0, 0); } while (0)
; #define PG8_LDA(dst, b, h) do { _Pragma("unroll") for (int m = 0; m < 4; ++m) _Pragma("unroll") for (int k = 0; k < 2; ++k) dst[m][k] = *(const LAS bf16x8*)(lds + PG8_SA(b, h) + aoff + m * 2048 + k * 1024); } while (0)
; #define PG8_LDB(dst, b, h) do { _Pragma("unroll") for (int n = 0; n < 2; ++n) _Pragma("unroll") for (int k = 0; k < 2; ++k) dst[n][k] = *(const LAS bf16x8*)(lds + PG8_SB(b, h) + boff + n * 2048 + k * 1024); } while (0)
; #define PG8_MMA(ai, bj, At, Bt) do { __builtin_amdgcn_s_setprio(1); _Pragma("unroll") for (int m = 0; m < 4; ++m) _Pragma("unroll") for (int n = 0; n < 2; ++n) _Pragma("unroll") for (int k = 0; k < 2; ++k) \
;         acc[ai][bj][m][n] = __builtin_amdgcn_mfma_f32_16x16x32_bf16(Bt[n][k], At[m][k], acc[ai][bj][m][n], 0, 0, 0); __builtin_amdgcn_s_setprio(0); } while (0)
; #define PG8_WAIT_V(n) asm volatile("s_waitcnt vmcnt(" #n ")" ::: "memory")
; #define PG8_WAIT_L(n) asm volatile("s_waitcnt lgkmcnt(" #n ")" ::: "memory")
; #define PG8_BAR __builtin_amdgcn_s_barrier()
; #define PG8_SCHED __builtin_amdgcn_sched_barrier(0)
; template <class Epi>
; __device__ __forceinline__ void gemm_phase(ldsp lds, const Gemm g, const StaticOrder& S, const Epi& E, int wave0) {
;     ...
;             const bool last = (t == nt - 2);
;             const char* a1 = cA + (size_t)(t + 1) * kstep;
;             const char* a2 = last ? nA : cA + (size_t)(t + 2) * kstep; const char* b2 = last ? nB : cB + (size_t)(t + 2) * kstep;
;             const char* a3 = a2 + kstep; const char* b3 = b2 + kstep;
;             PG8_LDB(B0, 0, 0); PG8_LDB(B1, 0, 1); PG8_SCHED; PG8_LDA(At, 0, 0); PG8_STAGE(PG8_SA(1, 1), a1 + hstep, voffA);
;             PG8_WAIT_V(8); PG8_WAIT_L(0); PG8_BAR; PG8_MMA(0, 0, At, B0); PG8_MMA(0, 1, At, B1); PG8_BAR; PG8_SCHED;
;             PG8_LDA(At, 0, 1); PG8_STAGE(PG8_SB(0, 0), b2, voffB); PG8_STAGE(PG8_SB(0, 1), b2 + hstep, voffB); PG8_STAGE(PG8_SA(0, 0), a2, voffA);
;             PG8_WAIT_V(8); PG8_WAIT_L(0); PG8_BAR; PG8_MMA(1, 0, At, B0); PG8_MMA(1, 1, At, B1); PG8_BAR; PG8_SCHED;
.LBB0_222:
	ds_read_b128 v[152:155], v149
	ds_read_b128 v[156:159], v149 offset:1024
	ds_read_b128 v[160:163], v149 offset:2048
	ds_read_b128 v[164:167], v149 offset:3072
	ds_read_b128 v[168:171], v150
	ds_read_b128 v[172:175], v150 offset:1024
	ds_read_b128 v[176:179], v150 offset:2048
	ds_read_b128 v[180:183], v150 offset:3072
	s_add_u32 s36, s34, 0x100
	s_addc_u32 s37, s35, 0
	s_cmpk_eq_i32 s69, 0x54
	s_cselect_b32 s41, s5, s37
	s_cselect_b32 s40, s4, s36
	s_cselect_b32 s39, s31, s68
	s_cselect_b32 s38, s30, s67
	s_add_i32 m0, s49, 0xc000
	ds_read_b128 v[184:187], v151
	ds_read_b128 v[188:191], v151 offset:1024
	ds_read_b128 v[192:195], v151 offset:2048
	ds_read_b128 v[196:199], v151 offset:3072
	ds_read_b128 v[200:203], v151 offset:4096
	ds_read_b128 v[204:207], v151 offset:5120
	ds_read_b128 v[208:211], v151 offset:6144
	ds_read_b128 v[212:215], v151 offset:7168
	global_load_lds_dwordx4 v138, s[34:35]
	s_add_i32 m0, s49, 0xe000
	s_nop 0
	global_load_lds_dwordx4 v136, s[34:35]
	s_waitcnt vmcnt(8)
	s_waitcnt lgkmcnt(0)
	s_barrier
	s_setprio 1
	s_waitcnt lgkmcnt(0)
	v_mfma_f32_16x16x32_bf16 v[124:127], v[152:155], v[184:187], v[124:127]
	v_mfma_f32_16x16x32_bf16 v[120:123], v[160:163], v[184:187], v[120:123]
	v_mfma_f32_16x16x32_bf16 v[112:115], v[152:155], v[192:195], v[112:115]
	v_mfma_f32_16x16x32_bf16 v[104:107], v[160:163], v[192:195], v[104:107]
	v_mfma_f32_16x16x32_bf16 v[96:99], v[152:155], v[200:203], v[96:99]
	v_mfma_f32_16x16x32_bf16 v[88:91], v[160:163], v[200:203], v[88:91]
	v_mfma_f32_16x16x32_bf16 v[80:83], v[152:155], v[208:211], v[80:83]
	v_mfma_f32_16x16x32_bf16 v[72:75], v[160:163], v[208:211], v[72:75]
	v_mfma_f32_16x16x32_bf16 v[124:127], v[156:159], v[188:191], v[124:127]
	v_mfma_f32_16x16x32_bf16 v[120:123], v[164:167], v[188:191], v[120:123]
	v_mfma_f32_16x16x32_bf16 v[112:115], v[156:159], v[196:199], v[112:115]
	v_mfma_f32_16x16x32_bf16 v[104:107], v[164:167], v[196:199], v[104:107]
	v_mfma_f32_16x16x32_bf16 v[96:99], v[156:159], v[204:207], v[96:99]
	v_mfma_f32_16x16x32_bf16 v[88:91], v[164:167], v[204:207], v[88:91]
	v_mfma_f32_16x16x32_bf16 v[80:83], v[156:159], v[212:215], v[80:83]
	v_mfma_f32_16x16x32_bf16 v[72:75], v[164:167], v[212:215], v[72:75]
	v_mfma_f32_16x16x32_bf16 v[116:119], v[168:171], v[184:187], v[116:119]
	v_mfma_f32_16x16x32_bf16 v[108:111], v[176:179], v[184:187], v[108:111]
	v_mfma_f32_16x16x32_bf16 v[100:103], v[168:171], v[192:195], v[100:103]
	v_mfma_f32_16x16x32_bf16 v[92:95], v[176:179], v[192:195], v[92:95]
	v_mfma_f32_16x16x32_bf16 v[84:87], v[168:171], v[200:203], v[84:87]
	v_mfma_f32_16x16x32_bf16 v[76:79], v[176:179], v[200:203], v[76:79]
	v_mfma_f32_16x16x32_bf16 v[68:71], v[168:171], v[208:211], v[68:71]
	v_mfma_f32_16x16x32_bf16 v[64:67], v[176:179], v[208:211], v[64:67]
	v_mfma_f32_16x16x32_bf16 v[116:119], v[172:175], v[188:191], v[116:119]
	v_mfma_f32_16x16x32_bf16 v[108:111], v[180:183], v[188:191], v[108:111]
	v_mfma_f32_16x16x32_bf16 v[100:103], v[172:175], v[196:199], v[100:103]
	v_mfma_f32_16x16x32_bf16 v[92:95], v[180:183], v[196:199], v[92:95]
	v_mfma_f32_16x16x32_bf16 v[84:87], v[172:175], v[204:207], v[84:87]
	v_mfma_f32_16x16x32_bf16 v[76:79], v[180:183], v[204:207], v[76:79]
	v_mfma_f32_16x16x32_bf16 v[68:71], v[172:175], v[212:215], v[68:71]
	v_mfma_f32_16x16x32_bf16 v[64:67], v[180:183], v[212:215], v[64:67]
	s_setprio 0
	s_barrier
	s_add_i32 s34, s61, s48
	s_mov_b32 m0, s34
	ds_read_b128 v[184:187], v151 offset:16384
	ds_read_b128 v[188:191], v151 offset:17408
	ds_read_b128 v[192:195], v151 offset:18432
	ds_read_b128 v[196:199], v151 offset:19456
	ds_read_b128 v[200:203], v151 offset:20480
	ds_read_b128 v[204:207], v151 offset:21504
	ds_read_b128 v[208:211], v151 offset:22528
	ds_read_b128 v[212:215], v151 offset:23552
	global_load_lds_dwordx4 v130, s[38:39]
	s_add_i32 m0, s34, 0x2000
	s_add_u32 s34, s38, 0x160000
	s_addc_u32 s35, s39, 0
	s_add_i32 s70, s62, s48
	global_load_lds_dwordx4 v134, s[38:39]
	s_mov_b32 m0, s70
	s_nop 0
	global_load_lds_dwordx4 v130, s[34:35]
	s_add_i32 m0, s70, 0x2000
	s_nop 0
	global_load_lds_dwordx4 v134, s[34:35]
	s_mov_b32 m0, s49
	s_nop 0
	global_load_lds_dwordx4 v128, s[40:41]
	s_mov_b32 m0, s50
	s_nop 0
	global_load_lds_dwordx4 v132, s[40:41]
	s_waitcnt vmcnt(8)
	s_waitcnt lgkmcnt(0)
	s_barrier
	s_setprio 1
	s_waitcnt lgkmcnt(0)
	v_mfma_f32_16x16x32_bf16 v[60:63], v[152:155], v[184:187], v[60:63]
	v_mfma_f32_16x16x32_bf16 v[56:59], v[160:163], v[184:187], v[56:59]
	v_mfma_f32_16x16x32_bf16 v[48:51], v[152:155], v[192:195], v[48:51]
	v_mfma_f32_16x16x32_bf16 v[40:43], v[160:163], v[192:195], v[40:43]
	v_mfma_f32_16x16x32_bf16 v[32:35], v[152:155], v[200:203], v[32:35]
	v_mfma_f32_16x16x32_bf16 v[24:27], v[160:163], v[200:203], v[24:27]
	v_mfma_f32_16x16x32_bf16 v[16:19], v[152:155], v[208:211], v[16:19]
	v_mfma_f32_16x16x32_bf16 v[8:11], v[160:163], v[208:211], v[8:11]
	v_mfma_f32_16x16x32_bf16 v[60:63], v[156:159], v[188:191], v[60:63]
	v_mfma_f32_16x16x32_bf16 v[56:59], v[164:167], v[188:191], v[56:59]
	v_mfma_f32_16x16x32_bf16 v[48:51], v[156:159], v[196:199], v[48:51]
	v_mfma_f32_16x16x32_bf16 v[40:43], v[164:167], v[196:199], v[40:43]
	v_mfma_f32_16x16x32_bf16 v[32:35], v[156:159], v[204:207], v[32:35]
	v_mfma_f32_16x16x32_bf16 v[24:27], v[164:167], v[204:207], v[24:27]
	v_mfma_f32_16x16x32_bf16 v[16:19], v[156:159], v[212:215], v[16:19]
	v_mfma_f32_16x16x32_bf16 v[8:11], v[164:167], v[212:215], v[8:11]
	v_mfma_f32_16x16x32_bf16 v[52:55], v[168:171], v[184:187], v[52:55]
	v_mfma_f32_16x16x32_bf16 v[44:47], v[176:179], v[184:187], v[44:47]
	v_mfma_f32_16x16x32_bf16 v[36:39], v[168:171], v[192:195], v[36:39]
	v_mfma_f32_16x16x32_bf16 v[28:31], v[176:179], v[192:195], v[28:31]
	v_mfma_f32_16x16x32_bf16 v[20:23], v[168:171], v[200:203], v[20:23]
	v_mfma_f32_16x16x32_bf16 v[12:15], v[176:179], v[200:203], v[12:15]
	v_mfma_f32_16x16x32_bf16 v[4:7], v[168:171], v[208:211], v[4:7]
	v_mfma_f32_16x16x32_bf16 v[0:3], v[176:179], v[208:211], v[0:3]
	v_mfma_f32_16x16x32_bf16 v[52:55], v[172:175], v[188:191], v[52:55]
	v_mfma_f32_16x16x32_bf16 v[44:47], v[180:183], v[188:191], v[44:47]
	v_mfma_f32_16x16x32_bf16 v[36:39], v[172:175], v[196:199], v[36:39]
	v_mfma_f32_16x16x32_bf16 v[28:31], v[180:183], v[196:199], v[28:31]
	v_mfma_f32_16x16x32_bf16 v[20:23], v[172:175], v[204:207], v[20:23]
	v_mfma_f32_16x16x32_bf16 v[12:15], v[180:183], v[204:207], v[12:15]
	v_mfma_f32_16x16x32_bf16 v[4:7], v[172:175], v[212:215], v[4:7]
	v_mfma_f32_16x16x32_bf16 v[0:3], v[180:183], v[212:215], v[0:3]
	s_setprio 0
	s_barrier
; #define PG8_STAGE(bufoff, gbase, voff) do { _Pragma("unroll") for (int _i = 0; _i < 2; ++_i) \
;         __builtin_amdgcn_global_load_lds((const unsigned*)((const char*)(gbase) + (voff)[_i]), (LAS unsigned*)(lds + (bufoff) + ldsw + _i * 8192), 16, 0, 0); } while (0)
; #define PG8_LDA(dst, b, h) do { _Pragma("unroll") for (int m = 0; m < 4; ++m) _Pragma("unroll") for (int k = 0; k < 2; ++k) dst[m][k] = *(const LAS bf16x8*)(lds + PG8_SA(b, h) + aoff + m * 2048 + k * 1024); } while (0)
; #define PG8_LDB(dst, b, h) do { _Pragma("unroll") for (int n = 0; n < 2; ++n) _Pragma("unroll") for (int k = 0; k < 2; ++k) dst[n][k] = *(const LAS bf16x8*)(lds + PG8_SB(b, h) + boff + n * 2048 + k * 1024); } while (0)
; #define PG8_MMA(ai, bj, At, Bt) do { __builtin_amdgcn_s_setprio(1); _Pragma("unroll") for (int m = 0; m < 4; ++m) _Pragma("unroll") for (int n = 0; n < 2; ++n) _Pragma("unroll") for (int k = 0; k < 2; ++k) \
;         acc[ai][bj][m][n] = __builtin_amdgcn_mfma_f32_16x16x32_bf16(Bt[n][k], At[m][k], acc[ai][bj][m][n], 0, 0, 0); __builtin_amdgcn_s_setprio(0); } while (0)
; #define PG8_WAIT_V(n) asm volatile("s_waitcnt vmcnt(" #n ")" ::: "memory")
; #define PG8_WAIT_L(n) asm volatile("s_waitcnt lgkmcnt(" #n ")" ::: "memory")
; #define PG8_BAR __builtin_amdgcn_s_barrier()
; #define PG8_SCHED __builtin_amdgcn_sched_barrier(0)
; template <class Epi>
; __device__ __forceinline__ void gemm_phase(ldsp lds, const Gemm g, const StaticOrder& S, const Epi& E, int wave0) {
;     ...
;             PG8_LDB(B0, 1, 0); PG8_LDB(B1, 1, 1); PG8_SCHED; PG8_LDA(At, 1, 0); PG8_STAGE(PG8_SA(0, 1), a2 + hstep, voffA);
;             PG8_WAIT_V(8); PG8_WAIT_L(0); PG8_BAR; PG8_MMA(0, 0, At, B0); PG8_MMA(0, 1, At, B1); PG8_BAR; PG8_SCHED;
;             PG8_LDA(At, 1, 1); PG8_STAGE(PG8_SB(1, 0), b3, voffB); PG8_STAGE(PG8_SB(1, 1), b3 + hstep, voffB); PG8_STAGE(PG8_SA(1, 0), a3, voffA);
;             PG8_WAIT_V(8); PG8_WAIT_L(0); PG8_BAR; PG8_MMA(1, 0, At, B0); PG8_MMA(1, 1, At, B1); PG8_BAR; PG8_SCHED;
;         }
	s_add_i32 s70, 0, 0x18000
	s_add_i32 s71, 0, 0x1c000
	v_add_u32_e32 v164, s70, v148
	v_add_u32_e32 v180, s71, v148
	ds_read_b128 v[152:155], v164
	ds_read_b128 v[156:159], v164 offset:1024
	ds_read_b128 v[160:163], v164 offset:2048
	ds_read_b128 v[164:167], v164 offset:3072
	ds_read_b128 v[168:171], v180
	ds_read_b128 v[172:175], v180 offset:1024
	ds_read_b128 v[176:179], v180 offset:2048
	ds_read_b128 v[180:183], v180 offset:3072
	s_add_u32 s34, s40, 0x160000
	s_addc_u32 s35, s41, 0
	s_mov_b32 m0, s51
	ds_read_b128 v[184:187], v151 offset:32768
	ds_read_b128 v[188:191], v151 offset:33792
	ds_read_b128 v[192:195], v151 offset:34816
	ds_read_b128 v[196:199], v151 offset:35840
	ds_read_b128 v[200:203], v151 offset:36864
	ds_read_b128 v[204:207], v151 offset:37888
	ds_read_b128 v[208:211], v151 offset:38912
	ds_read_b128 v[212:215], v151 offset:39936
	global_load_lds_dwordx4 v128, s[34:35]
	s_mov_b32 m0, s52
	s_nop 0
	global_load_lds_dwordx4 v132, s[34:35]
	s_waitcnt vmcnt(8)
	s_waitcnt lgkmcnt(0)
	s_barrier
	s_setprio 1
	s_waitcnt lgkmcnt(0)
	v_mfma_f32_16x16x32_bf16 v[124:127], v[152:155], v[184:187], v[124:127]
	v_mfma_f32_16x16x32_bf16 v[120:123], v[160:163], v[184:187], v[120:123]
	v_mfma_f32_16x16x32_bf16 v[112:115], v[152:155], v[192:195], v[112:115]
	v_mfma_f32_16x16x32_bf16 v[104:107], v[160:163], v[192:195], v[104:107]
	v_mfma_f32_16x16x32_bf16 v[96:99], v[152:155], v[200:203], v[96:99]
	v_mfma_f32_16x16x32_bf16 v[88:91], v[160:163], v[200:203], v[88:91]
	v_mfma_f32_16x16x32_bf16 v[80:83], v[152:155], v[208:211], v[80:83]
	v_mfma_f32_16x16x32_bf16 v[72:75], v[160:163], v[208:211], v[72:75]
	v_mfma_f32_16x16x32_bf16 v[124:127], v[156:159], v[188:191], v[124:127]
	v_mfma_f32_16x16x32_bf16 v[120:123], v[164:167], v[188:191], v[120:123]
	v_mfma_f32_16x16x32_bf16 v[112:115], v[156:159], v[196:199], v[112:115]
	v_mfma_f32_16x16x32_bf16 v[104:107], v[164:167], v[196:199], v[104:107]
	v_mfma_f32_16x16x32_bf16 v[96:99], v[156:159], v[204:207], v[96:99]
	v_mfma_f32_16x16x32_bf16 v[88:91], v[164:167], v[204:207], v[88:91]
	v_mfma_f32_16x16x32_bf16 v[80:83], v[156:159], v[212:215], v[80:83]
	v_mfma_f32_16x16x32_bf16 v[72:75], v[164:167], v[212:215], v[72:75]
	v_mfma_f32_16x16x32_bf16 v[116:119], v[168:171], v[184:187], v[116:119]
	v_mfma_f32_16x16x32_bf16 v[108:111], v[176:179], v[184:187], v[108:111]
	v_mfma_f32_16x16x32_bf16 v[100:103], v[168:171], v[192:195], v[100:103]
	v_mfma_f32_16x16x32_bf16 v[92:95], v[176:179], v[192:195], v[92:95]
	v_mfma_f32_16x16x32_bf16 v[84:87], v[168:171], v[200:203], v[84:87]
	v_mfma_f32_16x16x32_bf16 v[76:79], v[176:179], v[200:203], v[76:79]
	v_mfma_f32_16x16x32_bf16 v[68:71], v[168:171], v[208:211], v[68:71]
	v_mfma_f32_16x16x32_bf16 v[64:67], v[176:179], v[208:211], v[64:67]
	v_mfma_f32_16x16x32_bf16 v[116:119], v[172:175], v[188:191], v[116:119]
	v_mfma_f32_16x16x32_bf16 v[108:111], v[180:183], v[188:191], v[108:111]
	v_mfma_f32_16x16x32_bf16 v[100:103], v[172:175], v[196:199], v[100:103]
	v_mfma_f32_16x16x32_bf16 v[92:95], v[180:183], v[196:199], v[92:95]
	v_mfma_f32_16x16x32_bf16 v[84:87], v[172:175], v[204:207], v[84:87]
	v_mfma_f32_16x16x32_bf16 v[76:79], v[180:183], v[204:207], v[76:79]
	v_mfma_f32_16x16x32_bf16 v[68:71], v[172:175], v[212:215], v[68:71]
	v_mfma_f32_16x16x32_bf16 v[64:67], v[180:183], v[212:215], v[64:67]
	s_setprio 0
	s_barrier
	s_add_i32 s34, s70, s48
	s_add_u32 s100, s38, 0x80
	s_addc_u32 s101, s39, 0
	s_add_u32 s98, s40, 0x80
	s_addc_u32 s99, s41, 0
	s_mov_b32 m0, s34
	ds_read_b128 v[184:187], v151 offset:49152
	ds_read_b128 v[188:191], v151 offset:50176
	ds_read_b128 v[192:195], v151 offset:51200
	ds_read_b128 v[196:199], v151 offset:52224
	ds_read_b128 v[200:203], v151 offset:53248
	ds_read_b128 v[204:207], v151 offset:54272
	ds_read_b128 v[208:211], v151 offset:55296
	ds_read_b128 v[212:215], v151 offset:56320
	global_load_lds_dwordx4 v130, s[100:101]
	s_add_i32 m0, s34, 0x2000
	s_add_u32 s34, s38, 0x160080
	s_addc_u32 s35, s39, 0
	s_add_i32 s38, s71, s48
	global_load_lds_dwordx4 v134, s[100:101]
	s_mov_b32 m0, s38
	s_nop 0
	global_load_lds_dwordx4 v130, s[34:35]
	s_add_i32 m0, s38, 0x2000
	s_nop 0
	global_load_lds_dwordx4 v134, s[34:35]
	s_mov_b32 m0, s56
	s_nop 0
	global_load_lds_dwordx4 v128, s[98:99]
	s_mov_b32 m0, s57
	s_nop 0
	global_load_lds_dwordx4 v132, s[98:99]
	s_waitcnt vmcnt(8)
	s_waitcnt lgkmcnt(0)
	s_barrier
	s_setprio 1
	s_waitcnt lgkmcnt(0)
	v_mfma_f32_16x16x32_bf16 v[60:63], v[152:155], v[184:187], v[60:63]
	v_mfma_f32_16x16x32_bf16 v[56:59], v[160:163], v[184:187], v[56:59]
	v_mfma_f32_16x16x32_bf16 v[48:51], v[152:155], v[192:195], v[48:51]
	v_mfma_f32_16x16x32_bf16 v[40:43], v[160:163], v[192:195], v[40:43]
	v_mfma_f32_16x16x32_bf16 v[32:35], v[152:155], v[200:203], v[32:35]
	v_mfma_f32_16x16x32_bf16 v[24:27], v[160:163], v[200:203], v[24:27]
	v_mfma_f32_16x16x32_bf16 v[16:19], v[152:155], v[208:211], v[16:19]
	v_mfma_f32_16x16x32_bf16 v[8:11], v[160:163], v[208:211], v[8:11]
	v_mfma_f32_16x16x32_bf16 v[60:63], v[156:159], v[188:191], v[60:63]
	v_mfma_f32_16x16x32_bf16 v[56:59], v[164:167], v[188:191], v[56:59]
	v_mfma_f32_16x16x32_bf16 v[48:51], v[156:159], v[196:199], v[48:51]
	v_mfma_f32_16x16x32_bf16 v[40:43], v[164:167], v[196:199], v[40:43]
	v_mfma_f32_16x16x32_bf16 v[32:35], v[156:159], v[204:207], v[32:35]
	v_mfma_f32_16x16x32_bf16 v[24:27], v[164:167], v[204:207], v[24:27]
	v_mfma_f32_16x16x32_bf16 v[16:19], v[156:159], v[212:215], v[16:19]
	v_mfma_f32_16x16x32_bf16 v[8:11], v[164:167], v[212:215], v[8:11]
	v_mfma_f32_16x16x32_bf16 v[52:55], v[168:171], v[184:187], v[52:55]
	v_mfma_f32_16x16x32_bf16 v[44:47], v[176:179], v[184:187], v[44:47]
	v_mfma_f32_16x16x32_bf16 v[36:39], v[168:171], v[192:195], v[36:39]
	v_mfma_f32_16x16x32_bf16 v[28:31], v[176:179], v[192:195], v[28:31]
	v_mfma_f32_16x16x32_bf16 v[20:23], v[168:171], v[200:203], v[20:23]
	v_mfma_f32_16x16x32_bf16 v[12:15], v[176:179], v[200:203], v[12:15]
	v_mfma_f32_16x16x32_bf16 v[4:7], v[168:171], v[208:211], v[4:7]
	v_mfma_f32_16x16x32_bf16 v[0:3], v[176:179], v[208:211], v[0:3]
	v_mfma_f32_16x16x32_bf16 v[52:55], v[172:175], v[188:191], v[52:55]
	v_mfma_f32_16x16x32_bf16 v[44:47], v[180:183], v[188:191], v[44:47]
	v_mfma_f32_16x16x32_bf16 v[36:39], v[172:175], v[196:199], v[36:39]
	v_mfma_f32_16x16x32_bf16 v[28:31], v[180:183], v[196:199], v[28:31]
	v_mfma_f32_16x16x32_bf16 v[20:23], v[172:175], v[204:207], v[20:23]
	v_mfma_f32_16x16x32_bf16 v[12:15], v[180:183], v[204:207], v[12:15]
	v_mfma_f32_16x16x32_bf16 v[4:7], v[172:175], v[212:215], v[4:7]
	v_mfma_f32_16x16x32_bf16 v[0:3], v[180:183], v[212:215], v[0:3]
	s_setprio 0
	s_barrier
	s_add_i32 s69, s69, 2
	s_add_u32 s67, s67, 0x100
	s_addc_u32 s68, s68, 0
	s_cmpk_gt_u32 s69, 0x55
	s_mov_b64 s[34:35], s[36:37]
	s_cbranch_scc0 .LBB0_222
	s_and_b64 vcc, exec, s[14:15]
	s_cbranch_vccz .LBB0_225
	s_barrier

; #define PG8_STAGE(bufoff, gbase, voff) do { _Pragma("unroll") for (int _i = 0; _i < 2; ++_i) \
;         __builtin_amdgcn_global_load_lds((const unsigned*)((const char*)(gbase) + (voff)[_i]), (LAS unsigned*)(lds + (bufoff) + ldsw + _i * 8192), 16, 0, 0); } while (0)
; #define PG8_LDA(dst, b, h) do { _Pragma("unroll") for (int m = 0; m < 4; ++m) _Pragma("unroll") for (int k = 0; k < 2; ++k) dst[m][k] = *(const LAS bf16x8*)(lds + PG8_SA(b, h) + aoff + m * 2048 + k * 1024); } while (0)
; #define PG8_LDB(dst, b, h) do { _Pragma("unroll") for (int n = 0; n < 2; ++n) _Pragma("unroll") for (int k = 0; k < 2; ++k) dst[n][k] = *(const LAS bf16x8*)(lds + PG8_SB(b, h) + boff + n * 2048 + k * 1024); } while (0)
; #define PG8_MMA(ai, bj, At, Bt) do { __builtin_amdgcn_s_setprio(1); _Pragma("unroll") for (int m = 0; m < 4; ++m) _Pragma("unroll") for (int n = 0; n < 2; ++n) _Pragma("unroll") for (int k = 0; k < 2; ++k) \
;         acc[ai][bj][m][n] = __builtin_amdgcn_mfma_f32_16x16x32_bf16(Bt[n][k], At[m][k], acc[ai][bj][m][n], 0, 0, 0); __builtin_amdgcn_s_setprio(0); } while (0)
; #define PG8_WAIT_V(n) asm volatile("s_waitcnt vmcnt(" #n ")" ::: "memory")
; #define PG8_WAIT_L(n) asm volatile("s_waitcnt lgkmcnt(" #n ")" ::: "memory")
; #define PG8_BAR __builtin_amdgcn_s_barrier()
; #define PG8_SCHED __builtin_amdgcn_sched_barrier(0)
; template <class Epi>
; __device__ __forceinline__ void gemm_phase(ldsp lds, const Gemm g, const StaticOrder& S, const Epi& E, int wave0) {
;     ...
;             const bool last = (t == nt - 2);
;             const char* a1 = cA + (size_t)(t + 1) * kstep;
;             const char* a2 = last ? nA : cA + (size_t)(t + 2) * kstep; const char* b2 = last ? nB : cB + (size_t)(t + 2) * kstep;
;             const char* a3 = a2 + kstep; const char* b3 = b2 + kstep;
;             PG8_LDB(B0, 0, 0); PG8_LDB(B1, 0, 1); PG8_SCHED; PG8_LDA(At, 0, 0); PG8_STAGE(PG8_SA(1, 1), a1 + hstep, voffA);
;             PG8_WAIT_V(8); PG8_WAIT_L(0); PG8_BAR; PG8_MMA(0, 0, At, B0); PG8_MMA(0, 1, At, B1); PG8_BAR; PG8_SCHED;
;             PG8_LDA(At, 0, 1); PG8_STAGE(PG8_SB(0, 0), b2, voffB); PG8_STAGE(PG8_SB(0, 1), b2 + hstep, voffB); PG8_STAGE(PG8_SA(0, 0), a2, voffA);
;             PG8_WAIT_V(8); PG8_WAIT_L(0); PG8_BAR; PG8_MMA(1, 0, At, B0); PG8_MMA(1, 1, At, B1); PG8_BAR; PG8_SCHED;
.LBB0_332:
	ds_read_b128 v[128:131], v171
	ds_read_b128 v[132:135], v171 offset:1024
	ds_read_b128 v[136:139], v171 offset:2048
	ds_read_b128 v[140:143], v171 offset:3072
	ds_read_b128 v[160:163], v172
	ds_read_b128 v[164:167], v172 offset:1024
	ds_read_b128 v[176:179], v172 offset:2048
	ds_read_b128 v[180:183], v172 offset:3072
	s_add_u32 s48, s46, 0xfff80080
	s_addc_u32 s49, s47, -1
	s_cmp_eq_u32 s89, 28
	s_cselect_b32 s51, s37, s49
	s_cselect_b32 s50, s45, s48
	s_cselect_b32 s49, s35, s88
	s_cselect_b32 s48, s52, s53
	s_add_i32 m0, s43, 0xc000
	ds_read_b128 v[184:187], v173
	ds_read_b128 v[188:191], v173 offset:1024
	ds_read_b128 v[192:195], v173 offset:2048
	ds_read_b128 v[196:199], v173 offset:3072
	ds_read_b128 v[200:203], v173 offset:4096
	ds_read_b128 v[204:207], v173 offset:5120
	ds_read_b128 v[208:211], v173 offset:6144
	ds_read_b128 v[212:215], v173 offset:7168
	global_load_lds_dwordx4 v154, s[46:47]
	s_add_i32 m0, s43, 0xe000
	s_nop 0
	global_load_lds_dwordx4 v152, s[46:47]
	s_waitcnt vmcnt(8)
	s_waitcnt lgkmcnt(0)
	s_barrier
	s_setprio 1
	s_waitcnt lgkmcnt(0)
	v_mfma_f32_16x16x32_bf16 v[124:127], v[128:131], v[184:187], v[124:127]
	v_mfma_f32_16x16x32_bf16 v[120:123], v[136:139], v[184:187], v[120:123]
	v_mfma_f32_16x16x32_bf16 v[108:111], v[128:131], v[192:195], v[108:111]
	v_mfma_f32_16x16x32_bf16 v[104:107], v[136:139], v[192:195], v[104:107]
	v_mfma_f32_16x16x32_bf16 v[92:95], v[128:131], v[200:203], v[92:95]
	v_mfma_f32_16x16x32_bf16 v[88:91], v[136:139], v[200:203], v[88:91]
	v_mfma_f32_16x16x32_bf16 v[76:79], v[128:131], v[208:211], v[76:79]
	v_mfma_f32_16x16x32_bf16 v[72:75], v[136:139], v[208:211], v[72:75]
	v_mfma_f32_16x16x32_bf16 v[124:127], v[132:135], v[188:191], v[124:127]
	v_mfma_f32_16x16x32_bf16 v[120:123], v[140:143], v[188:191], v[120:123]
	v_mfma_f32_16x16x32_bf16 v[108:111], v[132:135], v[196:199], v[108:111]
	v_mfma_f32_16x16x32_bf16 v[104:107], v[140:143], v[196:199], v[104:107]
	v_mfma_f32_16x16x32_bf16 v[92:95], v[132:135], v[204:207], v[92:95]
	v_mfma_f32_16x16x32_bf16 v[88:91], v[140:143], v[204:207], v[88:91]
	v_mfma_f32_16x16x32_bf16 v[76:79], v[132:135], v[212:215], v[76:79]
	v_mfma_f32_16x16x32_bf16 v[72:75], v[140:143], v[212:215], v[72:75]
	v_mfma_f32_16x16x32_bf16 v[116:119], v[160:163], v[184:187], v[116:119]
	v_mfma_f32_16x16x32_bf16 v[112:115], v[176:179], v[184:187], v[112:115]
	v_mfma_f32_16x16x32_bf16 v[100:103], v[160:163], v[192:195], v[100:103]
	v_mfma_f32_16x16x32_bf16 v[96:99], v[176:179], v[192:195], v[96:99]
	v_mfma_f32_16x16x32_bf16 v[84:87], v[160:163], v[200:203], v[84:87]
	v_mfma_f32_16x16x32_bf16 v[80:83], v[176:179], v[200:203], v[80:83]
	v_mfma_f32_16x16x32_bf16 v[68:71], v[160:163], v[208:211], v[68:71]
	v_mfma_f32_16x16x32_bf16 v[64:67], v[176:179], v[208:211], v[64:67]
	v_mfma_f32_16x16x32_bf16 v[116:119], v[164:167], v[188:191], v[116:119]
	v_mfma_f32_16x16x32_bf16 v[112:115], v[180:183], v[188:191], v[112:115]
	v_mfma_f32_16x16x32_bf16 v[100:103], v[164:167], v[196:199], v[100:103]
	v_mfma_f32_16x16x32_bf16 v[96:99], v[180:183], v[196:199], v[96:99]
	v_mfma_f32_16x16x32_bf16 v[84:87], v[164:167], v[204:207], v[84:87]
	v_mfma_f32_16x16x32_bf16 v[80:83], v[180:183], v[204:207], v[80:83]
	v_mfma_f32_16x16x32_bf16 v[68:71], v[164:167], v[212:215], v[68:71]
	v_mfma_f32_16x16x32_bf16 v[64:67], v[180:183], v[212:215], v[64:67]
	s_setprio 0
	s_barrier
	s_add_i32 s90, s79, s62
	s_add_u32 s100, s50, 0x80
	s_addc_u32 s101, s51, 0
	s_mov_b32 m0, s90
	ds_read_b128 v[184:187], v173 offset:16384
	ds_read_b128 v[188:191], v173 offset:17408
	ds_read_b128 v[192:195], v173 offset:18432
	ds_read_b128 v[196:199], v173 offset:19456
	ds_read_b128 v[200:203], v173 offset:20480
	ds_read_b128 v[204:207], v173 offset:21504
	ds_read_b128 v[208:211], v173 offset:22528
	ds_read_b128 v[212:215], v173 offset:23552
	global_load_lds_dwordx4 v146, s[48:49]
	s_add_i32 m0, s90, 0x2000
	s_add_u32 s90, s48, 0x80000
	s_addc_u32 s91, s49, 0
	s_add_i32 s92, s80, s62
	global_load_lds_dwordx4 v150, s[48:49]
	s_mov_b32 m0, s92
	s_nop 0
	global_load_lds_dwordx4 v146, s[90:91]
	s_add_i32 m0, s92, 0x2000
	s_nop 0
	global_load_lds_dwordx4 v150, s[90:91]
	s_mov_b32 m0, s43
	s_nop 0
	global_load_lds_dwordx4 v144, s[50:51]
	s_mov_b32 m0, s63
	s_nop 0
	global_load_lds_dwordx4 v148, s[50:51]
	s_waitcnt vmcnt(8)
	s_waitcnt lgkmcnt(0)
	s_barrier
	s_setprio 1
	s_waitcnt lgkmcnt(0)
	v_mfma_f32_16x16x32_bf16 v[60:63], v[128:131], v[184:187], v[60:63]
	v_mfma_f32_16x16x32_bf16 v[56:59], v[136:139], v[184:187], v[56:59]
	v_mfma_f32_16x16x32_bf16 v[44:47], v[128:131], v[192:195], v[44:47]
	v_mfma_f32_16x16x32_bf16 v[40:43], v[136:139], v[192:195], v[40:43]
	v_mfma_f32_16x16x32_bf16 v[28:31], v[128:131], v[200:203], v[28:31]
	v_mfma_f32_16x16x32_bf16 v[24:27], v[136:139], v[200:203], v[24:27]
	v_mfma_f32_16x16x32_bf16 v[12:15], v[128:131], v[208:211], v[12:15]
	v_mfma_f32_16x16x32_bf16 v[8:11], v[136:139], v[208:211], v[8:11]
	v_mfma_f32_16x16x32_bf16 v[60:63], v[132:135], v[188:191], v[60:63]
	v_mfma_f32_16x16x32_bf16 v[56:59], v[140:143], v[188:191], v[56:59]
	v_mfma_f32_16x16x32_bf16 v[44:47], v[132:135], v[196:199], v[44:47]
	v_mfma_f32_16x16x32_bf16 v[40:43], v[140:143], v[196:199], v[40:43]
	v_mfma_f32_16x16x32_bf16 v[28:31], v[132:135], v[204:207], v[28:31]
	v_mfma_f32_16x16x32_bf16 v[24:27], v[140:143], v[204:207], v[24:27]
	v_mfma_f32_16x16x32_bf16 v[12:15], v[132:135], v[212:215], v[12:15]
	v_mfma_f32_16x16x32_bf16 v[8:11], v[140:143], v[212:215], v[8:11]
	v_mfma_f32_16x16x32_bf16 v[52:55], v[160:163], v[184:187], v[52:55]
	v_mfma_f32_16x16x32_bf16 v[48:51], v[176:179], v[184:187], v[48:51]
	v_mfma_f32_16x16x32_bf16 v[36:39], v[160:163], v[192:195], v[36:39]
	v_mfma_f32_16x16x32_bf16 v[32:35], v[176:179], v[192:195], v[32:35]
	v_mfma_f32_16x16x32_bf16 v[20:23], v[160:163], v[200:203], v[20:23]
	v_mfma_f32_16x16x32_bf16 v[16:19], v[176:179], v[200:203], v[16:19]
	v_mfma_f32_16x16x32_bf16 v[4:7], v[160:163], v[208:211], v[4:7]
	v_mfma_f32_16x16x32_bf16 v[0:3], v[176:179], v[208:211], v[0:3]
	v_mfma_f32_16x16x32_bf16 v[52:55], v[164:167], v[188:191], v[52:55]
	v_mfma_f32_16x16x32_bf16 v[48:51], v[180:183], v[188:191], v[48:51]
	v_mfma_f32_16x16x32_bf16 v[36:39], v[164:167], v[196:199], v[36:39]
	v_mfma_f32_16x16x32_bf16 v[32:35], v[180:183], v[196:199], v[32:35]
	v_mfma_f32_16x16x32_bf16 v[20:23], v[164:167], v[204:207], v[20:23]
	v_mfma_f32_16x16x32_bf16 v[16:19], v[180:183], v[204:207], v[16:19]
	v_mfma_f32_16x16x32_bf16 v[4:7], v[164:167], v[212:215], v[4:7]
	v_mfma_f32_16x16x32_bf16 v[0:3], v[180:183], v[212:215], v[0:3]
	s_setprio 0
	s_barrier
; #define PG8_STAGE(bufoff, gbase, voff) do { _Pragma("unroll") for (int _i = 0; _i < 2; ++_i) \
;         __builtin_amdgcn_global_load_lds((const unsigned*)((const char*)(gbase) + (voff)[_i]), (LAS unsigned*)(lds + (bufoff) + ldsw + _i * 8192), 16, 0, 0); } while (0)
; #define PG8_LDA(dst, b, h) do { _Pragma("unroll") for (int m = 0; m < 4; ++m) _Pragma("unroll") for (int k = 0; k < 2; ++k) dst[m][k] = *(const LAS bf16x8*)(lds + PG8_SA(b, h) + aoff + m * 2048 + k * 1024); } while (0)
; #define PG8_LDB(dst, b, h) do { _Pragma("unroll") for (int n = 0; n < 2; ++n) _Pragma("unroll") for (int k = 0; k < 2; ++k) dst[n][k] = *(const LAS bf16x8*)(lds + PG8_SB(b, h) + boff + n * 2048 + k * 1024); } while (0)
; #define PG8_MMA(ai, bj, At, Bt) do { __builtin_amdgcn_s_setprio(1); _Pragma("unroll") for (int m = 0; m < 4; ++m) _Pragma("unroll") for (int n = 0; n < 2; ++n) _Pragma("unroll") for (int k = 0; k < 2; ++k) \
;         acc[ai][bj][m][n] = __builtin_amdgcn_mfma_f32_16x16x32_bf16(Bt[n][k], At[m][k], acc[ai][bj][m][n], 0, 0, 0); __builtin_amdgcn_s_setprio(0); } while (0)
; #define PG8_WAIT_V(n) asm volatile("s_waitcnt vmcnt(" #n ")" ::: "memory")
; #define PG8_WAIT_L(n) asm volatile("s_waitcnt lgkmcnt(" #n ")" ::: "memory")
; #define PG8_BAR __builtin_amdgcn_s_barrier()
; #define PG8_SCHED __builtin_amdgcn_sched_barrier(0)
; template <class Epi>
; __device__ __forceinline__ void gemm_phase(ldsp lds, const Gemm g, const StaticOrder& S, const Epi& E, int wave0) {
;     ...
;             PG8_LDB(B0, 1, 0); PG8_LDB(B1, 1, 1); PG8_SCHED; PG8_LDA(At, 1, 0); PG8_STAGE(PG8_SA(0, 1), a2 + hstep, voffA);
;             PG8_WAIT_V(8); PG8_WAIT_L(0); PG8_BAR; PG8_MMA(0, 0, At, B0); PG8_MMA(0, 1, At, B1); PG8_BAR; PG8_SCHED;
;             PG8_LDA(At, 1, 1); PG8_STAGE(PG8_SB(1, 0), b3, voffB); PG8_STAGE(PG8_SB(1, 1), b3 + hstep, voffB); PG8_STAGE(PG8_SA(1, 0), a3, voffA);
;             PG8_WAIT_V(8); PG8_WAIT_L(0); PG8_BAR; PG8_MMA(1, 0, At, B0); PG8_MMA(1, 1, At, B1); PG8_BAR; PG8_SCHED;
;         }
;         if (wr == 0) PG8_BAR;
	s_add_i32 s90, 0, 0x18000
	s_add_i32 s91, 0, 0x1c000
	v_add_u32_e32 v140, s90, v170
	v_add_u32_e32 v175, s91, v170
	ds_read_b128 v[128:131], v140
	ds_read_b128 v[132:135], v140 offset:1024
	ds_read_b128 v[136:139], v140 offset:2048
	ds_read_b128 v[140:143], v140 offset:3072
	ds_read_b128 v[160:163], v175
	ds_read_b128 v[164:167], v175 offset:1024
	ds_read_b128 v[176:179], v175 offset:2048
	ds_read_b128 v[180:183], v175 offset:3072
	s_add_u32 s50, s50, 0x80000
	s_addc_u32 s51, s51, 0
	s_mov_b32 m0, s64
	ds_read_b128 v[184:187], v173 offset:32768
	ds_read_b128 v[188:191], v173 offset:33792
	ds_read_b128 v[192:195], v173 offset:34816
	ds_read_b128 v[196:199], v173 offset:35840
	ds_read_b128 v[200:203], v173 offset:36864
	ds_read_b128 v[204:207], v173 offset:37888
	ds_read_b128 v[208:211], v173 offset:38912
	ds_read_b128 v[212:215], v173 offset:39936
	global_load_lds_dwordx4 v144, s[50:51]
	s_mov_b32 m0, s65
	s_nop 0
	global_load_lds_dwordx4 v148, s[50:51]
	s_waitcnt vmcnt(8)
	s_waitcnt lgkmcnt(0)
	s_barrier
	s_setprio 1
	s_waitcnt lgkmcnt(0)
	v_mfma_f32_16x16x32_bf16 v[124:127], v[128:131], v[184:187], v[124:127]
	v_mfma_f32_16x16x32_bf16 v[120:123], v[136:139], v[184:187], v[120:123]
	v_mfma_f32_16x16x32_bf16 v[108:111], v[128:131], v[192:195], v[108:111]
	v_mfma_f32_16x16x32_bf16 v[104:107], v[136:139], v[192:195], v[104:107]
	v_mfma_f32_16x16x32_bf16 v[92:95], v[128:131], v[200:203], v[92:95]
	v_mfma_f32_16x16x32_bf16 v[88:91], v[136:139], v[200:203], v[88:91]
	v_mfma_f32_16x16x32_bf16 v[76:79], v[128:131], v[208:211], v[76:79]
	v_mfma_f32_16x16x32_bf16 v[72:75], v[136:139], v[208:211], v[72:75]
	v_mfma_f32_16x16x32_bf16 v[124:127], v[132:135], v[188:191], v[124:127]
	v_mfma_f32_16x16x32_bf16 v[120:123], v[140:143], v[188:191], v[120:123]
	v_mfma_f32_16x16x32_bf16 v[108:111], v[132:135], v[196:199], v[108:111]
	v_mfma_f32_16x16x32_bf16 v[104:107], v[140:143], v[196:199], v[104:107]
	v_mfma_f32_16x16x32_bf16 v[92:95], v[132:135], v[204:207], v[92:95]
	v_mfma_f32_16x16x32_bf16 v[88:91], v[140:143], v[204:207], v[88:91]
	v_mfma_f32_16x16x32_bf16 v[76:79], v[132:135], v[212:215], v[76:79]
	v_mfma_f32_16x16x32_bf16 v[72:75], v[140:143], v[212:215], v[72:75]
	v_mfma_f32_16x16x32_bf16 v[116:119], v[160:163], v[184:187], v[116:119]
	v_mfma_f32_16x16x32_bf16 v[112:115], v[176:179], v[184:187], v[112:115]
	v_mfma_f32_16x16x32_bf16 v[100:103], v[160:163], v[192:195], v[100:103]
	v_mfma_f32_16x16x32_bf16 v[96:99], v[176:179], v[192:195], v[96:99]
	v_mfma_f32_16x16x32_bf16 v[84:87], v[160:163], v[200:203], v[84:87]
	v_mfma_f32_16x16x32_bf16 v[80:83], v[176:179], v[200:203], v[80:83]
	v_mfma_f32_16x16x32_bf16 v[68:71], v[160:163], v[208:211], v[68:71]
	v_mfma_f32_16x16x32_bf16 v[64:67], v[176:179], v[208:211], v[64:67]
	v_mfma_f32_16x16x32_bf16 v[116:119], v[164:167], v[188:191], v[116:119]
	v_mfma_f32_16x16x32_bf16 v[112:115], v[180:183], v[188:191], v[112:115]
	v_mfma_f32_16x16x32_bf16 v[100:103], v[164:167], v[196:199], v[100:103]
	v_mfma_f32_16x16x32_bf16 v[96:99], v[180:183], v[196:199], v[96:99]
	v_mfma_f32_16x16x32_bf16 v[84:87], v[164:167], v[204:207], v[84:87]
	v_mfma_f32_16x16x32_bf16 v[80:83], v[180:183], v[204:207], v[80:83]
	v_mfma_f32_16x16x32_bf16 v[68:71], v[164:167], v[212:215], v[68:71]
	v_mfma_f32_16x16x32_bf16 v[64:67], v[180:183], v[212:215], v[64:67]
	s_setprio 0
	s_barrier
	s_add_i32 s50, s90, s62
	s_add_u32 s48, s48, 0x80
	s_addc_u32 s49, s49, 0
	s_mov_b32 m0, s50
	ds_read_b128 v[184:187], v173 offset:49152
	ds_read_b128 v[188:191], v173 offset:50176
	ds_read_b128 v[192:195], v173 offset:51200
	ds_read_b128 v[196:199], v173 offset:52224
	ds_read_b128 v[200:203], v173 offset:53248
	ds_read_b128 v[204:207], v173 offset:54272
	ds_read_b128 v[208:211], v173 offset:55296
	ds_read_b128 v[212:215], v173 offset:56320
	global_load_lds_dwordx4 v146, s[48:49]
	s_add_i32 m0, s50, 0x2000
	s_add_i32 s50, s91, s62
	global_load_lds_dwordx4 v150, s[48:49]
	s_add_u32 s48, s48, 0x80000
	s_addc_u32 s49, s49, 0
	s_mov_b32 m0, s50
	s_nop 0
	global_load_lds_dwordx4 v146, s[48:49]
	s_add_i32 m0, s50, 0x2000
	s_nop 0
	global_load_lds_dwordx4 v150, s[48:49]
	s_mov_b32 m0, s70
	s_nop 0
	global_load_lds_dwordx4 v144, s[100:101]
	s_mov_b32 m0, s71
	s_nop 0
	global_load_lds_dwordx4 v148, s[100:101]
	s_waitcnt vmcnt(8)
	s_waitcnt lgkmcnt(0)
	s_barrier
	s_setprio 1
	s_waitcnt lgkmcnt(0)
	v_mfma_f32_16x16x32_bf16 v[60:63], v[128:131], v[184:187], v[60:63]
	v_mfma_f32_16x16x32_bf16 v[56:59], v[136:139], v[184:187], v[56:59]
	v_mfma_f32_16x16x32_bf16 v[44:47], v[128:131], v[192:195], v[44:47]
	v_mfma_f32_16x16x32_bf16 v[40:43], v[136:139], v[192:195], v[40:43]
	v_mfma_f32_16x16x32_bf16 v[28:31], v[128:131], v[200:203], v[28:31]
	v_mfma_f32_16x16x32_bf16 v[24:27], v[136:139], v[200:203], v[24:27]
	v_mfma_f32_16x16x32_bf16 v[12:15], v[128:131], v[208:211], v[12:15]
	v_mfma_f32_16x16x32_bf16 v[8:11], v[136:139], v[208:211], v[8:11]
	v_mfma_f32_16x16x32_bf16 v[60:63], v[132:135], v[188:191], v[60:63]
	v_mfma_f32_16x16x32_bf16 v[56:59], v[140:143], v[188:191], v[56:59]
	v_mfma_f32_16x16x32_bf16 v[44:47], v[132:135], v[196:199], v[44:47]
	v_mfma_f32_16x16x32_bf16 v[40:43], v[140:143], v[196:199], v[40:43]
	v_mfma_f32_16x16x32_bf16 v[28:31], v[132:135], v[204:207], v[28:31]
	v_mfma_f32_16x16x32_bf16 v[24:27], v[140:143], v[204:207], v[24:27]
	v_mfma_f32_16x16x32_bf16 v[12:15], v[132:135], v[212:215], v[12:15]
	v_mfma_f32_16x16x32_bf16 v[8:11], v[140:143], v[212:215], v[8:11]
	v_mfma_f32_16x16x32_bf16 v[52:55], v[160:163], v[184:187], v[52:55]
	v_mfma_f32_16x16x32_bf16 v[48:51], v[176:179], v[184:187], v[48:51]
	v_mfma_f32_16x16x32_bf16 v[36:39], v[160:163], v[192:195], v[36:39]
	v_mfma_f32_16x16x32_bf16 v[32:35], v[176:179], v[192:195], v[32:35]
	v_mfma_f32_16x16x32_bf16 v[20:23], v[160:163], v[200:203], v[20:23]
	v_mfma_f32_16x16x32_bf16 v[16:19], v[176:179], v[200:203], v[16:19]
	v_mfma_f32_16x16x32_bf16 v[4:7], v[160:163], v[208:211], v[4:7]
	v_mfma_f32_16x16x32_bf16 v[0:3], v[176:179], v[208:211], v[0:3]
	v_mfma_f32_16x16x32_bf16 v[52:55], v[164:167], v[188:191], v[52:55]
	v_mfma_f32_16x16x32_bf16 v[48:51], v[180:183], v[188:191], v[48:51]
	v_mfma_f32_16x16x32_bf16 v[36:39], v[164:167], v[196:199], v[36:39]
	v_mfma_f32_16x16x32_bf16 v[32:35], v[180:183], v[196:199], v[32:35]
	v_mfma_f32_16x16x32_bf16 v[20:23], v[164:167], v[204:207], v[20:23]
	v_mfma_f32_16x16x32_bf16 v[16:19], v[180:183], v[204:207], v[16:19]
	v_mfma_f32_16x16x32_bf16 v[4:7], v[164:167], v[212:215], v[4:7]
	v_mfma_f32_16x16x32_bf16 v[0:3], v[180:183], v[212:215], v[0:3]
	s_setprio 0
	s_barrier
	s_add_i32 s89, s89, 2
	s_add_u32 s53, s53, 0x100
	s_addc_u32 s88, s88, 0
	s_add_u32 s46, s46, 0x100
	s_addc_u32 s47, s47, 0
	s_cmp_gt_u32 s89, 29
	s_cbranch_scc0 .LBB0_332
	s_and_b64 vcc, exec, s[18:19]
	s_cbranch_vccz .LBB0_335
	s_barrier

; #define PG8_STAGE(bufoff, gbase, voff) do { _Pragma("unroll") for (int _i = 0; _i < 2; ++_i) \
;         __builtin_amdgcn_global_load_lds((const unsigned*)((const char*)(gbase) + (voff)[_i]), (LAS unsigned*)(lds + (bufoff) + ldsw + _i * 8192), 16, 0, 0); } while (0)
; #define PG8_LDA(dst, b, h) do { _Pragma("unroll") for (int m = 0; m < 4; ++m) _Pragma("unroll") for (int k = 0; k < 2; ++k) dst[m][k] = *(const LAS bf16x8*)(lds + PG8_SA(b, h) + aoff + m * 2048 + k * 1024); } while (0)
; #define PG8_LDB(dst, b, h) do { _Pragma("unroll") for (int n = 0; n < 2; ++n) _Pragma("unroll") for (int k = 0; k < 2; ++k) dst[n][k] = *(const LAS bf16x8*)(lds + PG8_SB(b, h) + boff + n * 2048 + k * 1024); } while (0)
; #define PG8_MMA(ai, bj, At, Bt) do { __builtin_amdgcn_s_setprio(1); _Pragma("unroll") for (int m = 0; m < 4; ++m) _Pragma("unroll") for (int n = 0; n < 2; ++n) _Pragma("unroll") for (int k = 0; k < 2; ++k) \
;         acc[ai][bj][m][n] = __builtin_amdgcn_mfma_f32_16x16x32_bf16(Bt[n][k], At[m][k], acc[ai][bj][m][n], 0, 0, 0); __builtin_amdgcn_s_setprio(0); } while (0)
; #define PG8_WAIT_V(n) asm volatile("s_waitcnt vmcnt(" #n ")" ::: "memory")
; #define PG8_WAIT_L(n) asm volatile("s_waitcnt lgkmcnt(" #n ")" ::: "memory")
; #define PG8_BAR __builtin_amdgcn_s_barrier()
; #define PG8_SCHED __builtin_amdgcn_sched_barrier(0)
; template <class Epi>
; __device__ __forceinline__ void gemm_phase(ldsp lds, const Gemm g, const StaticOrder& S, const Epi& E, int wave0) {
;     ...
;             const bool last = (t == nt - 2);
;             const char* a1 = cA + (size_t)(t + 1) * kstep;
;             const char* a2 = last ? nA : cA + (size_t)(t + 2) * kstep; const char* b2 = last ? nB : cB + (size_t)(t + 2) * kstep;
;             const char* a3 = a2 + kstep; const char* b3 = b2 + kstep;
;             PG8_LDB(B0, 0, 0); PG8_LDB(B1, 0, 1); PG8_SCHED; PG8_LDA(At, 0, 0); PG8_STAGE(PG8_SA(1, 1), a1 + hstep, voffA);
;             PG8_WAIT_V(8); PG8_WAIT_L(0); PG8_BAR; PG8_MMA(0, 0, At, B0); PG8_MMA(0, 1, At, B1); PG8_BAR; PG8_SCHED;
;             PG8_LDA(At, 0, 1); PG8_STAGE(PG8_SB(0, 0), b2, voffB); PG8_STAGE(PG8_SB(0, 1), b2 + hstep, voffB); PG8_STAGE(PG8_SA(0, 0), a2, voffA);
;             PG8_WAIT_V(8); PG8_WAIT_L(0); PG8_BAR; PG8_MMA(1, 0, At, B0); PG8_MMA(1, 1, At, B1); PG8_BAR; PG8_SCHED;
.LBB0_375:
	ds_read_b128 v[144:147], v151
	ds_read_b128 v[154:157], v151 offset:1024
	ds_read_b128 v[158:161], v151 offset:2048
	ds_read_b128 v[162:165], v151 offset:3072
	ds_read_b128 v[166:169], v152
	ds_read_b128 v[170:173], v152 offset:1024
	ds_read_b128 v[174:177], v152 offset:2048
	ds_read_b128 v[178:181], v152 offset:3072
	s_add_u32 s20, s18, 0xfff80080
	s_addc_u32 s21, s19, -1
	s_cmp_eq_u32 s56, 28
	s_cselect_b32 s23, s11, s21
	s_cselect_b32 s22, s17, s20
	s_cselect_b32 s21, s9, s55
	s_cselect_b32 s20, s53, s54
	s_add_i32 m0, s36, 0xc000
	ds_read_b128 v[182:185], v153
	ds_read_b128 v[186:189], v153 offset:1024
	ds_read_b128 v[190:193], v153 offset:2048
	ds_read_b128 v[194:197], v153 offset:3072
	ds_read_b128 v[198:201], v153 offset:4096
	ds_read_b128 v[202:205], v153 offset:5120
	ds_read_b128 v[206:209], v153 offset:6144
	ds_read_b128 v[210:213], v153 offset:7168
	global_load_lds_dwordx4 v138, s[18:19]
	s_add_i32 m0, s36, 0xe000
	s_nop 0
	global_load_lds_dwordx4 v136, s[18:19]
	s_waitcnt vmcnt(8)
	s_waitcnt lgkmcnt(0)
	s_barrier
	s_setprio 1
	s_waitcnt lgkmcnt(0)
	v_mfma_f32_16x16x32_bf16 v[124:127], v[144:147], v[182:185], v[124:127]
	v_mfma_f32_16x16x32_bf16 v[120:123], v[158:161], v[182:185], v[120:123]
	v_mfma_f32_16x16x32_bf16 v[112:115], v[144:147], v[190:193], v[112:115]
	v_mfma_f32_16x16x32_bf16 v[104:107], v[158:161], v[190:193], v[104:107]
	v_mfma_f32_16x16x32_bf16 v[100:103], v[144:147], v[198:201], v[100:103]
	v_mfma_f32_16x16x32_bf16 v[92:95], v[158:161], v[198:201], v[92:95]
	v_mfma_f32_16x16x32_bf16 v[84:87], v[144:147], v[206:209], v[84:87]
	v_mfma_f32_16x16x32_bf16 v[76:79], v[158:161], v[206:209], v[76:79]
	v_mfma_f32_16x16x32_bf16 v[124:127], v[154:157], v[186:189], v[124:127]
	v_mfma_f32_16x16x32_bf16 v[120:123], v[162:165], v[186:189], v[120:123]
	v_mfma_f32_16x16x32_bf16 v[112:115], v[154:157], v[194:197], v[112:115]
	v_mfma_f32_16x16x32_bf16 v[104:107], v[162:165], v[194:197], v[104:107]
	v_mfma_f32_16x16x32_bf16 v[100:103], v[154:157], v[202:205], v[100:103]
	v_mfma_f32_16x16x32_bf16 v[92:95], v[162:165], v[202:205], v[92:95]
	v_mfma_f32_16x16x32_bf16 v[84:87], v[154:157], v[210:213], v[84:87]
	v_mfma_f32_16x16x32_bf16 v[76:79], v[162:165], v[210:213], v[76:79]
	v_mfma_f32_16x16x32_bf16 v[116:119], v[166:169], v[182:185], v[116:119]
	v_mfma_f32_16x16x32_bf16 v[108:111], v[174:177], v[182:185], v[108:111]
	v_mfma_f32_16x16x32_bf16 v[96:99], v[166:169], v[190:193], v[96:99]
	v_mfma_f32_16x16x32_bf16 v[88:91], v[174:177], v[190:193], v[88:91]
	v_mfma_f32_16x16x32_bf16 v[80:83], v[166:169], v[198:201], v[80:83]
	v_mfma_f32_16x16x32_bf16 v[72:75], v[174:177], v[198:201], v[72:75]
	v_mfma_f32_16x16x32_bf16 v[68:71], v[166:169], v[206:209], v[68:71]
	v_mfma_f32_16x16x32_bf16 v[64:67], v[174:177], v[206:209], v[64:67]
	v_mfma_f32_16x16x32_bf16 v[116:119], v[170:173], v[186:189], v[116:119]
	v_mfma_f32_16x16x32_bf16 v[108:111], v[178:181], v[186:189], v[108:111]
	v_mfma_f32_16x16x32_bf16 v[96:99], v[170:173], v[194:197], v[96:99]
	v_mfma_f32_16x16x32_bf16 v[88:91], v[178:181], v[194:197], v[88:91]
	v_mfma_f32_16x16x32_bf16 v[80:83], v[170:173], v[202:205], v[80:83]
	v_mfma_f32_16x16x32_bf16 v[72:75], v[178:181], v[202:205], v[72:75]
	v_mfma_f32_16x16x32_bf16 v[68:71], v[170:173], v[210:213], v[68:71]
	v_mfma_f32_16x16x32_bf16 v[64:67], v[178:181], v[210:213], v[64:67]
	s_setprio 0
	s_barrier
	s_add_i32 s57, s50, s31
	s_add_u32 s100, s22, 0x80
	s_addc_u32 s101, s23, 0
	s_mov_b32 m0, s57
	ds_read_b128 v[182:185], v153 offset:16384
	ds_read_b128 v[186:189], v153 offset:17408
	ds_read_b128 v[190:193], v153 offset:18432
	ds_read_b128 v[194:197], v153 offset:19456
	ds_read_b128 v[198:201], v153 offset:20480
	ds_read_b128 v[202:205], v153 offset:21504
	ds_read_b128 v[206:209], v153 offset:22528
	ds_read_b128 v[210:213], v153 offset:23552
	global_load_lds_dwordx4 v132, s[20:21]
	s_add_i32 m0, s57, 0x2000
	s_add_u32 s60, s20, 0x80000
	s_addc_u32 s61, s21, 0
	s_add_i32 s57, s51, s31
	global_load_lds_dwordx4 v128, s[20:21]
	s_mov_b32 m0, s57
	s_nop 0
	global_load_lds_dwordx4 v132, s[60:61]
	s_add_i32 m0, s57, 0x2000
	s_nop 0
	global_load_lds_dwordx4 v128, s[60:61]
	s_mov_b32 m0, s36
	s_nop 0
	global_load_lds_dwordx4 v134, s[22:23]
	s_mov_b32 m0, s37
	s_nop 0
	global_load_lds_dwordx4 v130, s[22:23]
	s_waitcnt vmcnt(8)
	s_waitcnt lgkmcnt(0)
	s_barrier
	s_setprio 1
	s_waitcnt lgkmcnt(0)
	v_mfma_f32_16x16x32_bf16 v[60:63], v[144:147], v[182:185], v[60:63]
	v_mfma_f32_16x16x32_bf16 v[56:59], v[158:161], v[182:185], v[56:59]
	v_mfma_f32_16x16x32_bf16 v[52:55], v[144:147], v[190:193], v[52:55]
	v_mfma_f32_16x16x32_bf16 v[44:47], v[158:161], v[190:193], v[44:47]
	v_mfma_f32_16x16x32_bf16 v[36:39], v[144:147], v[198:201], v[36:39]
	v_mfma_f32_16x16x32_bf16 v[28:31], v[158:161], v[198:201], v[28:31]
	v_mfma_f32_16x16x32_bf16 v[20:23], v[144:147], v[206:209], v[20:23]
	v_mfma_f32_16x16x32_bf16 v[12:15], v[158:161], v[206:209], v[12:15]
	v_mfma_f32_16x16x32_bf16 v[60:63], v[154:157], v[186:189], v[60:63]
	v_mfma_f32_16x16x32_bf16 v[56:59], v[162:165], v[186:189], v[56:59]
	v_mfma_f32_16x16x32_bf16 v[52:55], v[154:157], v[194:197], v[52:55]
	v_mfma_f32_16x16x32_bf16 v[44:47], v[162:165], v[194:197], v[44:47]
	v_mfma_f32_16x16x32_bf16 v[36:39], v[154:157], v[202:205], v[36:39]
	v_mfma_f32_16x16x32_bf16 v[28:31], v[162:165], v[202:205], v[28:31]
	v_mfma_f32_16x16x32_bf16 v[20:23], v[154:157], v[210:213], v[20:23]
	v_mfma_f32_16x16x32_bf16 v[12:15], v[162:165], v[210:213], v[12:15]
	v_mfma_f32_16x16x32_bf16 v[48:51], v[166:169], v[182:185], v[48:51]
	v_mfma_f32_16x16x32_bf16 v[40:43], v[174:177], v[182:185], v[40:43]
	v_mfma_f32_16x16x32_bf16 v[32:35], v[166:169], v[190:193], v[32:35]
	v_mfma_f32_16x16x32_bf16 v[24:27], v[174:177], v[190:193], v[24:27]
	v_mfma_f32_16x16x32_bf16 v[16:19], v[166:169], v[198:201], v[16:19]
	v_mfma_f32_16x16x32_bf16 v[8:11], v[174:177], v[198:201], v[8:11]
	v_mfma_f32_16x16x32_bf16 v[4:7], v[166:169], v[206:209], v[4:7]
	v_mfma_f32_16x16x32_bf16 v[0:3], v[174:177], v[206:209], v[0:3]
	v_mfma_f32_16x16x32_bf16 v[48:51], v[170:173], v[186:189], v[48:51]
	v_mfma_f32_16x16x32_bf16 v[40:43], v[178:181], v[186:189], v[40:43]
	v_mfma_f32_16x16x32_bf16 v[32:35], v[170:173], v[194:197], v[32:35]
	v_mfma_f32_16x16x32_bf16 v[24:27], v[178:181], v[194:197], v[24:27]
	v_mfma_f32_16x16x32_bf16 v[16:19], v[170:173], v[202:205], v[16:19]
	v_mfma_f32_16x16x32_bf16 v[8:11], v[178:181], v[202:205], v[8:11]
	v_mfma_f32_16x16x32_bf16 v[4:7], v[170:173], v[210:213], v[4:7]
	v_mfma_f32_16x16x32_bf16 v[0:3], v[178:181], v[210:213], v[0:3]
	s_setprio 0
	s_barrier
; #define PG8_STAGE(bufoff, gbase, voff) do { _Pragma("unroll") for (int _i = 0; _i < 2; ++_i) \
;         __builtin_amdgcn_global_load_lds((const unsigned*)((const char*)(gbase) + (voff)[_i]), (LAS unsigned*)(lds + (bufoff) + ldsw + _i * 8192), 16, 0, 0); } while (0)
; #define PG8_LDA(dst, b, h) do { _Pragma("unroll") for (int m = 0; m < 4; ++m) _Pragma("unroll") for (int k = 0; k < 2; ++k) dst[m][k] = *(const LAS bf16x8*)(lds + PG8_SA(b, h) + aoff + m * 2048 + k * 1024); } while (0)
; #define PG8_LDB(dst, b, h) do { _Pragma("unroll") for (int n = 0; n < 2; ++n) _Pragma("unroll") for (int k = 0; k < 2; ++k) dst[n][k] = *(const LAS bf16x8*)(lds + PG8_SB(b, h) + boff + n * 2048 + k * 1024); } while (0)
; #define PG8_MMA(ai, bj, At, Bt) do { __builtin_amdgcn_s_setprio(1); _Pragma("unroll") for (int m = 0; m < 4; ++m) _Pragma("unroll") for (int n = 0; n < 2; ++n) _Pragma("unroll") for (int k = 0; k < 2; ++k) \
;         acc[ai][bj][m][n] = __builtin_amdgcn_mfma_f32_16x16x32_bf16(Bt[n][k], At[m][k], acc[ai][bj][m][n], 0, 0, 0); __builtin_amdgcn_s_setprio(0); } while (0)
; #define PG8_WAIT_V(n) asm volatile("s_waitcnt vmcnt(" #n ")" ::: "memory")
; #define PG8_WAIT_L(n) asm volatile("s_waitcnt lgkmcnt(" #n ")" ::: "memory")
; #define PG8_BAR __builtin_amdgcn_s_barrier()
; #define PG8_SCHED __builtin_amdgcn_sched_barrier(0)
; template <class Epi>
; __device__ __forceinline__ void gemm_phase(ldsp lds, const Gemm g, const StaticOrder& S, const Epi& E, int wave0) {
;     ...
;             PG8_LDB(B0, 1, 0); PG8_LDB(B1, 1, 1); PG8_SCHED; PG8_LDA(At, 1, 0); PG8_STAGE(PG8_SA(0, 1), a2 + hstep, voffA);
;             PG8_WAIT_V(8); PG8_WAIT_L(0); PG8_BAR; PG8_MMA(0, 0, At, B0); PG8_MMA(0, 1, At, B1); PG8_BAR; PG8_SCHED;
;             PG8_LDA(At, 1, 1); PG8_STAGE(PG8_SB(1, 0), b3, voffB); PG8_STAGE(PG8_SB(1, 1), b3 + hstep, voffB); PG8_STAGE(PG8_SA(1, 0), a3, voffA);
;             PG8_WAIT_V(8); PG8_WAIT_L(0); PG8_BAR; PG8_MMA(1, 0, At, B0); PG8_MMA(1, 1, At, B1); PG8_BAR; PG8_SCHED;
;         }
;         if (wr == 0) PG8_BAR;
	s_add_i32 s57, 0, 0x18000
	s_add_i32 s60, 0, 0x1c000
	v_add_u32_e32 v162, s57, v150
	v_add_u32_e32 v178, s60, v150
	ds_read_b128 v[144:147], v162
	ds_read_b128 v[154:157], v162 offset:1024
	ds_read_b128 v[158:161], v162 offset:2048
	ds_read_b128 v[162:165], v162 offset:3072
	ds_read_b128 v[166:169], v178
	ds_read_b128 v[170:173], v178 offset:1024
	ds_read_b128 v[174:177], v178 offset:2048
	ds_read_b128 v[178:181], v178 offset:3072
	s_add_u32 s22, s22, 0x80000
	s_addc_u32 s23, s23, 0
	s_mov_b32 m0, s38
	ds_read_b128 v[182:185], v153 offset:32768
	ds_read_b128 v[186:189], v153 offset:33792
	ds_read_b128 v[190:193], v153 offset:34816
	ds_read_b128 v[194:197], v153 offset:35840
	ds_read_b128 v[198:201], v153 offset:36864
	ds_read_b128 v[202:205], v153 offset:37888
	ds_read_b128 v[206:209], v153 offset:38912
	ds_read_b128 v[210:213], v153 offset:39936
	global_load_lds_dwordx4 v134, s[22:23]
	s_mov_b32 m0, s39
	s_nop 0
	global_load_lds_dwordx4 v130, s[22:23]
	s_waitcnt vmcnt(8)
	s_waitcnt lgkmcnt(0)
	s_barrier
	s_setprio 1
	s_waitcnt lgkmcnt(0)
	v_mfma_f32_16x16x32_bf16 v[124:127], v[144:147], v[182:185], v[124:127]
	v_mfma_f32_16x16x32_bf16 v[120:123], v[158:161], v[182:185], v[120:123]
	v_mfma_f32_16x16x32_bf16 v[112:115], v[144:147], v[190:193], v[112:115]
	v_mfma_f32_16x16x32_bf16 v[104:107], v[158:161], v[190:193], v[104:107]
	v_mfma_f32_16x16x32_bf16 v[100:103], v[144:147], v[198:201], v[100:103]
	v_mfma_f32_16x16x32_bf16 v[92:95], v[158:161], v[198:201], v[92:95]
	v_mfma_f32_16x16x32_bf16 v[84:87], v[144:147], v[206:209], v[84:87]
	v_mfma_f32_16x16x32_bf16 v[76:79], v[158:161], v[206:209], v[76:79]
	v_mfma_f32_16x16x32_bf16 v[124:127], v[154:157], v[186:189], v[124:127]
	v_mfma_f32_16x16x32_bf16 v[120:123], v[162:165], v[186:189], v[120:123]
	v_mfma_f32_16x16x32_bf16 v[112:115], v[154:157], v[194:197], v[112:115]
	v_mfma_f32_16x16x32_bf16 v[104:107], v[162:165], v[194:197], v[104:107]
	v_mfma_f32_16x16x32_bf16 v[100:103], v[154:157], v[202:205], v[100:103]
	v_mfma_f32_16x16x32_bf16 v[92:95], v[162:165], v[202:205], v[92:95]
	v_mfma_f32_16x16x32_bf16 v[84:87], v[154:157], v[210:213], v[84:87]
	v_mfma_f32_16x16x32_bf16 v[76:79], v[162:165], v[210:213], v[76:79]
	v_mfma_f32_16x16x32_bf16 v[116:119], v[166:169], v[182:185], v[116:119]
	v_mfma_f32_16x16x32_bf16 v[108:111], v[174:177], v[182:185], v[108:111]
	v_mfma_f32_16x16x32_bf16 v[96:99], v[166:169], v[190:193], v[96:99]
	v_mfma_f32_16x16x32_bf16 v[88:91], v[174:177], v[190:193], v[88:91]
	v_mfma_f32_16x16x32_bf16 v[80:83], v[166:169], v[198:201], v[80:83]
	v_mfma_f32_16x16x32_bf16 v[72:75], v[174:177], v[198:201], v[72:75]
	v_mfma_f32_16x16x32_bf16 v[68:71], v[166:169], v[206:209], v[68:71]
	v_mfma_f32_16x16x32_bf16 v[64:67], v[174:177], v[206:209], v[64:67]
	v_mfma_f32_16x16x32_bf16 v[116:119], v[170:173], v[186:189], v[116:119]
	v_mfma_f32_16x16x32_bf16 v[108:111], v[178:181], v[186:189], v[108:111]
	v_mfma_f32_16x16x32_bf16 v[96:99], v[170:173], v[194:197], v[96:99]
	v_mfma_f32_16x16x32_bf16 v[88:91], v[178:181], v[194:197], v[88:91]
	v_mfma_f32_16x16x32_bf16 v[80:83], v[170:173], v[202:205], v[80:83]
	v_mfma_f32_16x16x32_bf16 v[72:75], v[178:181], v[202:205], v[72:75]
	v_mfma_f32_16x16x32_bf16 v[68:71], v[170:173], v[210:213], v[68:71]
	v_mfma_f32_16x16x32_bf16 v[64:67], v[178:181], v[210:213], v[64:67]
	s_setprio 0
	s_barrier
	s_add_i32 s22, s57, s31
	s_add_u32 s20, s20, 0x80
	s_addc_u32 s21, s21, 0
	s_mov_b32 m0, s22
	ds_read_b128 v[182:185], v153 offset:49152
	ds_read_b128 v[186:189], v153 offset:50176
	ds_read_b128 v[190:193], v153 offset:51200
	ds_read_b128 v[194:197], v153 offset:52224
	ds_read_b128 v[198:201], v153 offset:53248
	ds_read_b128 v[202:205], v153 offset:54272
	ds_read_b128 v[206:209], v153 offset:55296
	ds_read_b128 v[210:213], v153 offset:56320
	global_load_lds_dwordx4 v132, s[20:21]
	s_add_i32 m0, s22, 0x2000
	s_add_i32 s22, s60, s31
	global_load_lds_dwordx4 v128, s[20:21]
	s_add_u32 s20, s20, 0x80000
	s_addc_u32 s21, s21, 0
	s_mov_b32 m0, s22
	s_nop 0
	global_load_lds_dwordx4 v132, s[20:21]
	s_add_i32 m0, s22, 0x2000
	s_nop 0
	global_load_lds_dwordx4 v128, s[20:21]
	s_mov_b32 m0, s46
	s_nop 0
	global_load_lds_dwordx4 v134, s[100:101]
	s_mov_b32 m0, s47
	s_nop 0
	global_load_lds_dwordx4 v130, s[100:101]
	s_waitcnt vmcnt(8)
	s_waitcnt lgkmcnt(0)
	s_barrier
	s_setprio 1
	s_waitcnt lgkmcnt(0)
	v_mfma_f32_16x16x32_bf16 v[60:63], v[144:147], v[182:185], v[60:63]
	v_mfma_f32_16x16x32_bf16 v[56:59], v[158:161], v[182:185], v[56:59]
	v_mfma_f32_16x16x32_bf16 v[52:55], v[144:147], v[190:193], v[52:55]
	v_mfma_f32_16x16x32_bf16 v[44:47], v[158:161], v[190:193], v[44:47]
	v_mfma_f32_16x16x32_bf16 v[36:39], v[144:147], v[198:201], v[36:39]
	v_mfma_f32_16x16x32_bf16 v[28:31], v[158:161], v[198:201], v[28:31]
	v_mfma_f32_16x16x32_bf16 v[20:23], v[144:147], v[206:209], v[20:23]
	v_mfma_f32_16x16x32_bf16 v[12:15], v[158:161], v[206:209], v[12:15]
	v_mfma_f32_16x16x32_bf16 v[60:63], v[154:157], v[186:189], v[60:63]
	v_mfma_f32_16x16x32_bf16 v[56:59], v[162:165], v[186:189], v[56:59]
	v_mfma_f32_16x16x32_bf16 v[52:55], v[154:157], v[194:197], v[52:55]
	v_mfma_f32_16x16x32_bf16 v[44:47], v[162:165], v[194:197], v[44:47]
	v_mfma_f32_16x16x32_bf16 v[36:39], v[154:157], v[202:205], v[36:39]
	v_mfma_f32_16x16x32_bf16 v[28:31], v[162:165], v[202:205], v[28:31]
	v_mfma_f32_16x16x32_bf16 v[20:23], v[154:157], v[210:213], v[20:23]
	v_mfma_f32_16x16x32_bf16 v[12:15], v[162:165], v[210:213], v[12:15]
	v_mfma_f32_16x16x32_bf16 v[48:51], v[166:169], v[182:185], v[48:51]
	v_mfma_f32_16x16x32_bf16 v[40:43], v[174:177], v[182:185], v[40:43]
	v_mfma_f32_16x16x32_bf16 v[32:35], v[166:169], v[190:193], v[32:35]
	v_mfma_f32_16x16x32_bf16 v[24:27], v[174:177], v[190:193], v[24:27]
	v_mfma_f32_16x16x32_bf16 v[16:19], v[166:169], v[198:201], v[16:19]
	v_mfma_f32_16x16x32_bf16 v[8:11], v[174:177], v[198:201], v[8:11]
	v_mfma_f32_16x16x32_bf16 v[4:7], v[166:169], v[206:209], v[4:7]
	v_mfma_f32_16x16x32_bf16 v[0:3], v[174:177], v[206:209], v[0:3]
	v_mfma_f32_16x16x32_bf16 v[48:51], v[170:173], v[186:189], v[48:51]
	v_mfma_f32_16x16x32_bf16 v[40:43], v[178:181], v[186:189], v[40:43]
	v_mfma_f32_16x16x32_bf16 v[32:35], v[170:173], v[194:197], v[32:35]
	v_mfma_f32_16x16x32_bf16 v[24:27], v[178:181], v[194:197], v[24:27]
	v_mfma_f32_16x16x32_bf16 v[16:19], v[170:173], v[202:205], v[16:19]
	v_mfma_f32_16x16x32_bf16 v[8:11], v[178:181], v[202:205], v[8:11]
	v_mfma_f32_16x16x32_bf16 v[4:7], v[170:173], v[210:213], v[4:7]
	v_mfma_f32_16x16x32_bf16 v[0:3], v[178:181], v[210:213], v[0:3]
	s_setprio 0
	s_barrier
	s_add_i32 s56, s56, 2
	s_add_u32 s54, s54, 0x100
	s_addc_u32 s55, s55, 0
	s_add_u32 s18, s18, 0x100
	s_addc_u32 s19, s19, 0
	s_cmp_gt_u32 s56, 29
	s_cbranch_scc0 .LBB0_375
	s_and_b64 vcc, exec, s[6:7]
	s_cbranch_vccz .LBB0_378
	s_barrier

; #define PG8_STAGE(bufoff, gbase, voff) do { _Pragma("unroll") for (int _i = 0; _i < 2; ++_i) \
;         __builtin_amdgcn_global_load_lds((const unsigned*)((const char*)(gbase) + (voff)[_i]), (LAS unsigned*)(lds + (bufoff) + ldsw + _i * 8192), 16, 0, 0); } while (0)
; #define PG8_LDA(dst, b, h) do { _Pragma("unroll") for (int m = 0; m < 4; ++m) _Pragma("unroll") for (int k = 0; k < 2; ++k) dst[m][k] = *(const LAS bf16x8*)(lds + PG8_SA(b, h) + aoff + m * 2048 + k * 1024); } while (0)
; #define PG8_LDB(dst, b, h) do { _Pragma("unroll") for (int n = 0; n < 2; ++n) _Pragma("unroll") for (int k = 0; k < 2; ++k) dst[n][k] = *(const LAS bf16x8*)(lds + PG8_SB(b, h) + boff + n * 2048 + k * 1024); } while (0)
; #define PG8_MMA(ai, bj, At, Bt) do { __builtin_amdgcn_s_setprio(1); _Pragma("unroll") for (int m = 0; m < 4; ++m) _Pragma("unroll") for (int n = 0; n < 2; ++n) _Pragma("unroll") for (int k = 0; k < 2; ++k) \
;         acc[ai][bj][m][n] = __builtin_amdgcn_mfma_f32_16x16x32_bf16(Bt[n][k], At[m][k], acc[ai][bj][m][n], 0, 0, 0); __builtin_amdgcn_s_setprio(0); } while (0)
; #define PG8_WAIT_V(n) asm volatile("s_waitcnt vmcnt(" #n ")" ::: "memory")
; #define PG8_WAIT_L(n) asm volatile("s_waitcnt lgkmcnt(" #n ")" ::: "memory")
; #define PG8_BAR __builtin_amdgcn_s_barrier()
; #define PG8_SCHED __builtin_amdgcn_sched_barrier(0)
; template <class Epi>
; __device__ __forceinline__ void gemm_phase(ldsp lds, const Gemm g, const StaticOrder& S, const Epi& E, int wave0) {
;     ...
;             const bool last = (t == nt - 2);
;             const char* a1 = cA + (size_t)(t + 1) * kstep;
;             const char* a2 = last ? nA : cA + (size_t)(t + 2) * kstep; const char* b2 = last ? nB : cB + (size_t)(t + 2) * kstep;
;             const char* a3 = a2 + kstep; const char* b3 = b2 + kstep;
;             PG8_LDB(B0, 0, 0); PG8_LDB(B1, 0, 1); PG8_SCHED; PG8_LDA(At, 0, 0); PG8_STAGE(PG8_SA(1, 1), a1 + hstep, voffA);
;             PG8_WAIT_V(8); PG8_WAIT_L(0); PG8_BAR; PG8_MMA(0, 0, At, B0); PG8_MMA(0, 1, At, B1); PG8_BAR; PG8_SCHED;
;             PG8_LDA(At, 0, 1); PG8_STAGE(PG8_SB(0, 0), b2, voffB); PG8_STAGE(PG8_SB(0, 1), b2 + hstep, voffB); PG8_STAGE(PG8_SA(0, 0), a2, voffA);
;             PG8_WAIT_V(8); PG8_WAIT_L(0); PG8_BAR; PG8_MMA(1, 0, At, B0); PG8_MMA(1, 1, At, B1); PG8_BAR; PG8_SCHED;
.LBB0_621:
	ds_read_b128 v[152:155], v149
	ds_read_b128 v[156:159], v149 offset:1024
	ds_read_b128 v[160:163], v149 offset:2048
	ds_read_b128 v[164:167], v149 offset:3072
	ds_read_b128 v[168:171], v150
	ds_read_b128 v[172:175], v150 offset:1024
	ds_read_b128 v[176:179], v150 offset:2048
	ds_read_b128 v[180:183], v150 offset:3072
	s_add_u32 s36, s34, 0xfff80080
	s_addc_u32 s37, s35, -1
	s_cmp_eq_u32 s76, 28
	s_cselect_b32 s39, s25, s37
	s_cselect_b32 s38, s72, s36
	s_cselect_b32 s37, s23, s75
	s_cselect_b32 s36, s73, s74
	s_add_i32 m0, s31, 0xc000
	ds_read_b128 v[184:187], v151
	ds_read_b128 v[188:191], v151 offset:1024
	ds_read_b128 v[192:195], v151 offset:2048
	ds_read_b128 v[196:199], v151 offset:3072
	ds_read_b128 v[200:203], v151 offset:4096
	ds_read_b128 v[204:207], v151 offset:5120
	ds_read_b128 v[208:211], v151 offset:6144
	ds_read_b128 v[212:215], v151 offset:7168
	global_load_lds_dwordx4 v138, s[34:35]
	s_add_i32 m0, s31, 0xe000
	s_nop 0
	global_load_lds_dwordx4 v136, s[34:35]
	s_waitcnt vmcnt(8)
	s_waitcnt lgkmcnt(0)
	s_barrier
	s_setprio 1
	s_waitcnt lgkmcnt(0)
	v_mfma_f32_16x16x32_bf16 v[124:127], v[152:155], v[184:187], v[124:127]
	v_mfma_f32_16x16x32_bf16 v[120:123], v[160:163], v[184:187], v[120:123]
	v_mfma_f32_16x16x32_bf16 v[108:111], v[152:155], v[192:195], v[108:111]
	v_mfma_f32_16x16x32_bf16 v[104:107], v[160:163], v[192:195], v[104:107]
	v_mfma_f32_16x16x32_bf16 v[92:95], v[152:155], v[200:203], v[92:95]
	v_mfma_f32_16x16x32_bf16 v[88:91], v[160:163], v[200:203], v[88:91]
	v_mfma_f32_16x16x32_bf16 v[76:79], v[152:155], v[208:211], v[76:79]
	v_mfma_f32_16x16x32_bf16 v[72:75], v[160:163], v[208:211], v[72:75]
	v_mfma_f32_16x16x32_bf16 v[124:127], v[156:159], v[188:191], v[124:127]
	v_mfma_f32_16x16x32_bf16 v[120:123], v[164:167], v[188:191], v[120:123]
	v_mfma_f32_16x16x32_bf16 v[108:111], v[156:159], v[196:199], v[108:111]
	v_mfma_f32_16x16x32_bf16 v[104:107], v[164:167], v[196:199], v[104:107]
	v_mfma_f32_16x16x32_bf16 v[92:95], v[156:159], v[204:207], v[92:95]
	v_mfma_f32_16x16x32_bf16 v[88:91], v[164:167], v[204:207], v[88:91]
	v_mfma_f32_16x16x32_bf16 v[76:79], v[156:159], v[212:215], v[76:79]
	v_mfma_f32_16x16x32_bf16 v[72:75], v[164:167], v[212:215], v[72:75]
	v_mfma_f32_16x16x32_bf16 v[116:119], v[168:171], v[184:187], v[116:119]
	v_mfma_f32_16x16x32_bf16 v[112:115], v[176:179], v[184:187], v[112:115]
	v_mfma_f32_16x16x32_bf16 v[100:103], v[168:171], v[192:195], v[100:103]
	v_mfma_f32_16x16x32_bf16 v[96:99], v[176:179], v[192:195], v[96:99]
	v_mfma_f32_16x16x32_bf16 v[84:87], v[168:171], v[200:203], v[84:87]
	v_mfma_f32_16x16x32_bf16 v[80:83], v[176:179], v[200:203], v[80:83]
	v_mfma_f32_16x16x32_bf16 v[68:71], v[168:171], v[208:211], v[68:71]
	v_mfma_f32_16x16x32_bf16 v[64:67], v[176:179], v[208:211], v[64:67]
	v_mfma_f32_16x16x32_bf16 v[116:119], v[172:175], v[188:191], v[116:119]
	v_mfma_f32_16x16x32_bf16 v[112:115], v[180:183], v[188:191], v[112:115]
	v_mfma_f32_16x16x32_bf16 v[100:103], v[172:175], v[196:199], v[100:103]
	v_mfma_f32_16x16x32_bf16 v[96:99], v[180:183], v[196:199], v[96:99]
	v_mfma_f32_16x16x32_bf16 v[84:87], v[172:175], v[204:207], v[84:87]
	v_mfma_f32_16x16x32_bf16 v[80:83], v[180:183], v[204:207], v[80:83]
	v_mfma_f32_16x16x32_bf16 v[68:71], v[172:175], v[212:215], v[68:71]
	v_mfma_f32_16x16x32_bf16 v[64:67], v[180:183], v[212:215], v[64:67]
	s_setprio 0
	s_barrier
	s_add_i32 s77, s62, s49
	s_add_u32 s100, s38, 0x80
	s_addc_u32 s101, s39, 0
	s_mov_b32 m0, s77
	ds_read_b128 v[184:187], v151 offset:16384
	ds_read_b128 v[188:191], v151 offset:17408
	ds_read_b128 v[192:195], v151 offset:18432
	ds_read_b128 v[196:199], v151 offset:19456
	ds_read_b128 v[200:203], v151 offset:20480
	ds_read_b128 v[204:207], v151 offset:21504
	ds_read_b128 v[208:211], v151 offset:22528
	ds_read_b128 v[212:215], v151 offset:23552
	global_load_lds_dwordx4 v130, s[36:37]
	s_add_i32 m0, s77, 0x2000
	s_add_u32 s78, s36, 0x80000
	s_addc_u32 s79, s37, 0
	s_add_i32 s77, s63, s49
	global_load_lds_dwordx4 v134, s[36:37]
	s_mov_b32 m0, s77
	s_nop 0
	global_load_lds_dwordx4 v130, s[78:79]
	s_add_i32 m0, s77, 0x2000
	s_nop 0
	global_load_lds_dwordx4 v134, s[78:79]
	s_mov_b32 m0, s31
	s_nop 0
	global_load_lds_dwordx4 v128, s[38:39]
	s_mov_b32 m0, s50
	s_nop 0
	global_load_lds_dwordx4 v132, s[38:39]
	s_waitcnt vmcnt(8)
	s_waitcnt lgkmcnt(0)
	s_barrier
	s_setprio 1
	s_waitcnt lgkmcnt(0)
	v_mfma_f32_16x16x32_bf16 v[60:63], v[152:155], v[184:187], v[60:63]
	v_mfma_f32_16x16x32_bf16 v[56:59], v[160:163], v[184:187], v[56:59]
	v_mfma_f32_16x16x32_bf16 v[44:47], v[152:155], v[192:195], v[44:47]
	v_mfma_f32_16x16x32_bf16 v[40:43], v[160:163], v[192:195], v[40:43]
	v_mfma_f32_16x16x32_bf16 v[28:31], v[152:155], v[200:203], v[28:31]
	v_mfma_f32_16x16x32_bf16 v[24:27], v[160:163], v[200:203], v[24:27]
	v_mfma_f32_16x16x32_bf16 v[12:15], v[152:155], v[208:211], v[12:15]
	v_mfma_f32_16x16x32_bf16 v[8:11], v[160:163], v[208:211], v[8:11]
	v_mfma_f32_16x16x32_bf16 v[60:63], v[156:159], v[188:191], v[60:63]
	v_mfma_f32_16x16x32_bf16 v[56:59], v[164:167], v[188:191], v[56:59]
	v_mfma_f32_16x16x32_bf16 v[44:47], v[156:159], v[196:199], v[44:47]
	v_mfma_f32_16x16x32_bf16 v[40:43], v[164:167], v[196:199], v[40:43]
	v_mfma_f32_16x16x32_bf16 v[28:31], v[156:159], v[204:207], v[28:31]
	v_mfma_f32_16x16x32_bf16 v[24:27], v[164:167], v[204:207], v[24:27]
	v_mfma_f32_16x16x32_bf16 v[12:15], v[156:159], v[212:215], v[12:15]
	v_mfma_f32_16x16x32_bf16 v[8:11], v[164:167], v[212:215], v[8:11]
	v_mfma_f32_16x16x32_bf16 v[52:55], v[168:171], v[184:187], v[52:55]
	v_mfma_f32_16x16x32_bf16 v[48:51], v[176:179], v[184:187], v[48:51]
	v_mfma_f32_16x16x32_bf16 v[36:39], v[168:171], v[192:195], v[36:39]
	v_mfma_f32_16x16x32_bf16 v[32:35], v[176:179], v[192:195], v[32:35]
	v_mfma_f32_16x16x32_bf16 v[20:23], v[168:171], v[200:203], v[20:23]
	v_mfma_f32_16x16x32_bf16 v[16:19], v[176:179], v[200:203], v[16:19]
	v_mfma_f32_16x16x32_bf16 v[4:7], v[168:171], v[208:211], v[4:7]
	v_mfma_f32_16x16x32_bf16 v[0:3], v[176:179], v[208:211], v[0:3]
	v_mfma_f32_16x16x32_bf16 v[52:55], v[172:175], v[188:191], v[52:55]
	v_mfma_f32_16x16x32_bf16 v[48:51], v[180:183], v[188:191], v[48:51]
	v_mfma_f32_16x16x32_bf16 v[36:39], v[172:175], v[196:199], v[36:39]
	v_mfma_f32_16x16x32_bf16 v[32:35], v[180:183], v[196:199], v[32:35]
	v_mfma_f32_16x16x32_bf16 v[20:23], v[172:175], v[204:207], v[20:23]
	v_mfma_f32_16x16x32_bf16 v[16:19], v[180:183], v[204:207], v[16:19]
	v_mfma_f32_16x16x32_bf16 v[4:7], v[172:175], v[212:215], v[4:7]
	v_mfma_f32_16x16x32_bf16 v[0:3], v[180:183], v[212:215], v[0:3]
	s_setprio 0
	s_barrier
; #define PG8_STAGE(bufoff, gbase, voff) do { _Pragma("unroll") for (int _i = 0; _i < 2; ++_i) \
;         __builtin_amdgcn_global_load_lds((const unsigned*)((const char*)(gbase) + (voff)[_i]), (LAS unsigned*)(lds + (bufoff) + ldsw + _i * 8192), 16, 0, 0); } while (0)
; #define PG8_LDA(dst, b, h) do { _Pragma("unroll") for (int m = 0; m < 4; ++m) _Pragma("unroll") for (int k = 0; k < 2; ++k) dst[m][k] = *(const LAS bf16x8*)(lds + PG8_SA(b, h) + aoff + m * 2048 + k * 1024); } while (0)
; #define PG8_LDB(dst, b, h) do { _Pragma("unroll") for (int n = 0; n < 2; ++n) _Pragma("unroll") for (int k = 0; k < 2; ++k) dst[n][k] = *(const LAS bf16x8*)(lds + PG8_SB(b, h) + boff + n * 2048 + k * 1024); } while (0)
; #define PG8_MMA(ai, bj, At, Bt) do { __builtin_amdgcn_s_setprio(1); _Pragma("unroll") for (int m = 0; m < 4; ++m) _Pragma("unroll") for (int n = 0; n < 2; ++n) _Pragma("unroll") for (int k = 0; k < 2; ++k) \
;         acc[ai][bj][m][n] = __builtin_amdgcn_mfma_f32_16x16x32_bf16(Bt[n][k], At[m][k], acc[ai][bj][m][n], 0, 0, 0); __builtin_amdgcn_s_setprio(0); } while (0)
; #define PG8_WAIT_V(n) asm volatile("s_waitcnt vmcnt(" #n ")" ::: "memory")
; #define PG8_WAIT_L(n) asm volatile("s_waitcnt lgkmcnt(" #n ")" ::: "memory")
; #define PG8_BAR __builtin_amdgcn_s_barrier()
; #define PG8_SCHED __builtin_amdgcn_sched_barrier(0)
; template <class Epi>
; __device__ __forceinline__ void gemm_phase(ldsp lds, const Gemm g, const StaticOrder& S, const Epi& E, int wave0) {
;     ...
;             PG8_LDB(B0, 1, 0); PG8_LDB(B1, 1, 1); PG8_SCHED; PG8_LDA(At, 1, 0); PG8_STAGE(PG8_SA(0, 1), a2 + hstep, voffA);
;             PG8_WAIT_V(8); PG8_WAIT_L(0); PG8_BAR; PG8_MMA(0, 0, At, B0); PG8_MMA(0, 1, At, B1); PG8_BAR; PG8_SCHED;
;             PG8_LDA(At, 1, 1); PG8_STAGE(PG8_SB(1, 0), b3, voffB); PG8_STAGE(PG8_SB(1, 1), b3 + hstep, voffB); PG8_STAGE(PG8_SA(1, 0), a3, voffA);
;             PG8_WAIT_V(8); PG8_WAIT_L(0); PG8_BAR; PG8_MMA(1, 0, At, B0); PG8_MMA(1, 1, At, B1); PG8_BAR; PG8_SCHED;
;         }
;         if (wr == 0) PG8_BAR;
	s_add_i32 s77, 0, 0x18000
	s_add_i32 s78, 0, 0x1c000
	v_add_u32_e32 v164, s77, v148
	v_add_u32_e32 v180, s78, v148
	ds_read_b128 v[152:155], v164
	ds_read_b128 v[156:159], v164 offset:1024
	ds_read_b128 v[160:163], v164 offset:2048
	ds_read_b128 v[164:167], v164 offset:3072
	ds_read_b128 v[168:171], v180
	ds_read_b128 v[172:175], v180 offset:1024
	ds_read_b128 v[176:179], v180 offset:2048
	ds_read_b128 v[180:183], v180 offset:3072
	s_add_u32 s38, s38, 0x80000
	s_addc_u32 s39, s39, 0
	s_mov_b32 m0, s51
	ds_read_b128 v[184:187], v151 offset:32768
	ds_read_b128 v[188:191], v151 offset:33792
	ds_read_b128 v[192:195], v151 offset:34816
	ds_read_b128 v[196:199], v151 offset:35840
	ds_read_b128 v[200:203], v151 offset:36864
	ds_read_b128 v[204:207], v151 offset:37888
	ds_read_b128 v[208:211], v151 offset:38912
	ds_read_b128 v[212:215], v151 offset:39936
	global_load_lds_dwordx4 v128, s[38:39]
	s_mov_b32 m0, s52
	s_nop 0
	global_load_lds_dwordx4 v132, s[38:39]
	s_waitcnt vmcnt(8)
	s_waitcnt lgkmcnt(0)
	s_barrier
	s_setprio 1
	s_waitcnt lgkmcnt(0)
	v_mfma_f32_16x16x32_bf16 v[124:127], v[152:155], v[184:187], v[124:127]
	v_mfma_f32_16x16x32_bf16 v[120:123], v[160:163], v[184:187], v[120:123]
	v_mfma_f32_16x16x32_bf16 v[108:111], v[152:155], v[192:195], v[108:111]
	v_mfma_f32_16x16x32_bf16 v[104:107], v[160:163], v[192:195], v[104:107]
	v_mfma_f32_16x16x32_bf16 v[92:95], v[152:155], v[200:203], v[92:95]
	v_mfma_f32_16x16x32_bf16 v[88:91], v[160:163], v[200:203], v[88:91]
	v_mfma_f32_16x16x32_bf16 v[76:79], v[152:155], v[208:211], v[76:79]
	v_mfma_f32_16x16x32_bf16 v[72:75], v[160:163], v[208:211], v[72:75]
	v_mfma_f32_16x16x32_bf16 v[124:127], v[156:159], v[188:191], v[124:127]
	v_mfma_f32_16x16x32_bf16 v[120:123], v[164:167], v[188:191], v[120:123]
	v_mfma_f32_16x16x32_bf16 v[108:111], v[156:159], v[196:199], v[108:111]
	v_mfma_f32_16x16x32_bf16 v[104:107], v[164:167], v[196:199], v[104:107]
	v_mfma_f32_16x16x32_bf16 v[92:95], v[156:159], v[204:207], v[92:95]
	v_mfma_f32_16x16x32_bf16 v[88:91], v[164:167], v[204:207], v[88:91]
	v_mfma_f32_16x16x32_bf16 v[76:79], v[156:159], v[212:215], v[76:79]
	v_mfma_f32_16x16x32_bf16 v[72:75], v[164:167], v[212:215], v[72:75]
	v_mfma_f32_16x16x32_bf16 v[116:119], v[168:171], v[184:187], v[116:119]
	v_mfma_f32_16x16x32_bf16 v[112:115], v[176:179], v[184:187], v[112:115]
	v_mfma_f32_16x16x32_bf16 v[100:103], v[168:171], v[192:195], v[100:103]
	v_mfma_f32_16x16x32_bf16 v[96:99], v[176:179], v[192:195], v[96:99]
	v_mfma_f32_16x16x32_bf16 v[84:87], v[168:171], v[200:203], v[84:87]
	v_mfma_f32_16x16x32_bf16 v[80:83], v[176:179], v[200:203], v[80:83]
	v_mfma_f32_16x16x32_bf16 v[68:71], v[168:171], v[208:211], v[68:71]
	v_mfma_f32_16x16x32_bf16 v[64:67], v[176:179], v[208:211], v[64:67]
	v_mfma_f32_16x16x32_bf16 v[116:119], v[172:175], v[188:191], v[116:119]
	v_mfma_f32_16x16x32_bf16 v[112:115], v[180:183], v[188:191], v[112:115]
	v_mfma_f32_16x16x32_bf16 v[100:103], v[172:175], v[196:199], v[100:103]
	v_mfma_f32_16x16x32_bf16 v[96:99], v[180:183], v[196:199], v[96:99]
	v_mfma_f32_16x16x32_bf16 v[84:87], v[172:175], v[204:207], v[84:87]
	v_mfma_f32_16x16x32_bf16 v[80:83], v[180:183], v[204:207], v[80:83]
	v_mfma_f32_16x16x32_bf16 v[68:71], v[172:175], v[212:215], v[68:71]
	v_mfma_f32_16x16x32_bf16 v[64:67], v[180:183], v[212:215], v[64:67]
	s_setprio 0
	s_barrier
	s_add_i32 s38, s77, s49
	s_add_u32 s36, s36, 0x80
	s_addc_u32 s37, s37, 0
	s_mov_b32 m0, s38
	ds_read_b128 v[184:187], v151 offset:49152
	ds_read_b128 v[188:191], v151 offset:50176
	ds_read_b128 v[192:195], v151 offset:51200
	ds_read_b128 v[196:199], v151 offset:52224
	ds_read_b128 v[200:203], v151 offset:53248
	ds_read_b128 v[204:207], v151 offset:54272
	ds_read_b128 v[208:211], v151 offset:55296
	ds_read_b128 v[212:215], v151 offset:56320
	global_load_lds_dwordx4 v130, s[36:37]
	s_add_i32 m0, s38, 0x2000
	s_add_i32 s38, s78, s49
	global_load_lds_dwordx4 v134, s[36:37]
	s_add_u32 s36, s36, 0x80000
	s_addc_u32 s37, s37, 0
	s_mov_b32 m0, s38
	s_nop 0
	global_load_lds_dwordx4 v130, s[36:37]
	s_add_i32 m0, s38, 0x2000
	s_nop 0
	global_load_lds_dwordx4 v134, s[36:37]
	s_mov_b32 m0, s59
	s_nop 0
	global_load_lds_dwordx4 v128, s[100:101]
	s_mov_b32 m0, s60
	s_nop 0
	global_load_lds_dwordx4 v132, s[100:101]
	s_waitcnt vmcnt(8)
	s_waitcnt lgkmcnt(0)
	s_barrier
	s_setprio 1
	s_waitcnt lgkmcnt(0)
	v_mfma_f32_16x16x32_bf16 v[60:63], v[152:155], v[184:187], v[60:63]
	v_mfma_f32_16x16x32_bf16 v[56:59], v[160:163], v[184:187], v[56:59]
	v_mfma_f32_16x16x32_bf16 v[44:47], v[152:155], v[192:195], v[44:47]
	v_mfma_f32_16x16x32_bf16 v[40:43], v[160:163], v[192:195], v[40:43]
	v_mfma_f32_16x16x32_bf16 v[28:31], v[152:155], v[200:203], v[28:31]
	v_mfma_f32_16x16x32_bf16 v[24:27], v[160:163], v[200:203], v[24:27]
	v_mfma_f32_16x16x32_bf16 v[12:15], v[152:155], v[208:211], v[12:15]
	v_mfma_f32_16x16x32_bf16 v[8:11], v[160:163], v[208:211], v[8:11]
	v_mfma_f32_16x16x32_bf16 v[60:63], v[156:159], v[188:191], v[60:63]
	v_mfma_f32_16x16x32_bf16 v[56:59], v[164:167], v[188:191], v[56:59]
	v_mfma_f32_16x16x32_bf16 v[44:47], v[156:159], v[196:199], v[44:47]
	v_mfma_f32_16x16x32_bf16 v[40:43], v[164:167], v[196:199], v[40:43]
	v_mfma_f32_16x16x32_bf16 v[28:31], v[156:159], v[204:207], v[28:31]
	v_mfma_f32_16x16x32_bf16 v[24:27], v[164:167], v[204:207], v[24:27]
	v_mfma_f32_16x16x32_bf16 v[12:15], v[156:159], v[212:215], v[12:15]
	v_mfma_f32_16x16x32_bf16 v[8:11], v[164:167], v[212:215], v[8:11]
	v_mfma_f32_16x16x32_bf16 v[52:55], v[168:171], v[184:187], v[52:55]
	v_mfma_f32_16x16x32_bf16 v[48:51], v[176:179], v[184:187], v[48:51]
	v_mfma_f32_16x16x32_bf16 v[36:39], v[168:171], v[192:195], v[36:39]
	v_mfma_f32_16x16x32_bf16 v[32:35], v[176:179], v[192:195], v[32:35]
	v_mfma_f32_16x16x32_bf16 v[20:23], v[168:171], v[200:203], v[20:23]
	v_mfma_f32_16x16x32_bf16 v[16:19], v[176:179], v[200:203], v[16:19]
	v_mfma_f32_16x16x32_bf16 v[4:7], v[168:171], v[208:211], v[4:7]
	v_mfma_f32_16x16x32_bf16 v[0:3], v[176:179], v[208:211], v[0:3]
	v_mfma_f32_16x16x32_bf16 v[52:55], v[172:175], v[188:191], v[52:55]
	v_mfma_f32_16x16x32_bf16 v[48:51], v[180:183], v[188:191], v[48:51]
	v_mfma_f32_16x16x32_bf16 v[36:39], v[172:175], v[196:199], v[36:39]
	v_mfma_f32_16x16x32_bf16 v[32:35], v[180:183], v[196:199], v[32:35]
	v_mfma_f32_16x16x32_bf16 v[20:23], v[172:175], v[204:207], v[20:23]
	v_mfma_f32_16x16x32_bf16 v[16:19], v[180:183], v[204:207], v[16:19]
	v_mfma_f32_16x16x32_bf16 v[4:7], v[172:175], v[212:215], v[4:7]
	v_mfma_f32_16x16x32_bf16 v[0:3], v[180:183], v[212:215], v[0:3]
	s_setprio 0
	s_barrier
	s_add_i32 s76, s76, 2
	s_add_u32 s74, s74, 0x100
	s_addc_u32 s75, s75, 0
	s_add_u32 s34, s34, 0x100
	s_addc_u32 s35, s35, 0
	s_cmp_gt_u32 s76, 29
	s_cbranch_scc0 .LBB0_621
	s_and_b64 vcc, exec, s[8:9]
	s_cbranch_vccz .LBB0_624
	s_barrier

; #define PG8_STAGE(bufoff, gbase, voff) do { _Pragma("unroll") for (int _i = 0; _i < 2; ++_i) \
;         __builtin_amdgcn_global_load_lds((const unsigned*)((const char*)(gbase) + (voff)[_i]), (LAS unsigned*)(lds + (bufoff) + ldsw + _i * 8192), 16, 0, 0); } while (0)
; #define PG8_LDA(dst, b, h) do { _Pragma("unroll") for (int m = 0; m < 4; ++m) _Pragma("unroll") for (int k = 0; k < 2; ++k) dst[m][k] = *(const LAS bf16x8*)(lds + PG8_SA(b, h) + aoff + m * 2048 + k * 1024); } while (0)
; #define PG8_LDB(dst, b, h) do { _Pragma("unroll") for (int n = 0; n < 2; ++n) _Pragma("unroll") for (int k = 0; k < 2; ++k) dst[n][k] = *(const LAS bf16x8*)(lds + PG8_SB(b, h) + boff + n * 2048 + k * 1024); } while (0)
; #define PG8_MMA(ai, bj, At, Bt) do { __builtin_amdgcn_s_setprio(1); _Pragma("unroll") for (int m = 0; m < 4; ++m) _Pragma("unroll") for (int n = 0; n < 2; ++n) _Pragma("unroll") for (int k = 0; k < 2; ++k) \
;         acc[ai][bj][m][n] = __builtin_amdgcn_mfma_f32_16x16x32_bf16(Bt[n][k], At[m][k], acc[ai][bj][m][n], 0, 0, 0); __builtin_amdgcn_s_setprio(0); } while (0)
; #define PG8_WAIT_V(n) asm volatile("s_waitcnt vmcnt(" #n ")" ::: "memory")
; #define PG8_WAIT_L(n) asm volatile("s_waitcnt lgkmcnt(" #n ")" ::: "memory")
; #define PG8_BAR __builtin_amdgcn_s_barrier()
; #define PG8_SCHED __builtin_amdgcn_sched_barrier(0)
; template <class Epi>
; __device__ __forceinline__ void gemm_phase(ldsp lds, const Gemm g, const StaticOrder& S, const Epi& E, int wave0) {
;     ...
;             const bool last = (t == nt - 2);
;             const char* a1 = cA + (size_t)(t + 1) * kstep;
;             const char* a2 = last ? nA : cA + (size_t)(t + 2) * kstep; const char* b2 = last ? nB : cB + (size_t)(t + 2) * kstep;
;             const char* a3 = a2 + kstep; const char* b3 = b2 + kstep;
;             PG8_LDB(B0, 0, 0); PG8_LDB(B1, 0, 1); PG8_SCHED; PG8_LDA(At, 0, 0); PG8_STAGE(PG8_SA(1, 1), a1 + hstep, voffA);
;             PG8_WAIT_V(8); PG8_WAIT_L(0); PG8_BAR; PG8_MMA(0, 0, At, B0); PG8_MMA(0, 1, At, B1); PG8_BAR; PG8_SCHED;
;             PG8_LDA(At, 0, 1); PG8_STAGE(PG8_SB(0, 0), b2, voffB); PG8_STAGE(PG8_SB(0, 1), b2 + hstep, voffB); PG8_STAGE(PG8_SA(0, 0), a2, voffA);
;             PG8_WAIT_V(8); PG8_WAIT_L(0); PG8_BAR; PG8_MMA(1, 0, At, B0); PG8_MMA(1, 1, At, B1); PG8_BAR; PG8_SCHED;
.LBB0_689:
	ds_read_b128 v[152:155], v149
	ds_read_b128 v[156:159], v149 offset:1024
	ds_read_b128 v[160:163], v149 offset:2048
	ds_read_b128 v[164:167], v149 offset:3072
	ds_read_b128 v[168:171], v150
	ds_read_b128 v[172:175], v150 offset:1024
	ds_read_b128 v[176:179], v150 offset:2048
	ds_read_b128 v[180:183], v150 offset:3072
	s_add_u32 s38, s36, 0xfff80080
	s_addc_u32 s39, s37, -1
	s_cmp_eq_u32 s73, 28
	s_cselect_b32 s41, s27, s39
	s_cselect_b32 s40, s69, s38
	s_cselect_b32 s39, s25, s72
	s_cselect_b32 s38, s70, s71
	s_add_i32 m0, s35, 0xc000
	ds_read_b128 v[184:187], v151
	ds_read_b128 v[188:191], v151 offset:1024
	ds_read_b128 v[192:195], v151 offset:2048
	ds_read_b128 v[196:199], v151 offset:3072
	ds_read_b128 v[200:203], v151 offset:4096
	ds_read_b128 v[204:207], v151 offset:5120
	ds_read_b128 v[208:211], v151 offset:6144
	ds_read_b128 v[212:215], v151 offset:7168
	global_load_lds_dwordx4 v138, s[36:37]
	s_add_i32 m0, s35, 0xe000
	s_nop 0
	global_load_lds_dwordx4 v136, s[36:37]
	s_waitcnt vmcnt(8)
	s_waitcnt lgkmcnt(0)
	s_barrier
	s_setprio 1
	s_waitcnt lgkmcnt(0)
	v_mfma_f32_16x16x32_bf16 v[124:127], v[152:155], v[184:187], v[124:127]
	v_mfma_f32_16x16x32_bf16 v[120:123], v[160:163], v[184:187], v[120:123]
	v_mfma_f32_16x16x32_bf16 v[112:115], v[152:155], v[192:195], v[112:115]
	v_mfma_f32_16x16x32_bf16 v[104:107], v[160:163], v[192:195], v[104:107]
	v_mfma_f32_16x16x32_bf16 v[96:99], v[152:155], v[200:203], v[96:99]
	v_mfma_f32_16x16x32_bf16 v[88:91], v[160:163], v[200:203], v[88:91]
	v_mfma_f32_16x16x32_bf16 v[80:83], v[152:155], v[208:211], v[80:83]
	v_mfma_f32_16x16x32_bf16 v[72:75], v[160:163], v[208:211], v[72:75]
	v_mfma_f32_16x16x32_bf16 v[124:127], v[156:159], v[188:191], v[124:127]
	v_mfma_f32_16x16x32_bf16 v[120:123], v[164:167], v[188:191], v[120:123]
	v_mfma_f32_16x16x32_bf16 v[112:115], v[156:159], v[196:199], v[112:115]
	v_mfma_f32_16x16x32_bf16 v[104:107], v[164:167], v[196:199], v[104:107]
	v_mfma_f32_16x16x32_bf16 v[96:99], v[156:159], v[204:207], v[96:99]
	v_mfma_f32_16x16x32_bf16 v[88:91], v[164:167], v[204:207], v[88:91]
	v_mfma_f32_16x16x32_bf16 v[80:83], v[156:159], v[212:215], v[80:83]
	v_mfma_f32_16x16x32_bf16 v[72:75], v[164:167], v[212:215], v[72:75]
	v_mfma_f32_16x16x32_bf16 v[116:119], v[168:171], v[184:187], v[116:119]
	v_mfma_f32_16x16x32_bf16 v[108:111], v[176:179], v[184:187], v[108:111]
	v_mfma_f32_16x16x32_bf16 v[100:103], v[168:171], v[192:195], v[100:103]
	v_mfma_f32_16x16x32_bf16 v[92:95], v[176:179], v[192:195], v[92:95]
	v_mfma_f32_16x16x32_bf16 v[84:87], v[168:171], v[200:203], v[84:87]
	v_mfma_f32_16x16x32_bf16 v[76:79], v[176:179], v[200:203], v[76:79]
	v_mfma_f32_16x16x32_bf16 v[68:71], v[168:171], v[208:211], v[68:71]
	v_mfma_f32_16x16x32_bf16 v[64:67], v[176:179], v[208:211], v[64:67]
	v_mfma_f32_16x16x32_bf16 v[116:119], v[172:175], v[188:191], v[116:119]
	v_mfma_f32_16x16x32_bf16 v[108:111], v[180:183], v[188:191], v[108:111]
	v_mfma_f32_16x16x32_bf16 v[100:103], v[172:175], v[196:199], v[100:103]
	v_mfma_f32_16x16x32_bf16 v[92:95], v[180:183], v[196:199], v[92:95]
	v_mfma_f32_16x16x32_bf16 v[84:87], v[172:175], v[204:207], v[84:87]
	v_mfma_f32_16x16x32_bf16 v[76:79], v[180:183], v[204:207], v[76:79]
	v_mfma_f32_16x16x32_bf16 v[68:71], v[172:175], v[212:215], v[68:71]
	v_mfma_f32_16x16x32_bf16 v[64:67], v[180:183], v[212:215], v[64:67]
	s_setprio 0
	s_barrier
	s_add_i32 s74, s60, s49
	s_add_u32 s100, s40, 0x80
	s_addc_u32 s101, s41, 0
	s_mov_b32 m0, s74
	ds_read_b128 v[184:187], v151 offset:16384
	ds_read_b128 v[188:191], v151 offset:17408
	ds_read_b128 v[192:195], v151 offset:18432
	ds_read_b128 v[196:199], v151 offset:19456
	ds_read_b128 v[200:203], v151 offset:20480
	ds_read_b128 v[204:207], v151 offset:21504
	ds_read_b128 v[208:211], v151 offset:22528
	ds_read_b128 v[212:215], v151 offset:23552
	global_load_lds_dwordx4 v130, s[38:39]
	s_add_i32 m0, s74, 0x2000
	s_add_u32 s74, s38, 0x80000
	s_addc_u32 s75, s39, 0
	s_add_i32 s76, s61, s49
	global_load_lds_dwordx4 v134, s[38:39]
	s_mov_b32 m0, s76
	s_nop 0
	global_load_lds_dwordx4 v130, s[74:75]
	s_add_i32 m0, s76, 0x2000
	s_nop 0
	global_load_lds_dwordx4 v134, s[74:75]
	s_mov_b32 m0, s35
	s_nop 0
	global_load_lds_dwordx4 v128, s[40:41]
	s_mov_b32 m0, s50
	s_nop 0
	global_load_lds_dwordx4 v132, s[40:41]
	s_waitcnt vmcnt(8)
	s_waitcnt lgkmcnt(0)
	s_barrier
	s_setprio 1
	s_waitcnt lgkmcnt(0)
	v_mfma_f32_16x16x32_bf16 v[60:63], v[152:155], v[184:187], v[60:63]
	v_mfma_f32_16x16x32_bf16 v[56:59], v[160:163], v[184:187], v[56:59]
	v_mfma_f32_16x16x32_bf16 v[48:51], v[152:155], v[192:195], v[48:51]
	v_mfma_f32_16x16x32_bf16 v[40:43], v[160:163], v[192:195], v[40:43]
	v_mfma_f32_16x16x32_bf16 v[32:35], v[152:155], v[200:203], v[32:35]
	v_mfma_f32_16x16x32_bf16 v[24:27], v[160:163], v[200:203], v[24:27]
	v_mfma_f32_16x16x32_bf16 v[16:19], v[152:155], v[208:211], v[16:19]
	v_mfma_f32_16x16x32_bf16 v[8:11], v[160:163], v[208:211], v[8:11]
	v_mfma_f32_16x16x32_bf16 v[60:63], v[156:159], v[188:191], v[60:63]
	v_mfma_f32_16x16x32_bf16 v[56:59], v[164:167], v[188:191], v[56:59]
	v_mfma_f32_16x16x32_bf16 v[48:51], v[156:159], v[196:199], v[48:51]
	v_mfma_f32_16x16x32_bf16 v[40:43], v[164:167], v[196:199], v[40:43]
	v_mfma_f32_16x16x32_bf16 v[32:35], v[156:159], v[204:207], v[32:35]
	v_mfma_f32_16x16x32_bf16 v[24:27], v[164:167], v[204:207], v[24:27]
	v_mfma_f32_16x16x32_bf16 v[16:19], v[156:159], v[212:215], v[16:19]
	v_mfma_f32_16x16x32_bf16 v[8:11], v[164:167], v[212:215], v[8:11]
	v_mfma_f32_16x16x32_bf16 v[52:55], v[168:171], v[184:187], v[52:55]
	v_mfma_f32_16x16x32_bf16 v[44:47], v[176:179], v[184:187], v[44:47]
	v_mfma_f32_16x16x32_bf16 v[36:39], v[168:171], v[192:195], v[36:39]
	v_mfma_f32_16x16x32_bf16 v[28:31], v[176:179], v[192:195], v[28:31]
	v_mfma_f32_16x16x32_bf16 v[20:23], v[168:171], v[200:203], v[20:23]
	v_mfma_f32_16x16x32_bf16 v[12:15], v[176:179], v[200:203], v[12:15]
	v_mfma_f32_16x16x32_bf16 v[4:7], v[168:171], v[208:211], v[4:7]
	v_mfma_f32_16x16x32_bf16 v[0:3], v[176:179], v[208:211], v[0:3]
	v_mfma_f32_16x16x32_bf16 v[52:55], v[172:175], v[188:191], v[52:55]
	v_mfma_f32_16x16x32_bf16 v[44:47], v[180:183], v[188:191], v[44:47]
	v_mfma_f32_16x16x32_bf16 v[36:39], v[172:175], v[196:199], v[36:39]
	v_mfma_f32_16x16x32_bf16 v[28:31], v[180:183], v[196:199], v[28:31]
	v_mfma_f32_16x16x32_bf16 v[20:23], v[172:175], v[204:207], v[20:23]
	v_mfma_f32_16x16x32_bf16 v[12:15], v[180:183], v[204:207], v[12:15]
	v_mfma_f32_16x16x32_bf16 v[4:7], v[172:175], v[212:215], v[4:7]
	v_mfma_f32_16x16x32_bf16 v[0:3], v[180:183], v[212:215], v[0:3]
	s_setprio 0
	s_barrier
; #define PG8_STAGE(bufoff, gbase, voff) do { _Pragma("unroll") for (int _i = 0; _i < 2; ++_i) \
;         __builtin_amdgcn_global_load_lds((const unsigned*)((const char*)(gbase) + (voff)[_i]), (LAS unsigned*)(lds + (bufoff) + ldsw + _i * 8192), 16, 0, 0); } while (0)
; #define PG8_LDA(dst, b, h) do { _Pragma("unroll") for (int m = 0; m < 4; ++m) _Pragma("unroll") for (int k = 0; k < 2; ++k) dst[m][k] = *(const LAS bf16x8*)(lds + PG8_SA(b, h) + aoff + m * 2048 + k * 1024); } while (0)
; #define PG8_LDB(dst, b, h) do { _Pragma("unroll") for (int n = 0; n < 2; ++n) _Pragma("unroll") for (int k = 0; k < 2; ++k) dst[n][k] = *(const LAS bf16x8*)(lds + PG8_SB(b, h) + boff + n * 2048 + k * 1024); } while (0)
; #define PG8_MMA(ai, bj, At, Bt) do { __builtin_amdgcn_s_setprio(1); _Pragma("unroll") for (int m = 0; m < 4; ++m) _Pragma("unroll") for (int n = 0; n < 2; ++n) _Pragma("unroll") for (int k = 0; k < 2; ++k) \
;         acc[ai][bj][m][n] = __builtin_amdgcn_mfma_f32_16x16x32_bf16(Bt[n][k], At[m][k], acc[ai][bj][m][n], 0, 0, 0); __builtin_amdgcn_s_setprio(0); } while (0)
; #define PG8_WAIT_V(n) asm volatile("s_waitcnt vmcnt(" #n ")" ::: "memory")
; #define PG8_WAIT_L(n) asm volatile("s_waitcnt lgkmcnt(" #n ")" ::: "memory")
; #define PG8_BAR __builtin_amdgcn_s_barrier()
; #define PG8_SCHED __builtin_amdgcn_sched_barrier(0)
; template <class Epi>
; __device__ __forceinline__ void gemm_phase(ldsp lds, const Gemm g, const StaticOrder& S, const Epi& E, int wave0) {
;     ...
;             PG8_LDB(B0, 1, 0); PG8_LDB(B1, 1, 1); PG8_SCHED; PG8_LDA(At, 1, 0); PG8_STAGE(PG8_SA(0, 1), a2 + hstep, voffA);
;             PG8_WAIT_V(8); PG8_WAIT_L(0); PG8_BAR; PG8_MMA(0, 0, At, B0); PG8_MMA(0, 1, At, B1); PG8_BAR; PG8_SCHED;
;             PG8_LDA(At, 1, 1); PG8_STAGE(PG8_SB(1, 0), b3, voffB); PG8_STAGE(PG8_SB(1, 1), b3 + hstep, voffB); PG8_STAGE(PG8_SA(1, 0), a3, voffA);
;             PG8_WAIT_V(8); PG8_WAIT_L(0); PG8_BAR; PG8_MMA(1, 0, At, B0); PG8_MMA(1, 1, At, B1); PG8_BAR; PG8_SCHED;
;         }
;         if (wr == 0) PG8_BAR;
	s_add_i32 s74, 0, 0x18000
	s_add_i32 s75, 0, 0x1c000
	v_add_u32_e32 v164, s74, v148
	v_add_u32_e32 v180, s75, v148
	ds_read_b128 v[152:155], v164
	ds_read_b128 v[156:159], v164 offset:1024
	ds_read_b128 v[160:163], v164 offset:2048
	ds_read_b128 v[164:167], v164 offset:3072
	ds_read_b128 v[168:171], v180
	ds_read_b128 v[172:175], v180 offset:1024
	ds_read_b128 v[176:179], v180 offset:2048
	ds_read_b128 v[180:183], v180 offset:3072
	s_add_u32 s40, s40, 0x80000
	s_addc_u32 s41, s41, 0
	s_mov_b32 m0, s51
	ds_read_b128 v[184:187], v151 offset:32768
	ds_read_b128 v[188:191], v151 offset:33792
	ds_read_b128 v[192:195], v151 offset:34816
	ds_read_b128 v[196:199], v151 offset:35840
	ds_read_b128 v[200:203], v151 offset:36864
	ds_read_b128 v[204:207], v151 offset:37888
	ds_read_b128 v[208:211], v151 offset:38912
	ds_read_b128 v[212:215], v151 offset:39936
	global_load_lds_dwordx4 v128, s[40:41]
	s_mov_b32 m0, s52
	s_nop 0
	global_load_lds_dwordx4 v132, s[40:41]
	s_waitcnt vmcnt(8)
	s_waitcnt lgkmcnt(0)
	s_barrier
	s_setprio 1
	s_waitcnt lgkmcnt(0)
	v_mfma_f32_16x16x32_bf16 v[124:127], v[152:155], v[184:187], v[124:127]
	v_mfma_f32_16x16x32_bf16 v[120:123], v[160:163], v[184:187], v[120:123]
	v_mfma_f32_16x16x32_bf16 v[112:115], v[152:155], v[192:195], v[112:115]
	v_mfma_f32_16x16x32_bf16 v[104:107], v[160:163], v[192:195], v[104:107]
	v_mfma_f32_16x16x32_bf16 v[96:99], v[152:155], v[200:203], v[96:99]
	v_mfma_f32_16x16x32_bf16 v[88:91], v[160:163], v[200:203], v[88:91]
	v_mfma_f32_16x16x32_bf16 v[80:83], v[152:155], v[208:211], v[80:83]
	v_mfma_f32_16x16x32_bf16 v[72:75], v[160:163], v[208:211], v[72:75]
	v_mfma_f32_16x16x32_bf16 v[124:127], v[156:159], v[188:191], v[124:127]
	v_mfma_f32_16x16x32_bf16 v[120:123], v[164:167], v[188:191], v[120:123]
	v_mfma_f32_16x16x32_bf16 v[112:115], v[156:159], v[196:199], v[112:115]
	v_mfma_f32_16x16x32_bf16 v[104:107], v[164:167], v[196:199], v[104:107]
	v_mfma_f32_16x16x32_bf16 v[96:99], v[156:159], v[204:207], v[96:99]
	v_mfma_f32_16x16x32_bf16 v[88:91], v[164:167], v[204:207], v[88:91]
	v_mfma_f32_16x16x32_bf16 v[80:83], v[156:159], v[212:215], v[80:83]
	v_mfma_f32_16x16x32_bf16 v[72:75], v[164:167], v[212:215], v[72:75]
	v_mfma_f32_16x16x32_bf16 v[116:119], v[168:171], v[184:187], v[116:119]
	v_mfma_f32_16x16x32_bf16 v[108:111], v[176:179], v[184:187], v[108:111]
	v_mfma_f32_16x16x32_bf16 v[100:103], v[168:171], v[192:195], v[100:103]
	v_mfma_f32_16x16x32_bf16 v[92:95], v[176:179], v[192:195], v[92:95]
	v_mfma_f32_16x16x32_bf16 v[84:87], v[168:171], v[200:203], v[84:87]
	v_mfma_f32_16x16x32_bf16 v[76:79], v[176:179], v[200:203], v[76:79]
	v_mfma_f32_16x16x32_bf16 v[68:71], v[168:171], v[208:211], v[68:71]
	v_mfma_f32_16x16x32_bf16 v[64:67], v[176:179], v[208:211], v[64:67]
	v_mfma_f32_16x16x32_bf16 v[116:119], v[172:175], v[188:191], v[116:119]
	v_mfma_f32_16x16x32_bf16 v[108:111], v[180:183], v[188:191], v[108:111]
	v_mfma_f32_16x16x32_bf16 v[100:103], v[172:175], v[196:199], v[100:103]
	v_mfma_f32_16x16x32_bf16 v[92:95], v[180:183], v[196:199], v[92:95]
	v_mfma_f32_16x16x32_bf16 v[84:87], v[172:175], v[204:207], v[84:87]
	v_mfma_f32_16x16x32_bf16 v[76:79], v[180:183], v[204:207], v[76:79]
	v_mfma_f32_16x16x32_bf16 v[68:71], v[172:175], v[212:215], v[68:71]
	v_mfma_f32_16x16x32_bf16 v[64:67], v[180:183], v[212:215], v[64:67]
	s_setprio 0
	s_barrier
	s_add_i32 s40, s74, s49
	s_add_u32 s38, s38, 0x80
	s_addc_u32 s39, s39, 0
	s_mov_b32 m0, s40
	ds_read_b128 v[184:187], v151 offset:49152
	ds_read_b128 v[188:191], v151 offset:50176
	ds_read_b128 v[192:195], v151 offset:51200
	ds_read_b128 v[196:199], v151 offset:52224
	ds_read_b128 v[200:203], v151 offset:53248
	ds_read_b128 v[204:207], v151 offset:54272
	ds_read_b128 v[208:211], v151 offset:55296
	ds_read_b128 v[212:215], v151 offset:56320
	global_load_lds_dwordx4 v130, s[38:39]
	s_add_i32 m0, s40, 0x2000
	s_add_i32 s40, s75, s49
	global_load_lds_dwordx4 v134, s[38:39]
	s_add_u32 s38, s38, 0x80000
	s_addc_u32 s39, s39, 0
	s_mov_b32 m0, s40
	s_nop 0
	global_load_lds_dwordx4 v130, s[38:39]
	s_add_i32 m0, s40, 0x2000
	s_nop 0
	global_load_lds_dwordx4 v134, s[38:39]
	s_mov_b32 m0, s57
	s_nop 0
	global_load_lds_dwordx4 v128, s[100:101]
	s_mov_b32 m0, s58
	s_nop 0
	global_load_lds_dwordx4 v132, s[100:101]
	s_waitcnt vmcnt(8)
	s_waitcnt lgkmcnt(0)
	s_barrier
	s_setprio 1
	s_waitcnt lgkmcnt(0)
	v_mfma_f32_16x16x32_bf16 v[60:63], v[152:155], v[184:187], v[60:63]
	v_mfma_f32_16x16x32_bf16 v[56:59], v[160:163], v[184:187], v[56:59]
	v_mfma_f32_16x16x32_bf16 v[48:51], v[152:155], v[192:195], v[48:51]
	v_mfma_f32_16x16x32_bf16 v[40:43], v[160:163], v[192:195], v[40:43]
	v_mfma_f32_16x16x32_bf16 v[32:35], v[152:155], v[200:203], v[32:35]
	v_mfma_f32_16x16x32_bf16 v[24:27], v[160:163], v[200:203], v[24:27]
	v_mfma_f32_16x16x32_bf16 v[16:19], v[152:155], v[208:211], v[16:19]
	v_mfma_f32_16x16x32_bf16 v[8:11], v[160:163], v[208:211], v[8:11]
	v_mfma_f32_16x16x32_bf16 v[60:63], v[156:159], v[188:191], v[60:63]
	v_mfma_f32_16x16x32_bf16 v[56:59], v[164:167], v[188:191], v[56:59]
	v_mfma_f32_16x16x32_bf16 v[48:51], v[156:159], v[196:199], v[48:51]
	v_mfma_f32_16x16x32_bf16 v[40:43], v[164:167], v[196:199], v[40:43]
	v_mfma_f32_16x16x32_bf16 v[32:35], v[156:159], v[204:207], v[32:35]
	v_mfma_f32_16x16x32_bf16 v[24:27], v[164:167], v[204:207], v[24:27]
	v_mfma_f32_16x16x32_bf16 v[16:19], v[156:159], v[212:215], v[16:19]
	v_mfma_f32_16x16x32_bf16 v[8:11], v[164:167], v[212:215], v[8:11]
	v_mfma_f32_16x16x32_bf16 v[52:55], v[168:171], v[184:187], v[52:55]
	v_mfma_f32_16x16x32_bf16 v[44:47], v[176:179], v[184:187], v[44:47]
	v_mfma_f32_16x16x32_bf16 v[36:39], v[168:171], v[192:195], v[36:39]
	v_mfma_f32_16x16x32_bf16 v[28:31], v[176:179], v[192:195], v[28:31]
	v_mfma_f32_16x16x32_bf16 v[20:23], v[168:171], v[200:203], v[20:23]
	v_mfma_f32_16x16x32_bf16 v[12:15], v[176:179], v[200:203], v[12:15]
	v_mfma_f32_16x16x32_bf16 v[4:7], v[168:171], v[208:211], v[4:7]
	v_mfma_f32_16x16x32_bf16 v[0:3], v[176:179], v[208:211], v[0:3]
	v_mfma_f32_16x16x32_bf16 v[52:55], v[172:175], v[188:191], v[52:55]
	v_mfma_f32_16x16x32_bf16 v[44:47], v[180:183], v[188:191], v[44:47]
	v_mfma_f32_16x16x32_bf16 v[36:39], v[172:175], v[196:199], v[36:39]
	v_mfma_f32_16x16x32_bf16 v[28:31], v[180:183], v[196:199], v[28:31]
	v_mfma_f32_16x16x32_bf16 v[20:23], v[172:175], v[204:207], v[20:23]
	v_mfma_f32_16x16x32_bf16 v[12:15], v[180:183], v[204:207], v[12:15]
	v_mfma_f32_16x16x32_bf16 v[4:7], v[172:175], v[212:215], v[4:7]
	v_mfma_f32_16x16x32_bf16 v[0:3], v[180:183], v[212:215], v[0:3]
	s_setprio 0
	s_barrier
	s_add_i32 s73, s73, 2
	s_add_u32 s71, s71, 0x100
	s_addc_u32 s72, s72, 0
	s_add_u32 s36, s36, 0x100
	s_addc_u32 s37, s37, 0
	s_cmp_gt_u32 s73, 29
	s_cbranch_scc0 .LBB0_689
	s_and_b64 vcc, exec, s[10:11]
	s_cbranch_vccz .LBB0_692
	s_barrier

; #define PG8_STAGE(bufoff, gbase, voff) do { _Pragma("unroll") for (int _i = 0; _i < 2; ++_i) \
;         __builtin_amdgcn_global_load_lds((const unsigned*)((const char*)(gbase) + (voff)[_i]), (LAS unsigned*)(lds + (bufoff) + ldsw + _i * 8192), 16, 0, 0); } while (0)
; #define PG8_LDA(dst, b, h) do { _Pragma("unroll") for (int m = 0; m < 4; ++m) _Pragma("unroll") for (int k = 0; k < 2; ++k) dst[m][k] = *(const LAS bf16x8*)(lds + PG8_SA(b, h) + aoff + m * 2048 + k * 1024); } while (0)
; #define PG8_LDB(dst, b, h) do { _Pragma("unroll") for (int n = 0; n < 2; ++n) _Pragma("unroll") for (int k = 0; k < 2; ++k) dst[n][k] = *(const LAS bf16x8*)(lds + PG8_SB(b, h) + boff + n * 2048 + k * 1024); } while (0)
; #define PG8_MMA(ai, bj, At, Bt) do { __builtin_amdgcn_s_setprio(1); _Pragma("unroll") for (int m = 0; m < 4; ++m) _Pragma("unroll") for (int n = 0; n < 2; ++n) _Pragma("unroll") for (int k = 0; k < 2; ++k) \
;         acc[ai][bj][m][n] = __builtin_amdgcn_mfma_f32_16x16x32_bf16(Bt[n][k], At[m][k], acc[ai][bj][m][n], 0, 0, 0); __builtin_amdgcn_s_setprio(0); } while (0)
; #define PG8_WAIT_V(n) asm volatile("s_waitcnt vmcnt(" #n ")" ::: "memory")
; #define PG8_WAIT_L(n) asm volatile("s_waitcnt lgkmcnt(" #n ")" ::: "memory")
; #define PG8_BAR __builtin_amdgcn_s_barrier()
; #define PG8_SCHED __builtin_amdgcn_sched_barrier(0)
; template <class Epi>
; __device__ __forceinline__ void gemm_phase(ldsp lds, const Gemm g, const StaticOrder& S, const Epi& E, int wave0) {
;     ...
;             const bool last = (t == nt - 2);
;             const char* a1 = cA + (size_t)(t + 1) * kstep;
;             const char* a2 = last ? nA : cA + (size_t)(t + 2) * kstep; const char* b2 = last ? nB : cB + (size_t)(t + 2) * kstep;
;             const char* a3 = a2 + kstep; const char* b3 = b2 + kstep;
;             PG8_LDB(B0, 0, 0); PG8_LDB(B1, 0, 1); PG8_SCHED; PG8_LDA(At, 0, 0); PG8_STAGE(PG8_SA(1, 1), a1 + hstep, voffA);
;             PG8_WAIT_V(8); PG8_WAIT_L(0); PG8_BAR; PG8_MMA(0, 0, At, B0); PG8_MMA(0, 1, At, B1); PG8_BAR; PG8_SCHED;
;             PG8_LDA(At, 0, 1); PG8_STAGE(PG8_SB(0, 0), b2, voffB); PG8_STAGE(PG8_SB(0, 1), b2 + hstep, voffB); PG8_STAGE(PG8_SA(0, 0), a2, voffA);
;             PG8_WAIT_V(8); PG8_WAIT_L(0); PG8_BAR; PG8_MMA(1, 0, At, B0); PG8_MMA(1, 1, At, B1); PG8_BAR; PG8_SCHED;
.LBB0_713:
	ds_read_b128 v[152:155], v149
	ds_read_b128 v[156:159], v149 offset:1024
	ds_read_b128 v[160:163], v149 offset:2048
	ds_read_b128 v[164:167], v149 offset:3072
	ds_read_b128 v[168:171], v150
	ds_read_b128 v[172:175], v150 offset:1024
	ds_read_b128 v[176:179], v150 offset:2048
	ds_read_b128 v[180:183], v150 offset:3072
	s_add_u32 s40, s38, 0xfffc0080
	s_addc_u32 s41, s39, -1
	s_cmp_eq_u32 s66, 12
	s_cselect_b32 s43, s29, s41
	s_cselect_b32 s42, s62, s40
	s_cselect_b32 s41, s27, s65
	s_cselect_b32 s40, s63, s64
	s_add_i32 m0, s37, 0xc000
	ds_read_b128 v[184:187], v151
	ds_read_b128 v[188:191], v151 offset:1024
	ds_read_b128 v[192:195], v151 offset:2048
	ds_read_b128 v[196:199], v151 offset:3072
	ds_read_b128 v[200:203], v151 offset:4096
	ds_read_b128 v[204:207], v151 offset:5120
	ds_read_b128 v[208:211], v151 offset:6144
	ds_read_b128 v[212:215], v151 offset:7168
	global_load_lds_dwordx4 v138, s[38:39]
	s_add_i32 m0, s37, 0xe000
	s_nop 0
	global_load_lds_dwordx4 v136, s[38:39]
	s_waitcnt vmcnt(8)
	s_waitcnt lgkmcnt(0)
	s_barrier
	s_setprio 1
	s_waitcnt lgkmcnt(0)
	v_mfma_f32_16x16x32_bf16 v[124:127], v[152:155], v[184:187], v[124:127]
	v_mfma_f32_16x16x32_bf16 v[120:123], v[160:163], v[184:187], v[120:123]
	v_mfma_f32_16x16x32_bf16 v[108:111], v[152:155], v[192:195], v[108:111]
	v_mfma_f32_16x16x32_bf16 v[104:107], v[160:163], v[192:195], v[104:107]
	v_mfma_f32_16x16x32_bf16 v[92:95], v[152:155], v[200:203], v[92:95]
	v_mfma_f32_16x16x32_bf16 v[88:91], v[160:163], v[200:203], v[88:91]
	v_mfma_f32_16x16x32_bf16 v[76:79], v[152:155], v[208:211], v[76:79]
	v_mfma_f32_16x16x32_bf16 v[72:75], v[160:163], v[208:211], v[72:75]
	v_mfma_f32_16x16x32_bf16 v[124:127], v[156:159], v[188:191], v[124:127]
	v_mfma_f32_16x16x32_bf16 v[120:123], v[164:167], v[188:191], v[120:123]
	v_mfma_f32_16x16x32_bf16 v[108:111], v[156:159], v[196:199], v[108:111]
	v_mfma_f32_16x16x32_bf16 v[104:107], v[164:167], v[196:199], v[104:107]
	v_mfma_f32_16x16x32_bf16 v[92:95], v[156:159], v[204:207], v[92:95]
	v_mfma_f32_16x16x32_bf16 v[88:91], v[164:167], v[204:207], v[88:91]
	v_mfma_f32_16x16x32_bf16 v[76:79], v[156:159], v[212:215], v[76:79]
	v_mfma_f32_16x16x32_bf16 v[72:75], v[164:167], v[212:215], v[72:75]
	v_mfma_f32_16x16x32_bf16 v[116:119], v[168:171], v[184:187], v[116:119]
	v_mfma_f32_16x16x32_bf16 v[112:115], v[176:179], v[184:187], v[112:115]
	v_mfma_f32_16x16x32_bf16 v[100:103], v[168:171], v[192:195], v[100:103]
	v_mfma_f32_16x16x32_bf16 v[96:99], v[176:179], v[192:195], v[96:99]
	v_mfma_f32_16x16x32_bf16 v[84:87], v[168:171], v[200:203], v[84:87]
	v_mfma_f32_16x16x32_bf16 v[80:83], v[176:179], v[200:203], v[80:83]
	v_mfma_f32_16x16x32_bf16 v[68:71], v[168:171], v[208:211], v[68:71]
	v_mfma_f32_16x16x32_bf16 v[64:67], v[176:179], v[208:211], v[64:67]
	v_mfma_f32_16x16x32_bf16 v[116:119], v[172:175], v[188:191], v[116:119]
	v_mfma_f32_16x16x32_bf16 v[112:115], v[180:183], v[188:191], v[112:115]
	v_mfma_f32_16x16x32_bf16 v[100:103], v[172:175], v[196:199], v[100:103]
	v_mfma_f32_16x16x32_bf16 v[96:99], v[180:183], v[196:199], v[96:99]
	v_mfma_f32_16x16x32_bf16 v[84:87], v[172:175], v[204:207], v[84:87]
	v_mfma_f32_16x16x32_bf16 v[80:83], v[180:183], v[204:207], v[80:83]
	v_mfma_f32_16x16x32_bf16 v[68:71], v[172:175], v[212:215], v[68:71]
	v_mfma_f32_16x16x32_bf16 v[64:67], v[180:183], v[212:215], v[64:67]
	s_setprio 0
	s_barrier
	s_add_i32 s67, s59, s49
	s_add_u32 s100, s42, 0x80
	s_addc_u32 s101, s43, 0
	s_mov_b32 m0, s67
	ds_read_b128 v[184:187], v151 offset:16384
	ds_read_b128 v[188:191], v151 offset:17408
	ds_read_b128 v[192:195], v151 offset:18432
	ds_read_b128 v[196:199], v151 offset:19456
	ds_read_b128 v[200:203], v151 offset:20480
	ds_read_b128 v[204:207], v151 offset:21504
	ds_read_b128 v[208:211], v151 offset:22528
	ds_read_b128 v[212:215], v151 offset:23552
	global_load_lds_dwordx4 v130, s[40:41]
	s_add_i32 m0, s67, 0x2000
	s_add_u32 s68, s40, 0x40000
	s_addc_u32 s69, s41, 0
	s_add_i32 s67, s60, s49
	global_load_lds_dwordx4 v134, s[40:41]
	s_mov_b32 m0, s67
	s_nop 0
	global_load_lds_dwordx4 v130, s[68:69]
	s_add_i32 m0, s67, 0x2000
	s_nop 0
	global_load_lds_dwordx4 v134, s[68:69]
	s_mov_b32 m0, s37
	s_nop 0
	global_load_lds_dwordx4 v128, s[42:43]
	s_mov_b32 m0, s50
	s_nop 0
	global_load_lds_dwordx4 v132, s[42:43]
	s_waitcnt vmcnt(8)
	s_waitcnt lgkmcnt(0)
	s_barrier
	s_setprio 1
	s_waitcnt lgkmcnt(0)
	v_mfma_f32_16x16x32_bf16 v[60:63], v[152:155], v[184:187], v[60:63]
	v_mfma_f32_16x16x32_bf16 v[56:59], v[160:163], v[184:187], v[56:59]
	v_mfma_f32_16x16x32_bf16 v[44:47], v[152:155], v[192:195], v[44:47]
	v_mfma_f32_16x16x32_bf16 v[40:43], v[160:163], v[192:195], v[40:43]
	v_mfma_f32_16x16x32_bf16 v[28:31], v[152:155], v[200:203], v[28:31]
	v_mfma_f32_16x16x32_bf16 v[24:27], v[160:163], v[200:203], v[24:27]
	v_mfma_f32_16x16x32_bf16 v[12:15], v[152:155], v[208:211], v[12:15]
	v_mfma_f32_16x16x32_bf16 v[8:11], v[160:163], v[208:211], v[8:11]
	v_mfma_f32_16x16x32_bf16 v[60:63], v[156:159], v[188:191], v[60:63]
	v_mfma_f32_16x16x32_bf16 v[56:59], v[164:167], v[188:191], v[56:59]
	v_mfma_f32_16x16x32_bf16 v[44:47], v[156:159], v[196:199], v[44:47]
	v_mfma_f32_16x16x32_bf16 v[40:43], v[164:167], v[196:199], v[40:43]
	v_mfma_f32_16x16x32_bf16 v[28:31], v[156:159], v[204:207], v[28:31]
	v_mfma_f32_16x16x32_bf16 v[24:27], v[164:167], v[204:207], v[24:27]
	v_mfma_f32_16x16x32_bf16 v[12:15], v[156:159], v[212:215], v[12:15]
	v_mfma_f32_16x16x32_bf16 v[8:11], v[164:167], v[212:215], v[8:11]
	v_mfma_f32_16x16x32_bf16 v[52:55], v[168:171], v[184:187], v[52:55]
	v_mfma_f32_16x16x32_bf16 v[48:51], v[176:179], v[184:187], v[48:51]
	v_mfma_f32_16x16x32_bf16 v[36:39], v[168:171], v[192:195], v[36:39]
	v_mfma_f32_16x16x32_bf16 v[32:35], v[176:179], v[192:195], v[32:35]
	v_mfma_f32_16x16x32_bf16 v[20:23], v[168:171], v[200:203], v[20:23]
	v_mfma_f32_16x16x32_bf16 v[16:19], v[176:179], v[200:203], v[16:19]
	v_mfma_f32_16x16x32_bf16 v[4:7], v[168:171], v[208:211], v[4:7]
	v_mfma_f32_16x16x32_bf16 v[0:3], v[176:179], v[208:211], v[0:3]
	v_mfma_f32_16x16x32_bf16 v[52:55], v[172:175], v[188:191], v[52:55]
	v_mfma_f32_16x16x32_bf16 v[48:51], v[180:183], v[188:191], v[48:51]
	v_mfma_f32_16x16x32_bf16 v[36:39], v[172:175], v[196:199], v[36:39]
	v_mfma_f32_16x16x32_bf16 v[32:35], v[180:183], v[196:199], v[32:35]
	v_mfma_f32_16x16x32_bf16 v[20:23], v[172:175], v[204:207], v[20:23]
	v_mfma_f32_16x16x32_bf16 v[16:19], v[180:183], v[204:207], v[16:19]
	v_mfma_f32_16x16x32_bf16 v[4:7], v[172:175], v[212:215], v[4:7]
	v_mfma_f32_16x16x32_bf16 v[0:3], v[180:183], v[212:215], v[0:3]
	s_setprio 0
	s_barrier
; #define PG8_STAGE(bufoff, gbase, voff) do { _Pragma("unroll") for (int _i = 0; _i < 2; ++_i) \
;         __builtin_amdgcn_global_load_lds((const unsigned*)((const char*)(gbase) + (voff)[_i]), (LAS unsigned*)(lds + (bufoff) + ldsw + _i * 8192), 16, 0, 0); } while (0)
; #define PG8_LDA(dst, b, h) do { _Pragma("unroll") for (int m = 0; m < 4; ++m) _Pragma("unroll") for (int k = 0; k < 2; ++k) dst[m][k] = *(const LAS bf16x8*)(lds + PG8_SA(b, h) + aoff + m * 2048 + k * 1024); } while (0)
; #define PG8_LDB(dst, b, h) do { _Pragma("unroll") for (int n = 0; n < 2; ++n) _Pragma("unroll") for (int k = 0; k < 2; ++k) dst[n][k] = *(const LAS bf16x8*)(lds + PG8_SB(b, h) + boff + n * 2048 + k * 1024); } while (0)
; #define PG8_MMA(ai, bj, At, Bt) do { __builtin_amdgcn_s_setprio(1); _Pragma("unroll") for (int m = 0; m < 4; ++m) _Pragma("unroll") for (int n = 0; n < 2; ++n) _Pragma("unroll") for (int k = 0; k < 2; ++k) \
;         acc[ai][bj][m][n] = __builtin_amdgcn_mfma_f32_16x16x32_bf16(Bt[n][k], At[m][k], acc[ai][bj][m][n], 0, 0, 0); __builtin_amdgcn_s_setprio(0); } while (0)
; #define PG8_WAIT_V(n) asm volatile("s_waitcnt vmcnt(" #n ")" ::: "memory")
; #define PG8_WAIT_L(n) asm volatile("s_waitcnt lgkmcnt(" #n ")" ::: "memory")
; #define PG8_BAR __builtin_amdgcn_s_barrier()
; #define PG8_SCHED __builtin_amdgcn_sched_barrier(0)
; template <class Epi>
; __device__ __forceinline__ void gemm_phase(ldsp lds, const Gemm g, const StaticOrder& S, const Epi& E, int wave0) {
;     ...
;             PG8_LDB(B0, 1, 0); PG8_LDB(B1, 1, 1); PG8_SCHED; PG8_LDA(At, 1, 0); PG8_STAGE(PG8_SA(0, 1), a2 + hstep, voffA);
;             PG8_WAIT_V(8); PG8_WAIT_L(0); PG8_BAR; PG8_MMA(0, 0, At, B0); PG8_MMA(0, 1, At, B1); PG8_BAR; PG8_SCHED;
;             PG8_LDA(At, 1, 1); PG8_STAGE(PG8_SB(1, 0), b3, voffB); PG8_STAGE(PG8_SB(1, 1), b3 + hstep, voffB); PG8_STAGE(PG8_SA(1, 0), a3, voffA);
;             PG8_WAIT_V(8); PG8_WAIT_L(0); PG8_BAR; PG8_MMA(1, 0, At, B0); PG8_MMA(1, 1, At, B1); PG8_BAR; PG8_SCHED;
;         }
;         if (wr == 0) PG8_BAR;
	s_add_i32 s67, 0, 0x18000
	s_add_i32 s68, 0, 0x1c000
	v_add_u32_e32 v164, s67, v148
	v_add_u32_e32 v180, s68, v148
	ds_read_b128 v[152:155], v164
	ds_read_b128 v[156:159], v164 offset:1024
	ds_read_b128 v[160:163], v164 offset:2048
	ds_read_b128 v[164:167], v164 offset:3072
	ds_read_b128 v[168:171], v180
	ds_read_b128 v[172:175], v180 offset:1024
	ds_read_b128 v[176:179], v180 offset:2048
	ds_read_b128 v[180:183], v180 offset:3072
	s_add_u32 s42, s42, 0x40000
	s_addc_u32 s43, s43, 0
	s_mov_b32 m0, s51
	ds_read_b128 v[184:187], v151 offset:32768
	ds_read_b128 v[188:191], v151 offset:33792
	ds_read_b128 v[192:195], v151 offset:34816
	ds_read_b128 v[196:199], v151 offset:35840
	ds_read_b128 v[200:203], v151 offset:36864
	ds_read_b128 v[204:207], v151 offset:37888
	ds_read_b128 v[208:211], v151 offset:38912
	ds_read_b128 v[212:215], v151 offset:39936
	global_load_lds_dwordx4 v128, s[42:43]
	s_mov_b32 m0, s52
	s_nop 0
	global_load_lds_dwordx4 v132, s[42:43]
	s_waitcnt vmcnt(8)
	s_waitcnt lgkmcnt(0)
	s_barrier
	s_setprio 1
	s_waitcnt lgkmcnt(0)
	v_mfma_f32_16x16x32_bf16 v[124:127], v[152:155], v[184:187], v[124:127]
	v_mfma_f32_16x16x32_bf16 v[120:123], v[160:163], v[184:187], v[120:123]
	v_mfma_f32_16x16x32_bf16 v[108:111], v[152:155], v[192:195], v[108:111]
	v_mfma_f32_16x16x32_bf16 v[104:107], v[160:163], v[192:195], v[104:107]
	v_mfma_f32_16x16x32_bf16 v[92:95], v[152:155], v[200:203], v[92:95]
	v_mfma_f32_16x16x32_bf16 v[88:91], v[160:163], v[200:203], v[88:91]
	v_mfma_f32_16x16x32_bf16 v[76:79], v[152:155], v[208:211], v[76:79]
	v_mfma_f32_16x16x32_bf16 v[72:75], v[160:163], v[208:211], v[72:75]
	v_mfma_f32_16x16x32_bf16 v[124:127], v[156:159], v[188:191], v[124:127]
	v_mfma_f32_16x16x32_bf16 v[120:123], v[164:167], v[188:191], v[120:123]
	v_mfma_f32_16x16x32_bf16 v[108:111], v[156:159], v[196:199], v[108:111]
	v_mfma_f32_16x16x32_bf16 v[104:107], v[164:167], v[196:199], v[104:107]
	v_mfma_f32_16x16x32_bf16 v[92:95], v[156:159], v[204:207], v[92:95]
	v_mfma_f32_16x16x32_bf16 v[88:91], v[164:167], v[204:207], v[88:91]
	v_mfma_f32_16x16x32_bf16 v[76:79], v[156:159], v[212:215], v[76:79]
	v_mfma_f32_16x16x32_bf16 v[72:75], v[164:167], v[212:215], v[72:75]
	v_mfma_f32_16x16x32_bf16 v[116:119], v[168:171], v[184:187], v[116:119]
	v_mfma_f32_16x16x32_bf16 v[112:115], v[176:179], v[184:187], v[112:115]
	v_mfma_f32_16x16x32_bf16 v[100:103], v[168:171], v[192:195], v[100:103]
	v_mfma_f32_16x16x32_bf16 v[96:99], v[176:179], v[192:195], v[96:99]
	v_mfma_f32_16x16x32_bf16 v[84:87], v[168:171], v[200:203], v[84:87]
	v_mfma_f32_16x16x32_bf16 v[80:83], v[176:179], v[200:203], v[80:83]
	v_mfma_f32_16x16x32_bf16 v[68:71], v[168:171], v[208:211], v[68:71]
	v_mfma_f32_16x16x32_bf16 v[64:67], v[176:179], v[208:211], v[64:67]
	v_mfma_f32_16x16x32_bf16 v[116:119], v[172:175], v[188:191], v[116:119]
	v_mfma_f32_16x16x32_bf16 v[112:115], v[180:183], v[188:191], v[112:115]
	v_mfma_f32_16x16x32_bf16 v[100:103], v[172:175], v[196:199], v[100:103]
	v_mfma_f32_16x16x32_bf16 v[96:99], v[180:183], v[196:199], v[96:99]
	v_mfma_f32_16x16x32_bf16 v[84:87], v[172:175], v[204:207], v[84:87]
	v_mfma_f32_16x16x32_bf16 v[80:83], v[180:183], v[204:207], v[80:83]
	v_mfma_f32_16x16x32_bf16 v[68:71], v[172:175], v[212:215], v[68:71]
	v_mfma_f32_16x16x32_bf16 v[64:67], v[180:183], v[212:215], v[64:67]
	s_setprio 0
	s_barrier
	s_add_i32 s42, s67, s49
	s_add_u32 s40, s40, 0x80
	s_addc_u32 s41, s41, 0
	s_mov_b32 m0, s42
	ds_read_b128 v[184:187], v151 offset:49152
	ds_read_b128 v[188:191], v151 offset:50176
	ds_read_b128 v[192:195], v151 offset:51200
	ds_read_b128 v[196:199], v151 offset:52224
	ds_read_b128 v[200:203], v151 offset:53248
	ds_read_b128 v[204:207], v151 offset:54272
	ds_read_b128 v[208:211], v151 offset:55296
	ds_read_b128 v[212:215], v151 offset:56320
	global_load_lds_dwordx4 v130, s[40:41]
	s_add_i32 m0, s42, 0x2000
	s_add_i32 s42, s68, s49
	global_load_lds_dwordx4 v134, s[40:41]
	s_add_u32 s40, s40, 0x40000
	s_addc_u32 s41, s41, 0
	s_mov_b32 m0, s42
	s_nop 0
	global_load_lds_dwordx4 v130, s[40:41]
	s_add_i32 m0, s42, 0x2000
	s_nop 0
	global_load_lds_dwordx4 v134, s[40:41]
	s_mov_b32 m0, s56
	s_nop 0
	global_load_lds_dwordx4 v128, s[100:101]
	s_mov_b32 m0, s57
	s_nop 0
	global_load_lds_dwordx4 v132, s[100:101]
	s_waitcnt vmcnt(8)
	s_waitcnt lgkmcnt(0)
	s_barrier
	s_setprio 1
	s_waitcnt lgkmcnt(0)
	v_mfma_f32_16x16x32_bf16 v[60:63], v[152:155], v[184:187], v[60:63]
	v_mfma_f32_16x16x32_bf16 v[56:59], v[160:163], v[184:187], v[56:59]
	v_mfma_f32_16x16x32_bf16 v[44:47], v[152:155], v[192:195], v[44:47]
	v_mfma_f32_16x16x32_bf16 v[40:43], v[160:163], v[192:195], v[40:43]
	v_mfma_f32_16x16x32_bf16 v[28:31], v[152:155], v[200:203], v[28:31]
	v_mfma_f32_16x16x32_bf16 v[24:27], v[160:163], v[200:203], v[24:27]
	v_mfma_f32_16x16x32_bf16 v[12:15], v[152:155], v[208:211], v[12:15]
	v_mfma_f32_16x16x32_bf16 v[8:11], v[160:163], v[208:211], v[8:11]
	v_mfma_f32_16x16x32_bf16 v[60:63], v[156:159], v[188:191], v[60:63]
	v_mfma_f32_16x16x32_bf16 v[56:59], v[164:167], v[188:191], v[56:59]
	v_mfma_f32_16x16x32_bf16 v[44:47], v[156:159], v[196:199], v[44:47]
	v_mfma_f32_16x16x32_bf16 v[40:43], v[164:167], v[196:199], v[40:43]
	v_mfma_f32_16x16x32_bf16 v[28:31], v[156:159], v[204:207], v[28:31]
	v_mfma_f32_16x16x32_bf16 v[24:27], v[164:167], v[204:207], v[24:27]
	v_mfma_f32_16x16x32_bf16 v[12:15], v[156:159], v[212:215], v[12:15]
	v_mfma_f32_16x16x32_bf16 v[8:11], v[164:167], v[212:215], v[8:11]
	v_mfma_f32_16x16x32_bf16 v[52:55], v[168:171], v[184:187], v[52:55]
	v_mfma_f32_16x16x32_bf16 v[48:51], v[176:179], v[184:187], v[48:51]
	v_mfma_f32_16x16x32_bf16 v[36:39], v[168:171], v[192:195], v[36:39]
	v_mfma_f32_16x16x32_bf16 v[32:35], v[176:179], v[192:195], v[32:35]
	v_mfma_f32_16x16x32_bf16 v[20:23], v[168:171], v[200:203], v[20:23]
	v_mfma_f32_16x16x32_bf16 v[16:19], v[176:179], v[200:203], v[16:19]
	v_mfma_f32_16x16x32_bf16 v[4:7], v[168:171], v[208:211], v[4:7]
	v_mfma_f32_16x16x32_bf16 v[0:3], v[176:179], v[208:211], v[0:3]
	v_mfma_f32_16x16x32_bf16 v[52:55], v[172:175], v[188:191], v[52:55]
	v_mfma_f32_16x16x32_bf16 v[48:51], v[180:183], v[188:191], v[48:51]
	v_mfma_f32_16x16x32_bf16 v[36:39], v[172:175], v[196:199], v[36:39]
	v_mfma_f32_16x16x32_bf16 v[32:35], v[180:183], v[196:199], v[32:35]
	v_mfma_f32_16x16x32_bf16 v[20:23], v[172:175], v[204:207], v[20:23]
	v_mfma_f32_16x16x32_bf16 v[16:19], v[180:183], v[204:207], v[16:19]
	v_mfma_f32_16x16x32_bf16 v[4:7], v[172:175], v[212:215], v[4:7]
	v_mfma_f32_16x16x32_bf16 v[0:3], v[180:183], v[212:215], v[0:3]
	s_setprio 0
	s_barrier
	s_add_i32 s66, s66, 2
	s_add_u32 s64, s64, 0x100
	s_addc_u32 s65, s65, 0
	s_add_u32 s38, s38, 0x100
	s_addc_u32 s39, s39, 0
	s_cmp_gt_u32 s66, 13
	s_cbranch_scc0 .LBB0_713
	s_and_b64 vcc, exec, s[10:11]
	s_cbranch_vccz .LBB0_716
	s_barrier

; #define PG8_STAGE(bufoff, gbase, voff) do { _Pragma("unroll") for (int _i = 0; _i < 2; ++_i) \
;         __builtin_amdgcn_global_load_lds((const unsigned*)((const char*)(gbase) + (voff)[_i]), (LAS unsigned*)(lds + (bufoff) + ldsw + _i * 8192), 16, 0, 0); } while (0)
; #define PG8_LDA(dst, b, h) do { _Pragma("unroll") for (int m = 0; m < 4; ++m) _Pragma("unroll") for (int k = 0; k < 2; ++k) dst[m][k] = *(const LAS bf16x8*)(lds + PG8_SA(b, h) + aoff + m * 2048 + k * 1024); } while (0)
; #define PG8_LDB(dst, b, h) do { _Pragma("unroll") for (int n = 0; n < 2; ++n) _Pragma("unroll") for (int k = 0; k < 2; ++k) dst[n][k] = *(const LAS bf16x8*)(lds + PG8_SB(b, h) + boff + n * 2048 + k * 1024); } while (0)
; #define PG8_MMA(ai, bj, At, Bt) do { __builtin_amdgcn_s_setprio(1); _Pragma("unroll") for (int m = 0; m < 4; ++m) _Pragma("unroll") for (int n = 0; n < 2; ++n) _Pragma("unroll") for (int k = 0; k < 2; ++k) \
;         acc[ai][bj][m][n] = __builtin_amdgcn_mfma_f32_16x16x32_bf16(Bt[n][k], At[m][k], acc[ai][bj][m][n], 0, 0, 0); __builtin_amdgcn_s_setprio(0); } while (0)
; #define PG8_WAIT_V(n) asm volatile("s_waitcnt vmcnt(" #n ")" ::: "memory")
; #define PG8_WAIT_L(n) asm volatile("s_waitcnt lgkmcnt(" #n ")" ::: "memory")
; #define PG8_BAR __builtin_amdgcn_s_barrier()
; #define PG8_SCHED __builtin_amdgcn_sched_barrier(0)
; template <class Epi>
; __device__ __forceinline__ void gemm_phase(ldsp lds, const Gemm g, const StaticOrder& S, const Epi& E, int wave0) {
;     ...
;             const bool last = (t == nt - 2);
;             const char* a1 = cA + (size_t)(t + 1) * kstep;
;             const char* a2 = last ? nA : cA + (size_t)(t + 2) * kstep; const char* b2 = last ? nB : cB + (size_t)(t + 2) * kstep;
;             const char* a3 = a2 + kstep; const char* b3 = b2 + kstep;
;             PG8_LDB(B0, 0, 0); PG8_LDB(B1, 0, 1); PG8_SCHED; PG8_LDA(At, 0, 0); PG8_STAGE(PG8_SA(1, 1), a1 + hstep, voffA);
;             PG8_WAIT_V(8); PG8_WAIT_L(0); PG8_BAR; PG8_MMA(0, 0, At, B0); PG8_MMA(0, 1, At, B1); PG8_BAR; PG8_SCHED;
;             PG8_LDA(At, 0, 1); PG8_STAGE(PG8_SB(0, 0), b2, voffB); PG8_STAGE(PG8_SB(0, 1), b2 + hstep, voffB); PG8_STAGE(PG8_SA(0, 0), a2, voffA);
;             PG8_WAIT_V(8); PG8_WAIT_L(0); PG8_BAR; PG8_MMA(1, 0, At, B0); PG8_MMA(1, 1, At, B1); PG8_BAR; PG8_SCHED;
.LBB0_781:
	ds_read_b128 v[152:155], v149
	ds_read_b128 v[156:159], v149 offset:1024
	ds_read_b128 v[160:163], v149 offset:2048
	ds_read_b128 v[164:167], v149 offset:3072
	ds_read_b128 v[168:171], v150
	ds_read_b128 v[172:175], v150 offset:1024
	ds_read_b128 v[176:179], v150 offset:2048
	ds_read_b128 v[180:183], v150 offset:3072
	s_add_u32 s42, s40, 0xfff80080
	s_addc_u32 s43, s41, -1
	s_cmp_eq_u32 s69, 28
	s_cselect_b32 s45, s31, s43
	s_cselect_b32 s44, s65, s42
	s_cselect_b32 s43, s29, s68
	s_cselect_b32 s42, s66, s67
	s_add_i32 m0, s39, 0xc000
	ds_read_b128 v[184:187], v151
	ds_read_b128 v[188:191], v151 offset:1024
	ds_read_b128 v[192:195], v151 offset:2048
	ds_read_b128 v[196:199], v151 offset:3072
	ds_read_b128 v[200:203], v151 offset:4096
	ds_read_b128 v[204:207], v151 offset:5120
	ds_read_b128 v[208:211], v151 offset:6144
	ds_read_b128 v[212:215], v151 offset:7168
	global_load_lds_dwordx4 v138, s[40:41]
	s_add_i32 m0, s39, 0xe000
	s_nop 0
	global_load_lds_dwordx4 v136, s[40:41]
	s_waitcnt vmcnt(8)
	s_waitcnt lgkmcnt(0)
	s_barrier
	s_setprio 1
	s_waitcnt lgkmcnt(0)
	v_mfma_f32_16x16x32_bf16 v[124:127], v[152:155], v[184:187], v[124:127]
	v_mfma_f32_16x16x32_bf16 v[120:123], v[160:163], v[184:187], v[120:123]
	v_mfma_f32_16x16x32_bf16 v[108:111], v[152:155], v[192:195], v[108:111]
	v_mfma_f32_16x16x32_bf16 v[104:107], v[160:163], v[192:195], v[104:107]
	v_mfma_f32_16x16x32_bf16 v[92:95], v[152:155], v[200:203], v[92:95]
	v_mfma_f32_16x16x32_bf16 v[88:91], v[160:163], v[200:203], v[88:91]
	v_mfma_f32_16x16x32_bf16 v[76:79], v[152:155], v[208:211], v[76:79]
	v_mfma_f32_16x16x32_bf16 v[72:75], v[160:163], v[208:211], v[72:75]
	v_mfma_f32_16x16x32_bf16 v[124:127], v[156:159], v[188:191], v[124:127]
	v_mfma_f32_16x16x32_bf16 v[120:123], v[164:167], v[188:191], v[120:123]
	v_mfma_f32_16x16x32_bf16 v[108:111], v[156:159], v[196:199], v[108:111]
	v_mfma_f32_16x16x32_bf16 v[104:107], v[164:167], v[196:199], v[104:107]
	v_mfma_f32_16x16x32_bf16 v[92:95], v[156:159], v[204:207], v[92:95]
	v_mfma_f32_16x16x32_bf16 v[88:91], v[164:167], v[204:207], v[88:91]
	v_mfma_f32_16x16x32_bf16 v[76:79], v[156:159], v[212:215], v[76:79]
	v_mfma_f32_16x16x32_bf16 v[72:75], v[164:167], v[212:215], v[72:75]
	v_mfma_f32_16x16x32_bf16 v[116:119], v[168:171], v[184:187], v[116:119]
	v_mfma_f32_16x16x32_bf16 v[112:115], v[176:179], v[184:187], v[112:115]
	v_mfma_f32_16x16x32_bf16 v[100:103], v[168:171], v[192:195], v[100:103]
	v_mfma_f32_16x16x32_bf16 v[96:99], v[176:179], v[192:195], v[96:99]
	v_mfma_f32_16x16x32_bf16 v[84:87], v[168:171], v[200:203], v[84:87]
	v_mfma_f32_16x16x32_bf16 v[80:83], v[176:179], v[200:203], v[80:83]
	v_mfma_f32_16x16x32_bf16 v[68:71], v[168:171], v[208:211], v[68:71]
	v_mfma_f32_16x16x32_bf16 v[64:67], v[176:179], v[208:211], v[64:67]
	v_mfma_f32_16x16x32_bf16 v[116:119], v[172:175], v[188:191], v[116:119]
	v_mfma_f32_16x16x32_bf16 v[112:115], v[180:183], v[188:191], v[112:115]
	v_mfma_f32_16x16x32_bf16 v[100:103], v[172:175], v[196:199], v[100:103]
	v_mfma_f32_16x16x32_bf16 v[96:99], v[180:183], v[196:199], v[96:99]
	v_mfma_f32_16x16x32_bf16 v[84:87], v[172:175], v[204:207], v[84:87]
	v_mfma_f32_16x16x32_bf16 v[80:83], v[180:183], v[204:207], v[80:83]
	v_mfma_f32_16x16x32_bf16 v[68:71], v[172:175], v[212:215], v[68:71]
	v_mfma_f32_16x16x32_bf16 v[64:67], v[180:183], v[212:215], v[64:67]
	s_setprio 0
	s_barrier
	s_add_i32 s70, s62, s52
	s_add_u32 s100, s44, 0x80
	s_addc_u32 s101, s45, 0
	s_mov_b32 m0, s70
	ds_read_b128 v[184:187], v151 offset:16384
	ds_read_b128 v[188:191], v151 offset:17408
	ds_read_b128 v[192:195], v151 offset:18432
	ds_read_b128 v[196:199], v151 offset:19456
	ds_read_b128 v[200:203], v151 offset:20480
	ds_read_b128 v[204:207], v151 offset:21504
	ds_read_b128 v[208:211], v151 offset:22528
	ds_read_b128 v[212:215], v151 offset:23552
	global_load_lds_dwordx4 v130, s[42:43]
	s_add_i32 m0, s70, 0x2000
	s_add_u32 s70, s42, 0x80000
	s_addc_u32 s71, s43, 0
	s_add_i32 s72, s63, s52
	global_load_lds_dwordx4 v134, s[42:43]
	s_mov_b32 m0, s72
	s_nop 0
	global_load_lds_dwordx4 v130, s[70:71]
	s_add_i32 m0, s72, 0x2000
	s_nop 0
	global_load_lds_dwordx4 v134, s[70:71]
	s_mov_b32 m0, s39
	s_nop 0
	global_load_lds_dwordx4 v128, s[44:45]
	s_mov_b32 m0, s53
	s_nop 0
	global_load_lds_dwordx4 v132, s[44:45]
	s_waitcnt vmcnt(8)
	s_waitcnt lgkmcnt(0)
	s_barrier
	s_setprio 1
	s_waitcnt lgkmcnt(0)
	v_mfma_f32_16x16x32_bf16 v[60:63], v[152:155], v[184:187], v[60:63]
	v_mfma_f32_16x16x32_bf16 v[56:59], v[160:163], v[184:187], v[56:59]
	v_mfma_f32_16x16x32_bf16 v[44:47], v[152:155], v[192:195], v[44:47]
	v_mfma_f32_16x16x32_bf16 v[40:43], v[160:163], v[192:195], v[40:43]
	v_mfma_f32_16x16x32_bf16 v[28:31], v[152:155], v[200:203], v[28:31]
	v_mfma_f32_16x16x32_bf16 v[24:27], v[160:163], v[200:203], v[24:27]
	v_mfma_f32_16x16x32_bf16 v[12:15], v[152:155], v[208:211], v[12:15]
	v_mfma_f32_16x16x32_bf16 v[8:11], v[160:163], v[208:211], v[8:11]
	v_mfma_f32_16x16x32_bf16 v[60:63], v[156:159], v[188:191], v[60:63]
	v_mfma_f32_16x16x32_bf16 v[56:59], v[164:167], v[188:191], v[56:59]
	v_mfma_f32_16x16x32_bf16 v[44:47], v[156:159], v[196:199], v[44:47]
	v_mfma_f32_16x16x32_bf16 v[40:43], v[164:167], v[196:199], v[40:43]
	v_mfma_f32_16x16x32_bf16 v[28:31], v[156:159], v[204:207], v[28:31]
	v_mfma_f32_16x16x32_bf16 v[24:27], v[164:167], v[204:207], v[24:27]
	v_mfma_f32_16x16x32_bf16 v[12:15], v[156:159], v[212:215], v[12:15]
	v_mfma_f32_16x16x32_bf16 v[8:11], v[164:167], v[212:215], v[8:11]
	v_mfma_f32_16x16x32_bf16 v[52:55], v[168:171], v[184:187], v[52:55]
	v_mfma_f32_16x16x32_bf16 v[48:51], v[176:179], v[184:187], v[48:51]
	v_mfma_f32_16x16x32_bf16 v[36:39], v[168:171], v[192:195], v[36:39]
	v_mfma_f32_16x16x32_bf16 v[32:35], v[176:179], v[192:195], v[32:35]
	v_mfma_f32_16x16x32_bf16 v[20:23], v[168:171], v[200:203], v[20:23]
	v_mfma_f32_16x16x32_bf16 v[16:19], v[176:179], v[200:203], v[16:19]
	v_mfma_f32_16x16x32_bf16 v[4:7], v[168:171], v[208:211], v[4:7]
	v_mfma_f32_16x16x32_bf16 v[0:3], v[176:179], v[208:211], v[0:3]
	v_mfma_f32_16x16x32_bf16 v[52:55], v[172:175], v[188:191], v[52:55]
	v_mfma_f32_16x16x32_bf16 v[48:51], v[180:183], v[188:191], v[48:51]
	v_mfma_f32_16x16x32_bf16 v[36:39], v[172:175], v[196:199], v[36:39]
	v_mfma_f32_16x16x32_bf16 v[32:35], v[180:183], v[196:199], v[32:35]
	v_mfma_f32_16x16x32_bf16 v[20:23], v[172:175], v[204:207], v[20:23]
	v_mfma_f32_16x16x32_bf16 v[16:19], v[180:183], v[204:207], v[16:19]
	v_mfma_f32_16x16x32_bf16 v[4:7], v[172:175], v[212:215], v[4:7]
	v_mfma_f32_16x16x32_bf16 v[0:3], v[180:183], v[212:215], v[0:3]
	s_setprio 0
	s_barrier
; #define PG8_STAGE(bufoff, gbase, voff) do { _Pragma("unroll") for (int _i = 0; _i < 2; ++_i) \
;         __builtin_amdgcn_global_load_lds((const unsigned*)((const char*)(gbase) + (voff)[_i]), (LAS unsigned*)(lds + (bufoff) + ldsw + _i * 8192), 16, 0, 0); } while (0)
; #define PG8_LDA(dst, b, h) do { _Pragma("unroll") for (int m = 0; m < 4; ++m) _Pragma("unroll") for (int k = 0; k < 2; ++k) dst[m][k] = *(const LAS bf16x8*)(lds + PG8_SA(b, h) + aoff + m * 2048 + k * 1024); } while (0)
; #define PG8_LDB(dst, b, h) do { _Pragma("unroll") for (int n = 0; n < 2; ++n) _Pragma("unroll") for (int k = 0; k < 2; ++k) dst[n][k] = *(const LAS bf16x8*)(lds + PG8_SB(b, h) + boff + n * 2048 + k * 1024); } while (0)
; #define PG8_MMA(ai, bj, At, Bt) do { __builtin_amdgcn_s_setprio(1); _Pragma("unroll") for (int m = 0; m < 4; ++m) _Pragma("unroll") for (int n = 0; n < 2; ++n) _Pragma("unroll") for (int k = 0; k < 2; ++k) \
;         acc[ai][bj][m][n] = __builtin_amdgcn_mfma_f32_16x16x32_bf16(Bt[n][k], At[m][k], acc[ai][bj][m][n], 0, 0, 0); __builtin_amdgcn_s_setprio(0); } while (0)
; #define PG8_WAIT_V(n) asm volatile("s_waitcnt vmcnt(" #n ")" ::: "memory")
; #define PG8_WAIT_L(n) asm volatile("s_waitcnt lgkmcnt(" #n ")" ::: "memory")
; #define PG8_BAR __builtin_amdgcn_s_barrier()
; #define PG8_SCHED __builtin_amdgcn_sched_barrier(0)
; template <class Epi>
; __device__ __forceinline__ void gemm_phase(ldsp lds, const Gemm g, const StaticOrder& S, const Epi& E, int wave0) {
;     ...
;             PG8_LDB(B0, 1, 0); PG8_LDB(B1, 1, 1); PG8_SCHED; PG8_LDA(At, 1, 0); PG8_STAGE(PG8_SA(0, 1), a2 + hstep, voffA);
;             PG8_WAIT_V(8); PG8_WAIT_L(0); PG8_BAR; PG8_MMA(0, 0, At, B0); PG8_MMA(0, 1, At, B1); PG8_BAR; PG8_SCHED;
;             PG8_LDA(At, 1, 1); PG8_STAGE(PG8_SB(1, 0), b3, voffB); PG8_STAGE(PG8_SB(1, 1), b3 + hstep, voffB); PG8_STAGE(PG8_SA(1, 0), a3, voffA);
;             PG8_WAIT_V(8); PG8_WAIT_L(0); PG8_BAR; PG8_MMA(1, 0, At, B0); PG8_MMA(1, 1, At, B1); PG8_BAR; PG8_SCHED;
;         }
;         if (wr == 0) PG8_BAR;
	s_add_i32 s70, 0, 0x18000
	s_add_i32 s71, 0, 0x1c000
	v_add_u32_e32 v164, s70, v148
	v_add_u32_e32 v180, s71, v148
	ds_read_b128 v[152:155], v164
	ds_read_b128 v[156:159], v164 offset:1024
	ds_read_b128 v[160:163], v164 offset:2048
	ds_read_b128 v[164:167], v164 offset:3072
	ds_read_b128 v[168:171], v180
	ds_read_b128 v[172:175], v180 offset:1024
	ds_read_b128 v[176:179], v180 offset:2048
	ds_read_b128 v[180:183], v180 offset:3072
	s_add_u32 s44, s44, 0x80000
	s_addc_u32 s45, s45, 0
	s_mov_b32 m0, s54
	ds_read_b128 v[184:187], v151 offset:32768
	ds_read_b128 v[188:191], v151 offset:33792
	ds_read_b128 v[192:195], v151 offset:34816
	ds_read_b128 v[196:199], v151 offset:35840
	ds_read_b128 v[200:203], v151 offset:36864
	ds_read_b128 v[204:207], v151 offset:37888
	ds_read_b128 v[208:211], v151 offset:38912
	ds_read_b128 v[212:215], v151 offset:39936
	global_load_lds_dwordx4 v128, s[44:45]
	s_mov_b32 m0, s55
	s_nop 0
	global_load_lds_dwordx4 v132, s[44:45]
	s_waitcnt vmcnt(8)
	s_waitcnt lgkmcnt(0)
	s_barrier
	s_setprio 1
	s_waitcnt lgkmcnt(0)
	v_mfma_f32_16x16x32_bf16 v[124:127], v[152:155], v[184:187], v[124:127]
	v_mfma_f32_16x16x32_bf16 v[120:123], v[160:163], v[184:187], v[120:123]
	v_mfma_f32_16x16x32_bf16 v[108:111], v[152:155], v[192:195], v[108:111]
	v_mfma_f32_16x16x32_bf16 v[104:107], v[160:163], v[192:195], v[104:107]
	v_mfma_f32_16x16x32_bf16 v[92:95], v[152:155], v[200:203], v[92:95]
	v_mfma_f32_16x16x32_bf16 v[88:91], v[160:163], v[200:203], v[88:91]
	v_mfma_f32_16x16x32_bf16 v[76:79], v[152:155], v[208:211], v[76:79]
	v_mfma_f32_16x16x32_bf16 v[72:75], v[160:163], v[208:211], v[72:75]
	v_mfma_f32_16x16x32_bf16 v[124:127], v[156:159], v[188:191], v[124:127]
	v_mfma_f32_16x16x32_bf16 v[120:123], v[164:167], v[188:191], v[120:123]
	v_mfma_f32_16x16x32_bf16 v[108:111], v[156:159], v[196:199], v[108:111]
	v_mfma_f32_16x16x32_bf16 v[104:107], v[164:167], v[196:199], v[104:107]
	v_mfma_f32_16x16x32_bf16 v[92:95], v[156:159], v[204:207], v[92:95]
	v_mfma_f32_16x16x32_bf16 v[88:91], v[164:167], v[204:207], v[88:91]
	v_mfma_f32_16x16x32_bf16 v[76:79], v[156:159], v[212:215], v[76:79]
	v_mfma_f32_16x16x32_bf16 v[72:75], v[164:167], v[212:215], v[72:75]
	v_mfma_f32_16x16x32_bf16 v[116:119], v[168:171], v[184:187], v[116:119]
	v_mfma_f32_16x16x32_bf16 v[112:115], v[176:179], v[184:187], v[112:115]
	v_mfma_f32_16x16x32_bf16 v[100:103], v[168:171], v[192:195], v[100:103]
	v_mfma_f32_16x16x32_bf16 v[96:99], v[176:179], v[192:195], v[96:99]
	v_mfma_f32_16x16x32_bf16 v[84:87], v[168:171], v[200:203], v[84:87]
	v_mfma_f32_16x16x32_bf16 v[80:83], v[176:179], v[200:203], v[80:83]
	v_mfma_f32_16x16x32_bf16 v[68:71], v[168:171], v[208:211], v[68:71]
	v_mfma_f32_16x16x32_bf16 v[64:67], v[176:179], v[208:211], v[64:67]
	v_mfma_f32_16x16x32_bf16 v[116:119], v[172:175], v[188:191], v[116:119]
	v_mfma_f32_16x16x32_bf16 v[112:115], v[180:183], v[188:191], v[112:115]
	v_mfma_f32_16x16x32_bf16 v[100:103], v[172:175], v[196:199], v[100:103]
	v_mfma_f32_16x16x32_bf16 v[96:99], v[180:183], v[196:199], v[96:99]
	v_mfma_f32_16x16x32_bf16 v[84:87], v[172:175], v[204:207], v[84:87]
	v_mfma_f32_16x16x32_bf16 v[80:83], v[180:183], v[204:207], v[80:83]
	v_mfma_f32_16x16x32_bf16 v[68:71], v[172:175], v[212:215], v[68:71]
	v_mfma_f32_16x16x32_bf16 v[64:67], v[180:183], v[212:215], v[64:67]
	s_setprio 0
	s_barrier
	s_add_i32 s44, s70, s52
	s_add_u32 s42, s42, 0x80
	s_addc_u32 s43, s43, 0
	s_mov_b32 m0, s44
	ds_read_b128 v[184:187], v151 offset:49152
	ds_read_b128 v[188:191], v151 offset:50176
	ds_read_b128 v[192:195], v151 offset:51200
	ds_read_b128 v[196:199], v151 offset:52224
	ds_read_b128 v[200:203], v151 offset:53248
	ds_read_b128 v[204:207], v151 offset:54272
	ds_read_b128 v[208:211], v151 offset:55296
	ds_read_b128 v[212:215], v151 offset:56320
	global_load_lds_dwordx4 v130, s[42:43]
	s_add_i32 m0, s44, 0x2000
	s_add_i32 s44, s71, s52
	global_load_lds_dwordx4 v134, s[42:43]
	s_add_u32 s42, s42, 0x80000
	s_addc_u32 s43, s43, 0
	s_mov_b32 m0, s44
	s_nop 0
	global_load_lds_dwordx4 v130, s[42:43]
	s_add_i32 m0, s44, 0x2000
	s_nop 0
	global_load_lds_dwordx4 v134, s[42:43]
	s_mov_b32 m0, s59
	s_nop 0
	global_load_lds_dwordx4 v128, s[100:101]
	s_mov_b32 m0, s60
	s_nop 0
	global_load_lds_dwordx4 v132, s[100:101]
	s_waitcnt vmcnt(8)
	s_waitcnt lgkmcnt(0)
	s_barrier
	s_setprio 1
	s_waitcnt lgkmcnt(0)
	v_mfma_f32_16x16x32_bf16 v[60:63], v[152:155], v[184:187], v[60:63]
	v_mfma_f32_16x16x32_bf16 v[56:59], v[160:163], v[184:187], v[56:59]
	v_mfma_f32_16x16x32_bf16 v[44:47], v[152:155], v[192:195], v[44:47]
	v_mfma_f32_16x16x32_bf16 v[40:43], v[160:163], v[192:195], v[40:43]
	v_mfma_f32_16x16x32_bf16 v[28:31], v[152:155], v[200:203], v[28:31]
	v_mfma_f32_16x16x32_bf16 v[24:27], v[160:163], v[200:203], v[24:27]
	v_mfma_f32_16x16x32_bf16 v[12:15], v[152:155], v[208:211], v[12:15]
	v_mfma_f32_16x16x32_bf16 v[8:11], v[160:163], v[208:211], v[8:11]
	v_mfma_f32_16x16x32_bf16 v[60:63], v[156:159], v[188:191], v[60:63]
	v_mfma_f32_16x16x32_bf16 v[56:59], v[164:167], v[188:191], v[56:59]
	v_mfma_f32_16x16x32_bf16 v[44:47], v[156:159], v[196:199], v[44:47]
	v_mfma_f32_16x16x32_bf16 v[40:43], v[164:167], v[196:199], v[40:43]
	v_mfma_f32_16x16x32_bf16 v[28:31], v[156:159], v[204:207], v[28:31]
	v_mfma_f32_16x16x32_bf16 v[24:27], v[164:167], v[204:207], v[24:27]
	v_mfma_f32_16x16x32_bf16 v[12:15], v[156:159], v[212:215], v[12:15]
	v_mfma_f32_16x16x32_bf16 v[8:11], v[164:167], v[212:215], v[8:11]
	v_mfma_f32_16x16x32_bf16 v[52:55], v[168:171], v[184:187], v[52:55]
	v_mfma_f32_16x16x32_bf16 v[48:51], v[176:179], v[184:187], v[48:51]
	v_mfma_f32_16x16x32_bf16 v[36:39], v[168:171], v[192:195], v[36:39]
	v_mfma_f32_16x16x32_bf16 v[32:35], v[176:179], v[192:195], v[32:35]
	v_mfma_f32_16x16x32_bf16 v[20:23], v[168:171], v[200:203], v[20:23]
	v_mfma_f32_16x16x32_bf16 v[16:19], v[176:179], v[200:203], v[16:19]
	v_mfma_f32_16x16x32_bf16 v[4:7], v[168:171], v[208:211], v[4:7]
	v_mfma_f32_16x16x32_bf16 v[0:3], v[176:179], v[208:211], v[0:3]
	v_mfma_f32_16x16x32_bf16 v[52:55], v[172:175], v[188:191], v[52:55]
	v_mfma_f32_16x16x32_bf16 v[48:51], v[180:183], v[188:191], v[48:51]
	v_mfma_f32_16x16x32_bf16 v[36:39], v[172:175], v[196:199], v[36:39]
	v_mfma_f32_16x16x32_bf16 v[32:35], v[180:183], v[196:199], v[32:35]
	v_mfma_f32_16x16x32_bf16 v[20:23], v[172:175], v[204:207], v[20:23]
	v_mfma_f32_16x16x32_bf16 v[16:19], v[180:183], v[204:207], v[16:19]
	v_mfma_f32_16x16x32_bf16 v[4:7], v[172:175], v[212:215], v[4:7]
	v_mfma_f32_16x16x32_bf16 v[0:3], v[180:183], v[212:215], v[0:3]
	s_setprio 0
	s_barrier
	s_add_i32 s69, s69, 2
	s_add_u32 s67, s67, 0x100
	s_addc_u32 s68, s68, 0
	s_add_u32 s40, s40, 0x100
	s_addc_u32 s41, s41, 0
	s_cmp_gt_u32 s69, 29
	s_cbranch_scc0 .LBB0_781
	s_and_b64 vcc, exec, s[10:11]
	s_cbranch_vccz .LBB0_784
	s_barrier

; #define PG8_STAGE(bufoff, gbase, voff) do { _Pragma("unroll") for (int _i = 0; _i < 2; ++_i) \
;         __builtin_amdgcn_global_load_lds((const unsigned*)((const char*)(gbase) + (voff)[_i]), (LAS unsigned*)(lds + (bufoff) + ldsw + _i * 8192), 16, 0, 0); } while (0)
; #define PG8_LDA(dst, b, h) do { _Pragma("unroll") for (int m = 0; m < 4; ++m) _Pragma("unroll") for (int k = 0; k < 2; ++k) dst[m][k] = *(const LAS bf16x8*)(lds + PG8_SA(b, h) + aoff + m * 2048 + k * 1024); } while (0)
; #define PG8_LDB(dst, b, h) do { _Pragma("unroll") for (int n = 0; n < 2; ++n) _Pragma("unroll") for (int k = 0; k < 2; ++k) dst[n][k] = *(const LAS bf16x8*)(lds + PG8_SB(b, h) + boff + n * 2048 + k * 1024); } while (0)
; #define PG8_MMA(ai, bj, At, Bt) do { __builtin_amdgcn_s_setprio(1); _Pragma("unroll") for (int m = 0; m < 4; ++m) _Pragma("unroll") for (int n = 0; n < 2; ++n) _Pragma("unroll") for (int k = 0; k < 2; ++k) \
;         acc[ai][bj][m][n] = __builtin_amdgcn_mfma_f32_16x16x32_bf16(Bt[n][k], At[m][k], acc[ai][bj][m][n], 0, 0, 0); __builtin_amdgcn_s_setprio(0); } while (0)
; #define PG8_WAIT_V(n) asm volatile("s_waitcnt vmcnt(" #n ")" ::: "memory")
; #define PG8_WAIT_L(n) asm volatile("s_waitcnt lgkmcnt(" #n ")" ::: "memory")
; #define PG8_BAR __builtin_amdgcn_s_barrier()
; #define PG8_SCHED __builtin_amdgcn_sched_barrier(0)
; template <class Epi>
; __device__ __forceinline__ void gemm_phase(ldsp lds, const Gemm g, const StaticOrder& S, const Epi& E, int wave0) {
;     ...
;             const bool last = (t == nt - 2);
;             const char* a1 = cA + (size_t)(t + 1) * kstep;
;             const char* a2 = last ? nA : cA + (size_t)(t + 2) * kstep; const char* b2 = last ? nB : cB + (size_t)(t + 2) * kstep;
;             const char* a3 = a2 + kstep; const char* b3 = b2 + kstep;
;             PG8_LDB(B0, 0, 0); PG8_LDB(B1, 0, 1); PG8_SCHED; PG8_LDA(At, 0, 0); PG8_STAGE(PG8_SA(1, 1), a1 + hstep, voffA);
;             PG8_WAIT_V(8); PG8_WAIT_L(0); PG8_BAR; PG8_MMA(0, 0, At, B0); PG8_MMA(0, 1, At, B1); PG8_BAR; PG8_SCHED;
;             PG8_LDA(At, 0, 1); PG8_STAGE(PG8_SB(0, 0), b2, voffB); PG8_STAGE(PG8_SB(0, 1), b2 + hstep, voffB); PG8_STAGE(PG8_SA(0, 0), a2, voffA);
;             PG8_WAIT_V(8); PG8_WAIT_L(0); PG8_BAR; PG8_MMA(1, 0, At, B0); PG8_MMA(1, 1, At, B1); PG8_BAR; PG8_SCHED;
.LBB0_961:
	ds_read_b128 v[152:155], v149
	ds_read_b128 v[156:159], v149 offset:1024
	ds_read_b128 v[160:163], v149 offset:2048
	ds_read_b128 v[164:167], v149 offset:3072
	ds_read_b128 v[168:171], v150
	ds_read_b128 v[172:175], v150 offset:1024
	ds_read_b128 v[176:179], v150 offset:2048
	ds_read_b128 v[180:183], v150 offset:3072
	s_add_u32 s36, s34, 0x100
	s_addc_u32 s37, s35, 0
	s_cmpk_eq_i32 s67, 0x54
	s_cselect_b32 s41, s5, s37
	s_cselect_b32 s40, s4, s36
	s_cselect_b32 s39, s31, s66
	s_cselect_b32 s38, s30, s65
	s_add_i32 m0, s49, 0xc000
	ds_read_b128 v[184:187], v151
	ds_read_b128 v[188:191], v151 offset:1024
	ds_read_b128 v[192:195], v151 offset:2048
	ds_read_b128 v[196:199], v151 offset:3072
	ds_read_b128 v[200:203], v151 offset:4096
	ds_read_b128 v[204:207], v151 offset:5120
	ds_read_b128 v[208:211], v151 offset:6144
	ds_read_b128 v[212:215], v151 offset:7168
	global_load_lds_dwordx4 v138, s[34:35]
	s_add_i32 m0, s49, 0xe000
	s_nop 0
	global_load_lds_dwordx4 v136, s[34:35]
	s_waitcnt vmcnt(8)
	s_waitcnt lgkmcnt(0)
	s_barrier
	s_setprio 1
	s_waitcnt lgkmcnt(0)
	v_mfma_f32_16x16x32_bf16 v[124:127], v[152:155], v[184:187], v[124:127]
	v_mfma_f32_16x16x32_bf16 v[120:123], v[160:163], v[184:187], v[120:123]
	v_mfma_f32_16x16x32_bf16 v[108:111], v[152:155], v[192:195], v[108:111]
	v_mfma_f32_16x16x32_bf16 v[104:107], v[160:163], v[192:195], v[104:107]
	v_mfma_f32_16x16x32_bf16 v[92:95], v[152:155], v[200:203], v[92:95]
	v_mfma_f32_16x16x32_bf16 v[88:91], v[160:163], v[200:203], v[88:91]
	v_mfma_f32_16x16x32_bf16 v[76:79], v[152:155], v[208:211], v[76:79]
	v_mfma_f32_16x16x32_bf16 v[72:75], v[160:163], v[208:211], v[72:75]
	v_mfma_f32_16x16x32_bf16 v[124:127], v[156:159], v[188:191], v[124:127]
	v_mfma_f32_16x16x32_bf16 v[120:123], v[164:167], v[188:191], v[120:123]
	v_mfma_f32_16x16x32_bf16 v[108:111], v[156:159], v[196:199], v[108:111]
	v_mfma_f32_16x16x32_bf16 v[104:107], v[164:167], v[196:199], v[104:107]
	v_mfma_f32_16x16x32_bf16 v[92:95], v[156:159], v[204:207], v[92:95]
	v_mfma_f32_16x16x32_bf16 v[88:91], v[164:167], v[204:207], v[88:91]
	v_mfma_f32_16x16x32_bf16 v[76:79], v[156:159], v[212:215], v[76:79]
	v_mfma_f32_16x16x32_bf16 v[72:75], v[164:167], v[212:215], v[72:75]
	v_mfma_f32_16x16x32_bf16 v[116:119], v[168:171], v[184:187], v[116:119]
	v_mfma_f32_16x16x32_bf16 v[112:115], v[176:179], v[184:187], v[112:115]
	v_mfma_f32_16x16x32_bf16 v[100:103], v[168:171], v[192:195], v[100:103]
	v_mfma_f32_16x16x32_bf16 v[96:99], v[176:179], v[192:195], v[96:99]
	v_mfma_f32_16x16x32_bf16 v[84:87], v[168:171], v[200:203], v[84:87]
	v_mfma_f32_16x16x32_bf16 v[80:83], v[176:179], v[200:203], v[80:83]
	v_mfma_f32_16x16x32_bf16 v[68:71], v[168:171], v[208:211], v[68:71]
	v_mfma_f32_16x16x32_bf16 v[64:67], v[176:179], v[208:211], v[64:67]
	v_mfma_f32_16x16x32_bf16 v[116:119], v[172:175], v[188:191], v[116:119]
	v_mfma_f32_16x16x32_bf16 v[112:115], v[180:183], v[188:191], v[112:115]
	v_mfma_f32_16x16x32_bf16 v[100:103], v[172:175], v[196:199], v[100:103]
	v_mfma_f32_16x16x32_bf16 v[96:99], v[180:183], v[196:199], v[96:99]
	v_mfma_f32_16x16x32_bf16 v[84:87], v[172:175], v[204:207], v[84:87]
	v_mfma_f32_16x16x32_bf16 v[80:83], v[180:183], v[204:207], v[80:83]
	v_mfma_f32_16x16x32_bf16 v[68:71], v[172:175], v[212:215], v[68:71]
	v_mfma_f32_16x16x32_bf16 v[64:67], v[180:183], v[212:215], v[64:67]
	s_setprio 0
	s_barrier
	s_add_i32 s34, s59, s48
	s_mov_b32 m0, s34
	ds_read_b128 v[184:187], v151 offset:16384
	ds_read_b128 v[188:191], v151 offset:17408
	ds_read_b128 v[192:195], v151 offset:18432
	ds_read_b128 v[196:199], v151 offset:19456
	ds_read_b128 v[200:203], v151 offset:20480
	ds_read_b128 v[204:207], v151 offset:21504
	ds_read_b128 v[208:211], v151 offset:22528
	ds_read_b128 v[212:215], v151 offset:23552
	global_load_lds_dwordx4 v130, s[38:39]
	s_add_i32 m0, s34, 0x2000
	s_add_u32 s34, s38, 0x160000
	s_addc_u32 s35, s39, 0
	s_add_i32 s68, s60, s48
	global_load_lds_dwordx4 v134, s[38:39]
	s_mov_b32 m0, s68
	s_nop 0
	global_load_lds_dwordx4 v130, s[34:35]
	s_add_i32 m0, s68, 0x2000
	s_nop 0
	global_load_lds_dwordx4 v134, s[34:35]
	s_mov_b32 m0, s49
	s_nop 0
	global_load_lds_dwordx4 v128, s[40:41]
	s_mov_b32 m0, s50
	s_nop 0
	global_load_lds_dwordx4 v132, s[40:41]
	s_waitcnt vmcnt(8)
	s_waitcnt lgkmcnt(0)
	s_barrier
	s_setprio 1
	s_waitcnt lgkmcnt(0)
	v_mfma_f32_16x16x32_bf16 v[60:63], v[152:155], v[184:187], v[60:63]
	v_mfma_f32_16x16x32_bf16 v[56:59], v[160:163], v[184:187], v[56:59]
	v_mfma_f32_16x16x32_bf16 v[44:47], v[152:155], v[192:195], v[44:47]
	v_mfma_f32_16x16x32_bf16 v[40:43], v[160:163], v[192:195], v[40:43]
	v_mfma_f32_16x16x32_bf16 v[28:31], v[152:155], v[200:203], v[28:31]
	v_mfma_f32_16x16x32_bf16 v[24:27], v[160:163], v[200:203], v[24:27]
	v_mfma_f32_16x16x32_bf16 v[12:15], v[152:155], v[208:211], v[12:15]
	v_mfma_f32_16x16x32_bf16 v[8:11], v[160:163], v[208:211], v[8:11]
	v_mfma_f32_16x16x32_bf16 v[60:63], v[156:159], v[188:191], v[60:63]
	v_mfma_f32_16x16x32_bf16 v[56:59], v[164:167], v[188:191], v[56:59]
	v_mfma_f32_16x16x32_bf16 v[44:47], v[156:159], v[196:199], v[44:47]
	v_mfma_f32_16x16x32_bf16 v[40:43], v[164:167], v[196:199], v[40:43]
	v_mfma_f32_16x16x32_bf16 v[28:31], v[156:159], v[204:207], v[28:31]
	v_mfma_f32_16x16x32_bf16 v[24:27], v[164:167], v[204:207], v[24:27]
	v_mfma_f32_16x16x32_bf16 v[12:15], v[156:159], v[212:215], v[12:15]
	v_mfma_f32_16x16x32_bf16 v[8:11], v[164:167], v[212:215], v[8:11]
	v_mfma_f32_16x16x32_bf16 v[52:55], v[168:171], v[184:187], v[52:55]
	v_mfma_f32_16x16x32_bf16 v[48:51], v[176:179], v[184:187], v[48:51]
	v_mfma_f32_16x16x32_bf16 v[36:39], v[168:171], v[192:195], v[36:39]
	v_mfma_f32_16x16x32_bf16 v[32:35], v[176:179], v[192:195], v[32:35]
	v_mfma_f32_16x16x32_bf16 v[20:23], v[168:171], v[200:203], v[20:23]
	v_mfma_f32_16x16x32_bf16 v[16:19], v[176:179], v[200:203], v[16:19]
	v_mfma_f32_16x16x32_bf16 v[4:7], v[168:171], v[208:211], v[4:7]
	v_mfma_f32_16x16x32_bf16 v[0:3], v[176:179], v[208:211], v[0:3]
	v_mfma_f32_16x16x32_bf16 v[52:55], v[172:175], v[188:191], v[52:55]
	v_mfma_f32_16x16x32_bf16 v[48:51], v[180:183], v[188:191], v[48:51]
	v_mfma_f32_16x16x32_bf16 v[36:39], v[172:175], v[196:199], v[36:39]
	v_mfma_f32_16x16x32_bf16 v[32:35], v[180:183], v[196:199], v[32:35]
	v_mfma_f32_16x16x32_bf16 v[20:23], v[172:175], v[204:207], v[20:23]
	v_mfma_f32_16x16x32_bf16 v[16:19], v[180:183], v[204:207], v[16:19]
	v_mfma_f32_16x16x32_bf16 v[4:7], v[172:175], v[212:215], v[4:7]
	v_mfma_f32_16x16x32_bf16 v[0:3], v[180:183], v[212:215], v[0:3]
	s_setprio 0
	s_barrier
; #define PG8_STAGE(bufoff, gbase, voff) do { _Pragma("unroll") for (int _i = 0; _i < 2; ++_i) \
;         __builtin_amdgcn_global_load_lds((const unsigned*)((const char*)(gbase) + (voff)[_i]), (LAS unsigned*)(lds + (bufoff) + ldsw + _i * 8192), 16, 0, 0); } while (0)
; #define PG8_LDA(dst, b, h) do { _Pragma("unroll") for (int m = 0; m < 4; ++m) _Pragma("unroll") for (int k = 0; k < 2; ++k) dst[m][k] = *(const LAS bf16x8*)(lds + PG8_SA(b, h) + aoff + m * 2048 + k * 1024); } while (0)
; #define PG8_LDB(dst, b, h) do { _Pragma("unroll") for (int n = 0; n < 2; ++n) _Pragma("unroll") for (int k = 0; k < 2; ++k) dst[n][k] = *(const LAS bf16x8*)(lds + PG8_SB(b, h) + boff + n * 2048 + k * 1024); } while (0)
; #define PG8_MMA(ai, bj, At, Bt) do { __builtin_amdgcn_s_setprio(1); _Pragma("unroll") for (int m = 0; m < 4; ++m) _Pragma("unroll") for (int n = 0; n < 2; ++n) _Pragma("unroll") for (int k = 0; k < 2; ++k) \
;         acc[ai][bj][m][n] = __builtin_amdgcn_mfma_f32_16x16x32_bf16(Bt[n][k], At[m][k], acc[ai][bj][m][n], 0, 0, 0); __builtin_amdgcn_s_setprio(0); } while (0)
; #define PG8_WAIT_V(n) asm volatile("s_waitcnt vmcnt(" #n ")" ::: "memory")
; #define PG8_WAIT_L(n) asm volatile("s_waitcnt lgkmcnt(" #n ")" ::: "memory")
; #define PG8_BAR __builtin_amdgcn_s_barrier()
; #define PG8_SCHED __builtin_amdgcn_sched_barrier(0)
; template <class Epi>
; __device__ __forceinline__ void gemm_phase(ldsp lds, const Gemm g, const StaticOrder& S, const Epi& E, int wave0) {
;     ...
;             PG8_LDB(B0, 1, 0); PG8_LDB(B1, 1, 1); PG8_SCHED; PG8_LDA(At, 1, 0); PG8_STAGE(PG8_SA(0, 1), a2 + hstep, voffA);
;             PG8_WAIT_V(8); PG8_WAIT_L(0); PG8_BAR; PG8_MMA(0, 0, At, B0); PG8_MMA(0, 1, At, B1); PG8_BAR; PG8_SCHED;
;             PG8_LDA(At, 1, 1); PG8_STAGE(PG8_SB(1, 0), b3, voffB); PG8_STAGE(PG8_SB(1, 1), b3 + hstep, voffB); PG8_STAGE(PG8_SA(1, 0), a3, voffA);
;             PG8_WAIT_V(8); PG8_WAIT_L(0); PG8_BAR; PG8_MMA(1, 0, At, B0); PG8_MMA(1, 1, At, B1); PG8_BAR; PG8_SCHED;
;         }
;         if (wr == 0) PG8_BAR;
	s_add_i32 s68, 0, 0x18000
	s_add_i32 s69, 0, 0x1c000
	v_add_u32_e32 v164, s68, v148
	v_add_u32_e32 v180, s69, v148
	ds_read_b128 v[152:155], v164
	ds_read_b128 v[156:159], v164 offset:1024
	ds_read_b128 v[160:163], v164 offset:2048
	ds_read_b128 v[164:167], v164 offset:3072
	ds_read_b128 v[168:171], v180
	ds_read_b128 v[172:175], v180 offset:1024
	ds_read_b128 v[176:179], v180 offset:2048
	ds_read_b128 v[180:183], v180 offset:3072
	s_add_u32 s34, s40, 0x160000
	s_addc_u32 s35, s41, 0
	s_mov_b32 m0, s51
	ds_read_b128 v[184:187], v151 offset:32768
	ds_read_b128 v[188:191], v151 offset:33792
	ds_read_b128 v[192:195], v151 offset:34816
	ds_read_b128 v[196:199], v151 offset:35840
	ds_read_b128 v[200:203], v151 offset:36864
	ds_read_b128 v[204:207], v151 offset:37888
	ds_read_b128 v[208:211], v151 offset:38912
	ds_read_b128 v[212:215], v151 offset:39936
	global_load_lds_dwordx4 v128, s[34:35]
	s_mov_b32 m0, s52
	s_nop 0
	global_load_lds_dwordx4 v132, s[34:35]
	s_waitcnt vmcnt(8)
	s_waitcnt lgkmcnt(0)
	s_barrier
	s_setprio 1
	s_waitcnt lgkmcnt(0)
	v_mfma_f32_16x16x32_bf16 v[124:127], v[152:155], v[184:187], v[124:127]
	v_mfma_f32_16x16x32_bf16 v[120:123], v[160:163], v[184:187], v[120:123]
	v_mfma_f32_16x16x32_bf16 v[108:111], v[152:155], v[192:195], v[108:111]
	v_mfma_f32_16x16x32_bf16 v[104:107], v[160:163], v[192:195], v[104:107]
	v_mfma_f32_16x16x32_bf16 v[92:95], v[152:155], v[200:203], v[92:95]
	v_mfma_f32_16x16x32_bf16 v[88:91], v[160:163], v[200:203], v[88:91]
	v_mfma_f32_16x16x32_bf16 v[76:79], v[152:155], v[208:211], v[76:79]
	v_mfma_f32_16x16x32_bf16 v[72:75], v[160:163], v[208:211], v[72:75]
	v_mfma_f32_16x16x32_bf16 v[124:127], v[156:159], v[188:191], v[124:127]
	v_mfma_f32_16x16x32_bf16 v[120:123], v[164:167], v[188:191], v[120:123]
	v_mfma_f32_16x16x32_bf16 v[108:111], v[156:159], v[196:199], v[108:111]
	v_mfma_f32_16x16x32_bf16 v[104:107], v[164:167], v[196:199], v[104:107]
	v_mfma_f32_16x16x32_bf16 v[92:95], v[156:159], v[204:207], v[92:95]
	v_mfma_f32_16x16x32_bf16 v[88:91], v[164:167], v[204:207], v[88:91]
	v_mfma_f32_16x16x32_bf16 v[76:79], v[156:159], v[212:215], v[76:79]
	v_mfma_f32_16x16x32_bf16 v[72:75], v[164:167], v[212:215], v[72:75]
	v_mfma_f32_16x16x32_bf16 v[116:119], v[168:171], v[184:187], v[116:119]
	v_mfma_f32_16x16x32_bf16 v[112:115], v[176:179], v[184:187], v[112:115]
	v_mfma_f32_16x16x32_bf16 v[100:103], v[168:171], v[192:195], v[100:103]
	v_mfma_f32_16x16x32_bf16 v[96:99], v[176:179], v[192:195], v[96:99]
	v_mfma_f32_16x16x32_bf16 v[84:87], v[168:171], v[200:203], v[84:87]
	v_mfma_f32_16x16x32_bf16 v[80:83], v[176:179], v[200:203], v[80:83]
	v_mfma_f32_16x16x32_bf16 v[68:71], v[168:171], v[208:211], v[68:71]
	v_mfma_f32_16x16x32_bf16 v[64:67], v[176:179], v[208:211], v[64:67]
	v_mfma_f32_16x16x32_bf16 v[116:119], v[172:175], v[188:191], v[116:119]
	v_mfma_f32_16x16x32_bf16 v[112:115], v[180:183], v[188:191], v[112:115]
	v_mfma_f32_16x16x32_bf16 v[100:103], v[172:175], v[196:199], v[100:103]
	v_mfma_f32_16x16x32_bf16 v[96:99], v[180:183], v[196:199], v[96:99]
	v_mfma_f32_16x16x32_bf16 v[84:87], v[172:175], v[204:207], v[84:87]
	v_mfma_f32_16x16x32_bf16 v[80:83], v[180:183], v[204:207], v[80:83]
	v_mfma_f32_16x16x32_bf16 v[68:71], v[172:175], v[212:215], v[68:71]
	v_mfma_f32_16x16x32_bf16 v[64:67], v[180:183], v[212:215], v[64:67]
	s_setprio 0
	s_barrier
	s_add_i32 s34, s68, s48
	s_add_u32 s100, s38, 0x80
	s_addc_u32 s101, s39, 0
	s_add_u32 s98, s40, 0x80
	s_addc_u32 s99, s41, 0
	s_mov_b32 m0, s34
	ds_read_b128 v[184:187], v151 offset:49152
	ds_read_b128 v[188:191], v151 offset:50176
	ds_read_b128 v[192:195], v151 offset:51200
	ds_read_b128 v[196:199], v151 offset:52224
	ds_read_b128 v[200:203], v151 offset:53248
	ds_read_b128 v[204:207], v151 offset:54272
	ds_read_b128 v[208:211], v151 offset:55296
	ds_read_b128 v[212:215], v151 offset:56320
	global_load_lds_dwordx4 v130, s[100:101]
	s_add_i32 m0, s34, 0x2000
	s_add_u32 s34, s38, 0x160080
	s_addc_u32 s35, s39, 0
	s_add_i32 s38, s69, s48
	global_load_lds_dwordx4 v134, s[100:101]
	s_mov_b32 m0, s38
	s_nop 0
	global_load_lds_dwordx4 v130, s[34:35]
	s_add_i32 m0, s38, 0x2000
	s_nop 0
	global_load_lds_dwordx4 v134, s[34:35]
	s_mov_b32 m0, s56
	s_nop 0
	global_load_lds_dwordx4 v128, s[98:99]
	s_mov_b32 m0, s57
	s_nop 0
	global_load_lds_dwordx4 v132, s[98:99]
	s_waitcnt vmcnt(8)
	s_waitcnt lgkmcnt(0)
	s_barrier
	s_setprio 1
	s_waitcnt lgkmcnt(0)
	v_mfma_f32_16x16x32_bf16 v[60:63], v[152:155], v[184:187], v[60:63]
	v_mfma_f32_16x16x32_bf16 v[56:59], v[160:163], v[184:187], v[56:59]
	v_mfma_f32_16x16x32_bf16 v[44:47], v[152:155], v[192:195], v[44:47]
	v_mfma_f32_16x16x32_bf16 v[40:43], v[160:163], v[192:195], v[40:43]
	v_mfma_f32_16x16x32_bf16 v[28:31], v[152:155], v[200:203], v[28:31]
	v_mfma_f32_16x16x32_bf16 v[24:27], v[160:163], v[200:203], v[24:27]
	v_mfma_f32_16x16x32_bf16 v[12:15], v[152:155], v[208:211], v[12:15]
	v_mfma_f32_16x16x32_bf16 v[8:11], v[160:163], v[208:211], v[8:11]
	v_mfma_f32_16x16x32_bf16 v[60:63], v[156:159], v[188:191], v[60:63]
	v_mfma_f32_16x16x32_bf16 v[56:59], v[164:167], v[188:191], v[56:59]
	v_mfma_f32_16x16x32_bf16 v[44:47], v[156:159], v[196:199], v[44:47]
	v_mfma_f32_16x16x32_bf16 v[40:43], v[164:167], v[196:199], v[40:43]
	v_mfma_f32_16x16x32_bf16 v[28:31], v[156:159], v[204:207], v[28:31]
	v_mfma_f32_16x16x32_bf16 v[24:27], v[164:167], v[204:207], v[24:27]
	v_mfma_f32_16x16x32_bf16 v[12:15], v[156:159], v[212:215], v[12:15]
	v_mfma_f32_16x16x32_bf16 v[8:11], v[164:167], v[212:215], v[8:11]
	v_mfma_f32_16x16x32_bf16 v[52:55], v[168:171], v[184:187], v[52:55]
	v_mfma_f32_16x16x32_bf16 v[48:51], v[176:179], v[184:187], v[48:51]
	v_mfma_f32_16x16x32_bf16 v[36:39], v[168:171], v[192:195], v[36:39]
	v_mfma_f32_16x16x32_bf16 v[32:35], v[176:179], v[192:195], v[32:35]
	v_mfma_f32_16x16x32_bf16 v[20:23], v[168:171], v[200:203], v[20:23]
	v_mfma_f32_16x16x32_bf16 v[16:19], v[176:179], v[200:203], v[16:19]
	v_mfma_f32_16x16x32_bf16 v[4:7], v[168:171], v[208:211], v[4:7]
	v_mfma_f32_16x16x32_bf16 v[0:3], v[176:179], v[208:211], v[0:3]
	v_mfma_f32_16x16x32_bf16 v[52:55], v[172:175], v[188:191], v[52:55]
	v_mfma_f32_16x16x32_bf16 v[48:51], v[180:183], v[188:191], v[48:51]
	v_mfma_f32_16x16x32_bf16 v[36:39], v[172:175], v[196:199], v[36:39]
	v_mfma_f32_16x16x32_bf16 v[32:35], v[180:183], v[196:199], v[32:35]
	v_mfma_f32_16x16x32_bf16 v[20:23], v[172:175], v[204:207], v[20:23]
	v_mfma_f32_16x16x32_bf16 v[16:19], v[180:183], v[204:207], v[16:19]
	v_mfma_f32_16x16x32_bf16 v[4:7], v[172:175], v[212:215], v[4:7]
	v_mfma_f32_16x16x32_bf16 v[0:3], v[180:183], v[212:215], v[0:3]
	s_setprio 0
	s_barrier
	s_add_i32 s67, s67, 2
	s_add_u32 s65, s65, 0x100
	s_addc_u32 s66, s66, 0
	s_cmpk_gt_u32 s67, 0x55
	s_mov_b64 s[34:35], s[36:37]
	s_cbranch_scc0 .LBB0_961
	s_and_b64 vcc, exec, s[12:13]
	s_cbranch_vccz .LBB0_964
	s_barrier

; #define PG8_STAGE(bufoff, gbase, voff) do { _Pragma("unroll") for (int _i = 0; _i < 2; ++_i) \
;         __builtin_amdgcn_global_load_lds((const unsigned*)((const char*)(gbase) + (voff)[_i]), (LAS unsigned*)(lds + (bufoff) + ldsw + _i * 8192), 16, 0, 0); } while (0)
; #define PG8_LDA(dst, b, h) do { _Pragma("unroll") for (int m = 0; m < 4; ++m) _Pragma("unroll") for (int k = 0; k < 2; ++k) dst[m][k] = *(const LAS bf16x8*)(lds + PG8_SA(b, h) + aoff + m * 2048 + k * 1024); } while (0)
; #define PG8_LDB(dst, b, h) do { _Pragma("unroll") for (int n = 0; n < 2; ++n) _Pragma("unroll") for (int k = 0; k < 2; ++k) dst[n][k] = *(const LAS bf16x8*)(lds + PG8_SB(b, h) + boff + n * 2048 + k * 1024); } while (0)
; #define PG8_MMA(ai, bj, At, Bt) do { __builtin_amdgcn_s_setprio(1); _Pragma("unroll") for (int m = 0; m < 4; ++m) _Pragma("unroll") for (int n = 0; n < 2; ++n) _Pragma("unroll") for (int k = 0; k < 2; ++k) \
;         acc[ai][bj][m][n] = __builtin_amdgcn_mfma_f32_16x16x32_bf16(Bt[n][k], At[m][k], acc[ai][bj][m][n], 0, 0, 0); __builtin_amdgcn_s_setprio(0); } while (0)
; #define PG8_WAIT_V(n) asm volatile("s_waitcnt vmcnt(" #n ")" ::: "memory")
; #define PG8_WAIT_L(n) asm volatile("s_waitcnt lgkmcnt(" #n ")" ::: "memory")
; #define PG8_BAR __builtin_amdgcn_s_barrier()
; #define PG8_SCHED __builtin_amdgcn_sched_barrier(0)
; template <class Epi>
; __device__ __forceinline__ void gemm_phase(ldsp lds, const Gemm g, const StaticOrder& S, const Epi& E, int wave0) {
;     ...
;             const bool last = (t == nt - 2);
;             const char* a1 = cA + (size_t)(t + 1) * kstep;
;             const char* a2 = last ? nA : cA + (size_t)(t + 2) * kstep; const char* b2 = last ? nB : cB + (size_t)(t + 2) * kstep;
;             const char* a3 = a2 + kstep; const char* b3 = b2 + kstep;
;             PG8_LDB(B0, 0, 0); PG8_LDB(B1, 0, 1); PG8_SCHED; PG8_LDA(At, 0, 0); PG8_STAGE(PG8_SA(1, 1), a1 + hstep, voffA);
;             PG8_WAIT_V(8); PG8_WAIT_L(0); PG8_BAR; PG8_MMA(0, 0, At, B0); PG8_MMA(0, 1, At, B1); PG8_BAR; PG8_SCHED;
;             PG8_LDA(At, 0, 1); PG8_STAGE(PG8_SB(0, 0), b2, voffB); PG8_STAGE(PG8_SB(0, 1), b2 + hstep, voffB); PG8_STAGE(PG8_SA(0, 0), a2, voffA);
;             PG8_WAIT_V(8); PG8_WAIT_L(0); PG8_BAR; PG8_MMA(1, 0, At, B0); PG8_MMA(1, 1, At, B1); PG8_BAR; PG8_SCHED;
.LBB0_1099:
	ds_read_b128 v[152:155], v149
	ds_read_b128 v[156:159], v149 offset:1024
	ds_read_b128 v[160:163], v149 offset:2048
	ds_read_b128 v[164:167], v149 offset:3072
	ds_read_b128 v[168:171], v150
	ds_read_b128 v[172:175], v150 offset:1024
	ds_read_b128 v[176:179], v150 offset:2048
	ds_read_b128 v[180:183], v150 offset:3072
	s_add_u32 s44, s42, 0xfff80080
	s_addc_u32 s45, s43, -1
	s_cmp_eq_u32 s69, 28
	s_cselect_b32 s47, s35, s45
	s_cselect_b32 s46, s65, s44
	s_cselect_b32 s45, s31, s68
	s_cselect_b32 s44, s66, s67
	s_add_i32 m0, s41, 0xc000
	ds_read_b128 v[184:187], v151
	ds_read_b128 v[188:191], v151 offset:1024
	ds_read_b128 v[192:195], v151 offset:2048
	ds_read_b128 v[196:199], v151 offset:3072
	ds_read_b128 v[200:203], v151 offset:4096
	ds_read_b128 v[204:207], v151 offset:5120
	ds_read_b128 v[208:211], v151 offset:6144
	ds_read_b128 v[212:215], v151 offset:7168
	global_load_lds_dwordx4 v138, s[42:43]
	s_add_i32 m0, s41, 0xe000
	s_nop 0
	global_load_lds_dwordx4 v136, s[42:43]
	s_waitcnt vmcnt(8)
	s_waitcnt lgkmcnt(0)
	s_barrier
	s_setprio 1
	s_waitcnt lgkmcnt(0)
	v_mfma_f32_16x16x32_bf16 v[124:127], v[152:155], v[184:187], v[124:127]
	v_mfma_f32_16x16x32_bf16 v[120:123], v[160:163], v[184:187], v[120:123]
	v_mfma_f32_16x16x32_bf16 v[108:111], v[152:155], v[192:195], v[108:111]
	v_mfma_f32_16x16x32_bf16 v[104:107], v[160:163], v[192:195], v[104:107]
	v_mfma_f32_16x16x32_bf16 v[92:95], v[152:155], v[200:203], v[92:95]
	v_mfma_f32_16x16x32_bf16 v[88:91], v[160:163], v[200:203], v[88:91]
	v_mfma_f32_16x16x32_bf16 v[76:79], v[152:155], v[208:211], v[76:79]
	v_mfma_f32_16x16x32_bf16 v[72:75], v[160:163], v[208:211], v[72:75]
	v_mfma_f32_16x16x32_bf16 v[124:127], v[156:159], v[188:191], v[124:127]
	v_mfma_f32_16x16x32_bf16 v[120:123], v[164:167], v[188:191], v[120:123]
	v_mfma_f32_16x16x32_bf16 v[108:111], v[156:159], v[196:199], v[108:111]
	v_mfma_f32_16x16x32_bf16 v[104:107], v[164:167], v[196:199], v[104:107]
	v_mfma_f32_16x16x32_bf16 v[92:95], v[156:159], v[204:207], v[92:95]
	v_mfma_f32_16x16x32_bf16 v[88:91], v[164:167], v[204:207], v[88:91]
	v_mfma_f32_16x16x32_bf16 v[76:79], v[156:159], v[212:215], v[76:79]
	v_mfma_f32_16x16x32_bf16 v[72:75], v[164:167], v[212:215], v[72:75]
	v_mfma_f32_16x16x32_bf16 v[116:119], v[168:171], v[184:187], v[116:119]
	v_mfma_f32_16x16x32_bf16 v[112:115], v[176:179], v[184:187], v[112:115]
	v_mfma_f32_16x16x32_bf16 v[100:103], v[168:171], v[192:195], v[100:103]
	v_mfma_f32_16x16x32_bf16 v[96:99], v[176:179], v[192:195], v[96:99]
	v_mfma_f32_16x16x32_bf16 v[84:87], v[168:171], v[200:203], v[84:87]
	v_mfma_f32_16x16x32_bf16 v[80:83], v[176:179], v[200:203], v[80:83]
	v_mfma_f32_16x16x32_bf16 v[68:71], v[168:171], v[208:211], v[68:71]
	v_mfma_f32_16x16x32_bf16 v[64:67], v[176:179], v[208:211], v[64:67]
	v_mfma_f32_16x16x32_bf16 v[116:119], v[172:175], v[188:191], v[116:119]
	v_mfma_f32_16x16x32_bf16 v[112:115], v[180:183], v[188:191], v[112:115]
	v_mfma_f32_16x16x32_bf16 v[100:103], v[172:175], v[196:199], v[100:103]
	v_mfma_f32_16x16x32_bf16 v[96:99], v[180:183], v[196:199], v[96:99]
	v_mfma_f32_16x16x32_bf16 v[84:87], v[172:175], v[204:207], v[84:87]
	v_mfma_f32_16x16x32_bf16 v[80:83], v[180:183], v[204:207], v[80:83]
	v_mfma_f32_16x16x32_bf16 v[68:71], v[172:175], v[212:215], v[68:71]
	v_mfma_f32_16x16x32_bf16 v[64:67], v[180:183], v[212:215], v[64:67]
	s_setprio 0
	s_barrier
	s_add_i32 s70, s62, s52
	s_add_u32 s100, s46, 0x80
	s_addc_u32 s101, s47, 0
	s_mov_b32 m0, s70
	ds_read_b128 v[184:187], v151 offset:16384
	ds_read_b128 v[188:191], v151 offset:17408
	ds_read_b128 v[192:195], v151 offset:18432
	ds_read_b128 v[196:199], v151 offset:19456
	ds_read_b128 v[200:203], v151 offset:20480
	ds_read_b128 v[204:207], v151 offset:21504
	ds_read_b128 v[208:211], v151 offset:22528
	ds_read_b128 v[212:215], v151 offset:23552
	global_load_lds_dwordx4 v130, s[44:45]
	s_add_i32 m0, s70, 0x2000
	s_add_u32 s70, s44, 0x80000
	s_addc_u32 s71, s45, 0
	s_add_i32 s72, s63, s52
	global_load_lds_dwordx4 v134, s[44:45]
	s_mov_b32 m0, s72
	s_nop 0
	global_load_lds_dwordx4 v130, s[70:71]
	s_add_i32 m0, s72, 0x2000
	s_nop 0
	global_load_lds_dwordx4 v134, s[70:71]
	s_mov_b32 m0, s41
	s_nop 0
	global_load_lds_dwordx4 v128, s[46:47]
	s_mov_b32 m0, s53
	s_nop 0
	global_load_lds_dwordx4 v132, s[46:47]
	s_waitcnt vmcnt(8)
	s_waitcnt lgkmcnt(0)
	s_barrier
	s_setprio 1
	s_waitcnt lgkmcnt(0)
	v_mfma_f32_16x16x32_bf16 v[60:63], v[152:155], v[184:187], v[60:63]
	v_mfma_f32_16x16x32_bf16 v[56:59], v[160:163], v[184:187], v[56:59]
	v_mfma_f32_16x16x32_bf16 v[44:47], v[152:155], v[192:195], v[44:47]
	v_mfma_f32_16x16x32_bf16 v[40:43], v[160:163], v[192:195], v[40:43]
	v_mfma_f32_16x16x32_bf16 v[28:31], v[152:155], v[200:203], v[28:31]
	v_mfma_f32_16x16x32_bf16 v[24:27], v[160:163], v[200:203], v[24:27]
	v_mfma_f32_16x16x32_bf16 v[12:15], v[152:155], v[208:211], v[12:15]
	v_mfma_f32_16x16x32_bf16 v[8:11], v[160:163], v[208:211], v[8:11]
	v_mfma_f32_16x16x32_bf16 v[60:63], v[156:159], v[188:191], v[60:63]
	v_mfma_f32_16x16x32_bf16 v[56:59], v[164:167], v[188:191], v[56:59]
	v_mfma_f32_16x16x32_bf16 v[44:47], v[156:159], v[196:199], v[44:47]
	v_mfma_f32_16x16x32_bf16 v[40:43], v[164:167], v[196:199], v[40:43]
	v_mfma_f32_16x16x32_bf16 v[28:31], v[156:159], v[204:207], v[28:31]
	v_mfma_f32_16x16x32_bf16 v[24:27], v[164:167], v[204:207], v[24:27]
	v_mfma_f32_16x16x32_bf16 v[12:15], v[156:159], v[212:215], v[12:15]
	v_mfma_f32_16x16x32_bf16 v[8:11], v[164:167], v[212:215], v[8:11]
	v_mfma_f32_16x16x32_bf16 v[52:55], v[168:171], v[184:187], v[52:55]
	v_mfma_f32_16x16x32_bf16 v[48:51], v[176:179], v[184:187], v[48:51]
	v_mfma_f32_16x16x32_bf16 v[36:39], v[168:171], v[192:195], v[36:39]
	v_mfma_f32_16x16x32_bf16 v[32:35], v[176:179], v[192:195], v[32:35]
	v_mfma_f32_16x16x32_bf16 v[20:23], v[168:171], v[200:203], v[20:23]
	v_mfma_f32_16x16x32_bf16 v[16:19], v[176:179], v[200:203], v[16:19]
	v_mfma_f32_16x16x32_bf16 v[4:7], v[168:171], v[208:211], v[4:7]
	v_mfma_f32_16x16x32_bf16 v[0:3], v[176:179], v[208:211], v[0:3]
	v_mfma_f32_16x16x32_bf16 v[52:55], v[172:175], v[188:191], v[52:55]
	v_mfma_f32_16x16x32_bf16 v[48:51], v[180:183], v[188:191], v[48:51]
	v_mfma_f32_16x16x32_bf16 v[36:39], v[172:175], v[196:199], v[36:39]
	v_mfma_f32_16x16x32_bf16 v[32:35], v[180:183], v[196:199], v[32:35]
	v_mfma_f32_16x16x32_bf16 v[20:23], v[172:175], v[204:207], v[20:23]
	v_mfma_f32_16x16x32_bf16 v[16:19], v[180:183], v[204:207], v[16:19]
	v_mfma_f32_16x16x32_bf16 v[4:7], v[172:175], v[212:215], v[4:7]
	v_mfma_f32_16x16x32_bf16 v[0:3], v[180:183], v[212:215], v[0:3]
	s_setprio 0
	s_barrier
; #define PG8_STAGE(bufoff, gbase, voff) do { _Pragma("unroll") for (int _i = 0; _i < 2; ++_i) \
;         __builtin_amdgcn_global_load_lds((const unsigned*)((const char*)(gbase) + (voff)[_i]), (LAS unsigned*)(lds + (bufoff) + ldsw + _i * 8192), 16, 0, 0); } while (0)
; #define PG8_LDA(dst, b, h) do { _Pragma("unroll") for (int m = 0; m < 4; ++m) _Pragma("unroll") for (int k = 0; k < 2; ++k) dst[m][k] = *(const LAS bf16x8*)(lds + PG8_SA(b, h) + aoff + m * 2048 + k * 1024); } while (0)
; #define PG8_LDB(dst, b, h) do { _Pragma("unroll") for (int n = 0; n < 2; ++n) _Pragma("unroll") for (int k = 0; k < 2; ++k) dst[n][k] = *(const LAS bf16x8*)(lds + PG8_SB(b, h) + boff + n * 2048 + k * 1024); } while (0)
; #define PG8_MMA(ai, bj, At, Bt) do { __builtin_amdgcn_s_setprio(1); _Pragma("unroll") for (int m = 0; m < 4; ++m) _Pragma("unroll") for (int n = 0; n < 2; ++n) _Pragma("unroll") for (int k = 0; k < 2; ++k) \
;         acc[ai][bj][m][n] = __builtin_amdgcn_mfma_f32_16x16x32_bf16(Bt[n][k], At[m][k], acc[ai][bj][m][n], 0, 0, 0); __builtin_amdgcn_s_setprio(0); } while (0)
; #define PG8_WAIT_V(n) asm volatile("s_waitcnt vmcnt(" #n ")" ::: "memory")
; #define PG8_WAIT_L(n) asm volatile("s_waitcnt lgkmcnt(" #n ")" ::: "memory")
; #define PG8_BAR __builtin_amdgcn_s_barrier()
; #define PG8_SCHED __builtin_amdgcn_sched_barrier(0)
; template <class Epi>
; __device__ __forceinline__ void gemm_phase(ldsp lds, const Gemm g, const StaticOrder& S, const Epi& E, int wave0) {
;     ...
;             PG8_LDB(B0, 1, 0); PG8_LDB(B1, 1, 1); PG8_SCHED; PG8_LDA(At, 1, 0); PG8_STAGE(PG8_SA(0, 1), a2 + hstep, voffA);
;             PG8_WAIT_V(8); PG8_WAIT_L(0); PG8_BAR; PG8_MMA(0, 0, At, B0); PG8_MMA(0, 1, At, B1); PG8_BAR; PG8_SCHED;
;             PG8_LDA(At, 1, 1); PG8_STAGE(PG8_SB(1, 0), b3, voffB); PG8_STAGE(PG8_SB(1, 1), b3 + hstep, voffB); PG8_STAGE(PG8_SA(1, 0), a3, voffA);
;             PG8_WAIT_V(8); PG8_WAIT_L(0); PG8_BAR; PG8_MMA(1, 0, At, B0); PG8_MMA(1, 1, At, B1); PG8_BAR; PG8_SCHED;
;         }
;         if (wr == 0) PG8_BAR;
	s_add_i32 s70, 0, 0x18000
	s_add_i32 s71, 0, 0x1c000
	v_add_u32_e32 v164, s70, v148
	v_add_u32_e32 v180, s71, v148
	ds_read_b128 v[152:155], v164
	ds_read_b128 v[156:159], v164 offset:1024
	ds_read_b128 v[160:163], v164 offset:2048
	ds_read_b128 v[164:167], v164 offset:3072
	ds_read_b128 v[168:171], v180
	ds_read_b128 v[172:175], v180 offset:1024
	ds_read_b128 v[176:179], v180 offset:2048
	ds_read_b128 v[180:183], v180 offset:3072
	s_add_u32 s46, s46, 0x80000
	s_addc_u32 s47, s47, 0
	s_mov_b32 m0, s54
	ds_read_b128 v[184:187], v151 offset:32768
	ds_read_b128 v[188:191], v151 offset:33792
	ds_read_b128 v[192:195], v151 offset:34816
	ds_read_b128 v[196:199], v151 offset:35840
	ds_read_b128 v[200:203], v151 offset:36864
	ds_read_b128 v[204:207], v151 offset:37888
	ds_read_b128 v[208:211], v151 offset:38912
	ds_read_b128 v[212:215], v151 offset:39936
	global_load_lds_dwordx4 v128, s[46:47]
	s_mov_b32 m0, s55
	s_nop 0
	global_load_lds_dwordx4 v132, s[46:47]
	s_waitcnt vmcnt(8)
	s_waitcnt lgkmcnt(0)
	s_barrier
	s_setprio 1
	s_waitcnt lgkmcnt(0)
	v_mfma_f32_16x16x32_bf16 v[124:127], v[152:155], v[184:187], v[124:127]
	v_mfma_f32_16x16x32_bf16 v[120:123], v[160:163], v[184:187], v[120:123]
	v_mfma_f32_16x16x32_bf16 v[108:111], v[152:155], v[192:195], v[108:111]
	v_mfma_f32_16x16x32_bf16 v[104:107], v[160:163], v[192:195], v[104:107]
	v_mfma_f32_16x16x32_bf16 v[92:95], v[152:155], v[200:203], v[92:95]
	v_mfma_f32_16x16x32_bf16 v[88:91], v[160:163], v[200:203], v[88:91]
	v_mfma_f32_16x16x32_bf16 v[76:79], v[152:155], v[208:211], v[76:79]
	v_mfma_f32_16x16x32_bf16 v[72:75], v[160:163], v[208:211], v[72:75]
	v_mfma_f32_16x16x32_bf16 v[124:127], v[156:159], v[188:191], v[124:127]
	v_mfma_f32_16x16x32_bf16 v[120:123], v[164:167], v[188:191], v[120:123]
	v_mfma_f32_16x16x32_bf16 v[108:111], v[156:159], v[196:199], v[108:111]
	v_mfma_f32_16x16x32_bf16 v[104:107], v[164:167], v[196:199], v[104:107]
	v_mfma_f32_16x16x32_bf16 v[92:95], v[156:159], v[204:207], v[92:95]
	v_mfma_f32_16x16x32_bf16 v[88:91], v[164:167], v[204:207], v[88:91]
	v_mfma_f32_16x16x32_bf16 v[76:79], v[156:159], v[212:215], v[76:79]
	v_mfma_f32_16x16x32_bf16 v[72:75], v[164:167], v[212:215], v[72:75]
	v_mfma_f32_16x16x32_bf16 v[116:119], v[168:171], v[184:187], v[116:119]
	v_mfma_f32_16x16x32_bf16 v[112:115], v[176:179], v[184:187], v[112:115]
	v_mfma_f32_16x16x32_bf16 v[100:103], v[168:171], v[192:195], v[100:103]
	v_mfma_f32_16x16x32_bf16 v[96:99], v[176:179], v[192:195], v[96:99]
	v_mfma_f32_16x16x32_bf16 v[84:87], v[168:171], v[200:203], v[84:87]
	v_mfma_f32_16x16x32_bf16 v[80:83], v[176:179], v[200:203], v[80:83]
	v_mfma_f32_16x16x32_bf16 v[68:71], v[168:171], v[208:211], v[68:71]
	v_mfma_f32_16x16x32_bf16 v[64:67], v[176:179], v[208:211], v[64:67]
	v_mfma_f32_16x16x32_bf16 v[116:119], v[172:175], v[188:191], v[116:119]
	v_mfma_f32_16x16x32_bf16 v[112:115], v[180:183], v[188:191], v[112:115]
	v_mfma_f32_16x16x32_bf16 v[100:103], v[172:175], v[196:199], v[100:103]
	v_mfma_f32_16x16x32_bf16 v[96:99], v[180:183], v[196:199], v[96:99]
	v_mfma_f32_16x16x32_bf16 v[84:87], v[172:175], v[204:207], v[84:87]
	v_mfma_f32_16x16x32_bf16 v[80:83], v[180:183], v[204:207], v[80:83]
	v_mfma_f32_16x16x32_bf16 v[68:71], v[172:175], v[212:215], v[68:71]
	v_mfma_f32_16x16x32_bf16 v[64:67], v[180:183], v[212:215], v[64:67]
	s_setprio 0
	s_barrier
	s_add_i32 s46, s70, s52
	s_add_u32 s44, s44, 0x80
	s_addc_u32 s45, s45, 0
	s_mov_b32 m0, s46
	ds_read_b128 v[184:187], v151 offset:49152
	ds_read_b128 v[188:191], v151 offset:50176
	ds_read_b128 v[192:195], v151 offset:51200
	ds_read_b128 v[196:199], v151 offset:52224
	ds_read_b128 v[200:203], v151 offset:53248
	ds_read_b128 v[204:207], v151 offset:54272
	ds_read_b128 v[208:211], v151 offset:55296
	ds_read_b128 v[212:215], v151 offset:56320
	global_load_lds_dwordx4 v130, s[44:45]
	s_add_i32 m0, s46, 0x2000
	s_add_i32 s46, s71, s52
	global_load_lds_dwordx4 v134, s[44:45]
	s_add_u32 s44, s44, 0x80000
	s_addc_u32 s45, s45, 0
	s_mov_b32 m0, s46
	s_nop 0
	global_load_lds_dwordx4 v130, s[44:45]
	s_add_i32 m0, s46, 0x2000
	s_nop 0
	global_load_lds_dwordx4 v134, s[44:45]
	s_mov_b32 m0, s59
	s_nop 0
	global_load_lds_dwordx4 v128, s[100:101]
	s_mov_b32 m0, s60
	s_nop 0
	global_load_lds_dwordx4 v132, s[100:101]
	s_waitcnt vmcnt(8)
	s_waitcnt lgkmcnt(0)
	s_barrier
	s_setprio 1
	s_waitcnt lgkmcnt(0)
	v_mfma_f32_16x16x32_bf16 v[60:63], v[152:155], v[184:187], v[60:63]
	v_mfma_f32_16x16x32_bf16 v[56:59], v[160:163], v[184:187], v[56:59]
	v_mfma_f32_16x16x32_bf16 v[44:47], v[152:155], v[192:195], v[44:47]
	v_mfma_f32_16x16x32_bf16 v[40:43], v[160:163], v[192:195], v[40:43]
	v_mfma_f32_16x16x32_bf16 v[28:31], v[152:155], v[200:203], v[28:31]
	v_mfma_f32_16x16x32_bf16 v[24:27], v[160:163], v[200:203], v[24:27]
	v_mfma_f32_16x16x32_bf16 v[12:15], v[152:155], v[208:211], v[12:15]
	v_mfma_f32_16x16x32_bf16 v[8:11], v[160:163], v[208:211], v[8:11]
	v_mfma_f32_16x16x32_bf16 v[60:63], v[156:159], v[188:191], v[60:63]
	v_mfma_f32_16x16x32_bf16 v[56:59], v[164:167], v[188:191], v[56:59]
	v_mfma_f32_16x16x32_bf16 v[44:47], v[156:159], v[196:199], v[44:47]
	v_mfma_f32_16x16x32_bf16 v[40:43], v[164:167], v[196:199], v[40:43]
	v_mfma_f32_16x16x32_bf16 v[28:31], v[156:159], v[204:207], v[28:31]
	v_mfma_f32_16x16x32_bf16 v[24:27], v[164:167], v[204:207], v[24:27]
	v_mfma_f32_16x16x32_bf16 v[12:15], v[156:159], v[212:215], v[12:15]
	v_mfma_f32_16x16x32_bf16 v[8:11], v[164:167], v[212:215], v[8:11]
	v_mfma_f32_16x16x32_bf16 v[52:55], v[168:171], v[184:187], v[52:55]
	v_mfma_f32_16x16x32_bf16 v[48:51], v[176:179], v[184:187], v[48:51]
	v_mfma_f32_16x16x32_bf16 v[36:39], v[168:171], v[192:195], v[36:39]
	v_mfma_f32_16x16x32_bf16 v[32:35], v[176:179], v[192:195], v[32:35]
	v_mfma_f32_16x16x32_bf16 v[20:23], v[168:171], v[200:203], v[20:23]
	v_mfma_f32_16x16x32_bf16 v[16:19], v[176:179], v[200:203], v[16:19]
	v_mfma_f32_16x16x32_bf16 v[4:7], v[168:171], v[208:211], v[4:7]
	v_mfma_f32_16x16x32_bf16 v[0:3], v[176:179], v[208:211], v[0:3]
	v_mfma_f32_16x16x32_bf16 v[52:55], v[172:175], v[188:191], v[52:55]
	v_mfma_f32_16x16x32_bf16 v[48:51], v[180:183], v[188:191], v[48:51]
	v_mfma_f32_16x16x32_bf16 v[36:39], v[172:175], v[196:199], v[36:39]
	v_mfma_f32_16x16x32_bf16 v[32:35], v[180:183], v[196:199], v[32:35]
	v_mfma_f32_16x16x32_bf16 v[20:23], v[172:175], v[204:207], v[20:23]
	v_mfma_f32_16x16x32_bf16 v[16:19], v[180:183], v[204:207], v[16:19]
	v_mfma_f32_16x16x32_bf16 v[4:7], v[172:175], v[212:215], v[4:7]
	v_mfma_f32_16x16x32_bf16 v[0:3], v[180:183], v[212:215], v[0:3]
	s_setprio 0
	s_barrier
	s_add_i32 s69, s69, 2
	s_add_u32 s67, s67, 0x100
	s_addc_u32 s68, s68, 0
	s_add_u32 s42, s42, 0x100
	s_addc_u32 s43, s43, 0
	s_cmp_gt_u32 s69, 29
	s_cbranch_scc0 .LBB0_1099
	s_and_b64 vcc, exec, s[12:13]
	s_cbranch_vccz .LBB0_1102
	s_barrier
